# attention steady loops: first LDS fragment reads of each step hoisted above the LDS-DMA issue block
# speedup vs baseline: 1.0035x; 1.0025x over previous
.Lst0_u6_loop:
	ds_read_b128 v[96:99], v205 offset:16384
	ds_read_b128 v[100:103], v205 offset:24576
	s_add_i32 s46, s58, 0
	s_mov_b32 m0, s46
	s_nop 0
	global_load_lds_dwordx4 v198, s[98:99]
	s_add_i32 m0, s46, 0x400
	s_nop 0
	global_load_lds_dwordx4 v194, s[98:99]
	s_add_i32 s48, s58, 0x8000
	s_add_i32 m0, s48, 0xc000
	s_nop 0
	global_load_lds_dwordx4 v196, s[100:101]
	s_add_i32 m0, s48, 0xc400
	s_nop 0
	global_load_lds_dwordx4 v192, s[100:101]
	s_waitcnt lgkmcnt(0)
	v_mfma_f32_32x32x16_bf16 v[112:127], v[96:99], v[160:163], 0
	ds_read_b128 v[128:131], v211 offset:16384
	ds_read_b128 v[132:135], v211 offset:24576
	ds_read_b128 v[136:139], v212 offset:16384
	v_exp_f32_e32 v140, v48
	v_exp_f32_e32 v141, v49
	v_exp_f32_e32 v142, v50
	v_exp_f32_e32 v143, v51
	ds_read_b128 v[48:51], v212 offset:24576
	v_mfma_f32_32x32x16_bf16 v[96:111], v[100:103], v[160:163], 0
	v_exp_f32_e32 v144, v52
	v_exp_f32_e32 v145, v53
	v_exp_f32_e32 v146, v54
	v_exp_f32_e32 v147, v55
	s_waitcnt lgkmcnt(0)
	v_mfma_f32_32x32x16_bf16 v[112:127], v[128:131], v[164:167], v[112:127]
	ds_read_b128 v[52:55], v213 offset:16384
	v_exp_f32_e32 v148, v56
	v_exp_f32_e32 v149, v57
	v_exp_f32_e32 v150, v58
	v_exp_f32_e32 v151, v59
	v_mfma_f32_32x32x16_bf16 v[96:111], v[132:135], v[164:167], v[96:111]
	ds_read_b128 v[56:59], v213 offset:24576
	v_exp_f32_e32 v128, v60
	v_exp_f32_e32 v129, v61
	v_exp_f32_e32 v130, v62
	v_exp_f32_e32 v131, v63
	v_mfma_f32_32x32x16_bf16 v[112:127], v[136:139], v[168:171], v[112:127]
	ds_read_b128 v[60:63], v206 offset:49152
	v_exp_f32_e32 v132, v32
	v_exp_f32_e32 v133, v33
	v_exp_f32_e32 v134, v34
	v_exp_f32_e32 v135, v35
	v_mfma_f32_32x32x16_bf16 v[96:111], v[48:51], v[168:171], v[96:111]
	ds_read_b128 v[32:35], v206 offset:53248
	v_exp_f32_e32 v136, v36
	v_exp_f32_e32 v137, v37
	v_exp_f32_e32 v138, v38
	v_exp_f32_e32 v139, v39
	s_waitcnt lgkmcnt(0)
	v_mfma_f32_32x32x16_bf16 v[112:127], v[52:55], v[172:175], v[112:127]
	ds_read_b128 v[36:39], v206 offset:57344
	v_exp_f32_e32 v152, v40
	v_exp_f32_e32 v153, v41
	v_exp_f32_e32 v154, v42
	v_exp_f32_e32 v155, v43
	v_mfma_f32_32x32x16_bf16 v[96:111], v[56:59], v[172:175], v[96:111]
	ds_read_b128 v[40:43], v206 offset:61440
	v_exp_f32_e32 v156, v44
	v_exp_f32_e32 v157, v45
	v_exp_f32_e32 v158, v46
	v_exp_f32_e32 v159, v47
	v_cvt_pk_bf16_f32 v44, v140, v141
	v_cvt_pk_bf16_f32 v45, v142, v143
	v_cvt_pk_bf16_f32 v46, v144, v145
	v_cvt_pk_bf16_f32 v47, v146, v147
	s_nop 1
	v_mfma_f32_32x32x16_bf16 v[80:95], v[60:63], v[44:47], v[80:95]
	ds_read_b128 v[48:51], v207 offset:49152
	v_cvt_pk_bf16_f32 v52, v148, v149
	v_cvt_pk_bf16_f32 v53, v150, v151
	v_cvt_pk_bf16_f32 v54, v128, v129
	v_cvt_pk_bf16_f32 v55, v130, v131
	v_mfma_f32_32x32x16_bf16 v[64:79], v[32:35], v[44:47], v[64:79]
	ds_read_b128 v[56:59], v207 offset:53248
	v_pk_add_f32 v[62:63], v[146:147], v[142:143]
	v_pk_add_f32 v[60:61], v[144:145], v[140:141]
	s_waitcnt lgkmcnt(0)
	v_mfma_f32_32x32x16_bf16 v[16:31], v[36:39], v[44:47], v[16:31]
	ds_read_b128 v[32:35], v207 offset:57344
	v_add_f32_e64 v62, v150, v62
	v_add_f32_e64 v63, v151, v63
	v_add_f32_e64 v60, v148, v60
	v_add_f32_e64 v61, v149, v61
	v_pk_add_f32 v[62:63], v[130:131], v[62:63]
	v_pk_add_f32 v[60:61], v[128:129], v[60:61]
	v_mfma_f32_32x32x16_bf16 v[0:15], v[40:43], v[44:47], v[0:15]
	ds_read_b128 v[36:39], v207 offset:61440
	v_mfma_f32_32x32x16_bf16 v[80:95], v[48:51], v[52:55], v[80:95]
	ds_read_b128 v[40:43], v208 offset:49152
	v_cvt_pk_bf16_f32 v44, v132, v133
	v_cvt_pk_bf16_f32 v45, v134, v135
	v_cvt_pk_bf16_f32 v46, v136, v137
	v_cvt_pk_bf16_f32 v47, v138, v139
	v_mfma_f32_32x32x16_bf16 v[64:79], v[56:59], v[52:55], v[64:79]
	ds_read_b128 v[48:51], v208 offset:53248
	v_add_f32_e64 v62, v134, v62
	v_add_f32_e64 v63, v135, v63
	v_add_f32_e64 v60, v132, v60
	v_add_f32_e64 v61, v133, v61
	v_pk_add_f32 v[62:63], v[138:139], v[62:63]
	v_pk_add_f32 v[60:61], v[136:137], v[60:61]
	s_waitcnt lgkmcnt(0)
	v_mfma_f32_32x32x16_bf16 v[16:31], v[32:35], v[52:55], v[16:31]
	ds_read_b128 v[56:59], v208 offset:57344
	v_add_f32_e64 v62, v154, v62
	v_add_f32_e64 v63, v155, v63
	v_add_f32_e64 v60, v152, v60
	v_add_f32_e64 v61, v153, v61
	v_pk_add_f32 v[130:131], v[158:159], v[62:63]
	v_pk_add_f32 v[128:129], v[156:157], v[60:61]
	v_mfma_f32_32x32x16_bf16 v[0:15], v[36:39], v[52:55], v[0:15]
	ds_read_b128 v[32:35], v208 offset:61440
	v_mfma_f32_32x32x16_bf16 v[80:95], v[40:43], v[44:47], v[80:95]
	ds_read_b128 v[36:39], v209 offset:49152
	v_cvt_pk_bf16_f32 v52, v152, v153
	v_cvt_pk_bf16_f32 v53, v154, v155
	v_cvt_pk_bf16_f32 v54, v156, v157
	v_cvt_pk_bf16_f32 v55, v158, v159
	v_mfma_f32_32x32x16_bf16 v[64:79], v[48:51], v[44:47], v[64:79]
	ds_read_b128 v[40:43], v209 offset:53248
	s_waitcnt lgkmcnt(0)
	v_mfma_f32_32x32x16_bf16 v[16:31], v[56:59], v[44:47], v[16:31]
	ds_read_b128 v[48:51], v209 offset:57344
	v_mfma_f32_32x32x16_bf16 v[0:15], v[32:35], v[44:47], v[0:15]
	ds_read_b128 v[56:59], v209 offset:61440
	v_mfma_f32_32x32x16_bf16 v[80:95], v[36:39], v[52:55], v[80:95]
	v_mfma_f32_32x32x16_bf16 v[64:79], v[40:43], v[52:55], v[64:79]
	s_waitcnt lgkmcnt(0)
	v_mfma_f32_32x32x16_bf16 v[16:31], v[48:51], v[52:55], v[16:31]
	v_mfma_f32_32x32x16_bf16 v[0:15], v[56:59], v[52:55], v[0:15]
	s_waitcnt vmcnt(4) lgkmcnt(0)
	s_barrier
	ds_read_b128 v[32:35], v205 offset:32768
	ds_read_b128 v[36:39], v205 offset:40960
	s_add_u32 s68, s98, 0x18000
	s_addc_u32 s69, s99, 0
	s_add_i32 s49, 0x4000, s57
	s_mov_b32 m0, s49
	s_nop 0
	global_load_lds_dwordx4 v198, s[68:69]
	s_add_i32 m0, s49, 0x400
	s_nop 0
	global_load_lds_dwordx4 v194, s[68:69]
	s_add_u32 s44, s100, 0x80
	s_addc_u32 s45, s101, 0
	s_add_i32 s49, s58, 0xc000
	s_add_i32 m0, s49, 0xc000
	s_nop 0
	global_load_lds_dwordx4 v196, s[44:45]
	s_add_i32 m0, s49, 0xc400
	s_nop 0
	global_load_lds_dwordx4 v192, s[44:45]
	v_exp_f32_e32 v144, v112
	s_waitcnt lgkmcnt(0)
	v_mfma_f32_32x32x16_bf16 v[48:63], v[32:35], v[160:163], 0
	ds_read_b128 v[132:135], v211 offset:32768
	ds_read_b128 v[136:139], v211 offset:40960
	ds_read_b128 v[140:143], v212 offset:32768
	v_exp_f32_e32 v145, v113
	v_exp_f32_e32 v146, v114
	v_exp_f32_e32 v147, v115
	ds_read_b128 v[112:115], v212 offset:40960
	v_mfma_f32_32x32x16_bf16 v[32:47], v[36:39], v[160:163], 0
	v_exp_f32_e32 v148, v116
	v_exp_f32_e32 v149, v117
	v_exp_f32_e32 v150, v118
	v_exp_f32_e32 v151, v119
	s_waitcnt lgkmcnt(0)
	v_mfma_f32_32x32x16_bf16 v[48:63], v[132:135], v[164:167], v[48:63]
	ds_read_b128 v[116:119], v213 offset:32768
	v_exp_f32_e32 v152, v120
	v_exp_f32_e32 v153, v121
	v_exp_f32_e32 v154, v122
	v_exp_f32_e32 v155, v123
	v_mfma_f32_32x32x16_bf16 v[32:47], v[136:139], v[164:167], v[32:47]
	ds_read_b128 v[120:123], v213 offset:40960
	v_exp_f32_e32 v156, v124
	v_exp_f32_e32 v157, v125
	v_exp_f32_e32 v158, v126
	v_exp_f32_e32 v159, v127
	v_mfma_f32_32x32x16_bf16 v[48:63], v[140:143], v[168:171], v[48:63]
	ds_read_b128 v[124:127], v236
	v_exp_f32_e32 v136, v96
	v_exp_f32_e32 v137, v97
	v_exp_f32_e32 v138, v98
	v_exp_f32_e32 v139, v99
	v_mfma_f32_32x32x16_bf16 v[32:47], v[112:115], v[168:171], v[32:47]
	ds_read_b128 v[96:99], v236 offset:4096
	v_exp_f32_e32 v140, v100
	v_exp_f32_e32 v141, v101
	v_exp_f32_e32 v142, v102
	v_exp_f32_e32 v143, v103
	s_waitcnt lgkmcnt(0)
	v_mfma_f32_32x32x16_bf16 v[48:63], v[116:119], v[172:175], v[48:63]
	ds_read_b128 v[100:103], v236 offset:8192
	v_exp_f32_e32 v178, v104
	v_exp_f32_e32 v179, v105
	v_exp_f32_e32 v180, v106
	v_exp_f32_e32 v181, v107
	v_mfma_f32_32x32x16_bf16 v[32:47], v[120:123], v[172:175], v[32:47]
	ds_read_b128 v[104:107], v236 offset:12288
	v_exp_f32_e32 v182, v108
	v_exp_f32_e32 v183, v109
	v_exp_f32_e32 v184, v110
	v_exp_f32_e32 v185, v111
	v_cvt_pk_bf16_f32 v108, v144, v145
	v_cvt_pk_bf16_f32 v109, v146, v147
	v_cvt_pk_bf16_f32 v110, v148, v149
	v_cvt_pk_bf16_f32 v111, v150, v151
	s_nop 1
	v_mfma_f32_32x32x16_bf16 v[80:95], v[124:127], v[108:111], v[80:95]
	ds_read_b128 v[112:115], v237
	v_cvt_pk_bf16_f32 v116, v152, v153
	v_cvt_pk_bf16_f32 v117, v154, v155
	v_cvt_pk_bf16_f32 v118, v156, v157
	v_cvt_pk_bf16_f32 v119, v158, v159
	v_mfma_f32_32x32x16_bf16 v[64:79], v[96:99], v[108:111], v[64:79]
	ds_read_b128 v[120:123], v237 offset:4096
	v_pk_add_f32 v[126:127], v[150:151], v[146:147]
	v_pk_add_f32 v[124:125], v[148:149], v[144:145]
	s_waitcnt lgkmcnt(0)
	v_mfma_f32_32x32x16_bf16 v[16:31], v[100:103], v[108:111], v[16:31]
	ds_read_b128 v[132:135], v237 offset:8192
	v_add_f32_e64 v98, v154, v126
	v_add_f32_e64 v99, v155, v127
	v_add_f32_e64 v96, v152, v124
	v_add_f32_e64 v97, v153, v125
	v_pk_add_f32 v[98:99], v[158:159], v[98:99]
	v_pk_add_f32 v[96:97], v[156:157], v[96:97]
	v_mfma_f32_32x32x16_bf16 v[0:15], v[104:107], v[108:111], v[0:15]
	ds_read_b128 v[100:103], v237 offset:12288
	v_mfma_f32_32x32x16_bf16 v[80:95], v[112:115], v[116:119], v[80:95]
	ds_read_b128 v[104:107], v238
	v_cvt_pk_bf16_f32 v108, v136, v137
	v_cvt_pk_bf16_f32 v109, v138, v139
	v_cvt_pk_bf16_f32 v110, v140, v141
	v_cvt_pk_bf16_f32 v111, v142, v143
	v_mfma_f32_32x32x16_bf16 v[64:79], v[120:123], v[116:119], v[64:79]
	ds_read_b128 v[112:115], v238 offset:4096
	v_add_f32_e64 v98, v138, v98
	v_add_f32_e64 v99, v139, v99
	v_add_f32_e64 v96, v136, v96
	v_add_f32_e64 v97, v137, v97
	v_pk_add_f32 v[98:99], v[142:143], v[98:99]
	v_pk_add_f32 v[96:97], v[140:141], v[96:97]
	s_waitcnt lgkmcnt(0)
	v_mfma_f32_32x32x16_bf16 v[16:31], v[132:135], v[116:119], v[16:31]
	ds_read_b128 v[120:123], v238 offset:8192
	v_add_f32_e64 v98, v180, v98
	v_add_f32_e64 v99, v181, v99
	v_add_f32_e64 v96, v178, v96
	v_add_f32_e64 v97, v179, v97
	v_pk_add_f32 v[98:99], v[184:185], v[98:99]
	v_pk_add_f32 v[96:97], v[182:183], v[96:97]
	v_mfma_f32_32x32x16_bf16 v[0:15], v[100:103], v[116:119], v[0:15]
	ds_read_b128 v[124:127], v238 offset:12288
	v_mfma_f32_32x32x16_bf16 v[80:95], v[104:107], v[108:111], v[80:95]
	ds_read_b128 v[100:103], v239
	v_cvt_pk_bf16_f32 v116, v178, v179
	v_cvt_pk_bf16_f32 v117, v180, v181
	v_cvt_pk_bf16_f32 v118, v182, v183
	v_cvt_pk_bf16_f32 v119, v184, v185
	v_mfma_f32_32x32x16_bf16 v[64:79], v[112:115], v[108:111], v[64:79]
	ds_read_b128 v[104:107], v239 offset:4096
	s_waitcnt lgkmcnt(0)
	v_mfma_f32_32x32x16_bf16 v[16:31], v[120:123], v[108:111], v[16:31]
	ds_read_b128 v[112:115], v239 offset:8192
	v_mfma_f32_32x32x16_bf16 v[0:15], v[124:127], v[108:111], v[0:15]
	ds_read_b128 v[120:123], v239 offset:12288
	v_mfma_f32_32x32x16_bf16 v[80:95], v[100:103], v[116:119], v[80:95]
	v_mfma_f32_32x32x16_bf16 v[64:79], v[104:107], v[116:119], v[64:79]
	s_waitcnt lgkmcnt(0)
	v_mfma_f32_32x32x16_bf16 v[16:31], v[112:115], v[116:119], v[16:31]
	v_mfma_f32_32x32x16_bf16 v[0:15], v[120:123], v[116:119], v[0:15]
	s_waitcnt vmcnt(4) lgkmcnt(0)
	v_add_f32_e32 v100, v128, v129
	v_add_f32_e32 v101, v130, v131
	v_add_f32_e32 v100, v100, v101
	v_add_f32_e32 v96, v96, v97
	v_add_f32_e32 v97, v98, v99
	s_barrier
	v_add_f32_e32 v100, v177, v100
	v_add_f32_e32 v96, v96, v97
	v_add_f32_e32 v177, v100, v96
	ds_read_b128 v[96:99], v205
	ds_read_b128 v[100:103], v205 offset:8192
	s_add_u32 s98, s98, 0x30000
	s_addc_u32 s99, s99, 0
	s_add_u32 s100, s100, 0x100
	s_addc_u32 s101, s101, 0
	s_add_i32 s46, s58, 0x8000
	s_mov_b32 m0, s46
	s_nop 0
	global_load_lds_dwordx4 v198, s[98:99]
	s_add_i32 m0, s46, 0x400
	s_nop 0
	global_load_lds_dwordx4 v194, s[98:99]
	s_add_i32 s48, s58, 0
	s_add_i32 m0, s48, 0xc000
	s_nop 0
	global_load_lds_dwordx4 v196, s[100:101]
	s_add_i32 m0, s48, 0xc400
	s_nop 0
	global_load_lds_dwordx4 v192, s[100:101]
	s_waitcnt lgkmcnt(0)
	v_mfma_f32_32x32x16_bf16 v[112:127], v[96:99], v[160:163], 0
	ds_read_b128 v[128:131], v211
	ds_read_b128 v[132:135], v211 offset:8192
	ds_read_b128 v[136:139], v212
	v_exp_f32_e32 v140, v48
	v_exp_f32_e32 v141, v49
	v_exp_f32_e32 v142, v50
	v_exp_f32_e32 v143, v51
	ds_read_b128 v[48:51], v212 offset:8192
	v_mfma_f32_32x32x16_bf16 v[96:111], v[100:103], v[160:163], 0
	v_exp_f32_e32 v144, v52
	v_exp_f32_e32 v145, v53
	v_exp_f32_e32 v146, v54
	v_exp_f32_e32 v147, v55
	s_waitcnt lgkmcnt(0)
	v_mfma_f32_32x32x16_bf16 v[112:127], v[128:131], v[164:167], v[112:127]
	ds_read_b128 v[52:55], v213
	v_exp_f32_e32 v148, v56
	v_exp_f32_e32 v149, v57
	v_exp_f32_e32 v150, v58
	v_exp_f32_e32 v151, v59
	v_mfma_f32_32x32x16_bf16 v[96:111], v[132:135], v[164:167], v[96:111]
	ds_read_b128 v[56:59], v213 offset:8192
	v_exp_f32_e32 v128, v60
	v_exp_f32_e32 v129, v61
	v_exp_f32_e32 v130, v62
	v_exp_f32_e32 v131, v63
	v_mfma_f32_32x32x16_bf16 v[112:127], v[136:139], v[168:171], v[112:127]
	ds_read_b128 v[60:63], v236 offset:16384
	v_exp_f32_e32 v132, v32
	v_exp_f32_e32 v133, v33
	v_exp_f32_e32 v134, v34
	v_exp_f32_e32 v135, v35
	v_mfma_f32_32x32x16_bf16 v[96:111], v[48:51], v[168:171], v[96:111]
	ds_read_b128 v[32:35], v236 offset:20480
	v_exp_f32_e32 v136, v36
	v_exp_f32_e32 v137, v37
	v_exp_f32_e32 v138, v38
	v_exp_f32_e32 v139, v39
	s_waitcnt lgkmcnt(0)
	v_mfma_f32_32x32x16_bf16 v[112:127], v[52:55], v[172:175], v[112:127]
	ds_read_b128 v[36:39], v236 offset:24576
	v_exp_f32_e32 v152, v40
	v_exp_f32_e32 v153, v41
	v_exp_f32_e32 v154, v42
	v_exp_f32_e32 v155, v43
	v_mfma_f32_32x32x16_bf16 v[96:111], v[56:59], v[172:175], v[96:111]
	ds_read_b128 v[40:43], v236 offset:28672
	v_exp_f32_e32 v156, v44
	v_exp_f32_e32 v157, v45
	v_exp_f32_e32 v158, v46
	v_exp_f32_e32 v159, v47
	v_cvt_pk_bf16_f32 v44, v140, v141
	v_cvt_pk_bf16_f32 v45, v142, v143
	v_cvt_pk_bf16_f32 v46, v144, v145
	v_cvt_pk_bf16_f32 v47, v146, v147
	s_nop 1
	v_mfma_f32_32x32x16_bf16 v[80:95], v[60:63], v[44:47], v[80:95]
	ds_read_b128 v[48:51], v237 offset:16384
	v_cvt_pk_bf16_f32 v52, v148, v149
	v_cvt_pk_bf16_f32 v53, v150, v151
	v_cvt_pk_bf16_f32 v54, v128, v129
	v_cvt_pk_bf16_f32 v55, v130, v131
	v_mfma_f32_32x32x16_bf16 v[64:79], v[32:35], v[44:47], v[64:79]
	ds_read_b128 v[56:59], v237 offset:20480
	v_pk_add_f32 v[62:63], v[146:147], v[142:143]
	v_pk_add_f32 v[60:61], v[144:145], v[140:141]
	s_waitcnt lgkmcnt(0)
	v_mfma_f32_32x32x16_bf16 v[16:31], v[36:39], v[44:47], v[16:31]
	ds_read_b128 v[32:35], v237 offset:24576
	v_add_f32_e64 v62, v150, v62
	v_add_f32_e64 v63, v151, v63
	v_add_f32_e64 v60, v148, v60
	v_add_f32_e64 v61, v149, v61
	v_pk_add_f32 v[62:63], v[130:131], v[62:63]
	v_pk_add_f32 v[60:61], v[128:129], v[60:61]
	v_mfma_f32_32x32x16_bf16 v[0:15], v[40:43], v[44:47], v[0:15]
	ds_read_b128 v[36:39], v237 offset:28672
	v_mfma_f32_32x32x16_bf16 v[80:95], v[48:51], v[52:55], v[80:95]
	ds_read_b128 v[40:43], v238 offset:16384
	v_cvt_pk_bf16_f32 v44, v132, v133
	v_cvt_pk_bf16_f32 v45, v134, v135
	v_cvt_pk_bf16_f32 v46, v136, v137
	v_cvt_pk_bf16_f32 v47, v138, v139
	v_mfma_f32_32x32x16_bf16 v[64:79], v[56:59], v[52:55], v[64:79]
	ds_read_b128 v[48:51], v238 offset:20480
	v_add_f32_e64 v62, v134, v62
	v_add_f32_e64 v63, v135, v63
	v_add_f32_e64 v60, v132, v60
	v_add_f32_e64 v61, v133, v61
	v_pk_add_f32 v[62:63], v[138:139], v[62:63]
	v_pk_add_f32 v[60:61], v[136:137], v[60:61]
	s_waitcnt lgkmcnt(0)
	v_mfma_f32_32x32x16_bf16 v[16:31], v[32:35], v[52:55], v[16:31]
	ds_read_b128 v[56:59], v238 offset:24576
	v_add_f32_e64 v62, v154, v62
	v_add_f32_e64 v63, v155, v63
	v_add_f32_e64 v60, v152, v60
	v_add_f32_e64 v61, v153, v61
	v_pk_add_f32 v[130:131], v[158:159], v[62:63]
	v_pk_add_f32 v[128:129], v[156:157], v[60:61]
	v_mfma_f32_32x32x16_bf16 v[0:15], v[36:39], v[52:55], v[0:15]
	ds_read_b128 v[32:35], v238 offset:28672
	v_mfma_f32_32x32x16_bf16 v[80:95], v[40:43], v[44:47], v[80:95]
	ds_read_b128 v[36:39], v239 offset:16384
	v_cvt_pk_bf16_f32 v52, v152, v153
	v_cvt_pk_bf16_f32 v53, v154, v155
	v_cvt_pk_bf16_f32 v54, v156, v157
	v_cvt_pk_bf16_f32 v55, v158, v159
	v_mfma_f32_32x32x16_bf16 v[64:79], v[48:51], v[44:47], v[64:79]
	ds_read_b128 v[40:43], v239 offset:20480
	s_waitcnt lgkmcnt(0)
	v_mfma_f32_32x32x16_bf16 v[16:31], v[56:59], v[44:47], v[16:31]
	ds_read_b128 v[48:51], v239 offset:24576
	v_mfma_f32_32x32x16_bf16 v[0:15], v[32:35], v[44:47], v[0:15]
	ds_read_b128 v[56:59], v239 offset:28672
	v_mfma_f32_32x32x16_bf16 v[80:95], v[36:39], v[52:55], v[80:95]
	v_mfma_f32_32x32x16_bf16 v[64:79], v[40:43], v[52:55], v[64:79]
	s_waitcnt lgkmcnt(0)
	v_mfma_f32_32x32x16_bf16 v[16:31], v[48:51], v[52:55], v[16:31]
	v_mfma_f32_32x32x16_bf16 v[0:15], v[56:59], v[52:55], v[0:15]
	s_waitcnt vmcnt(4) lgkmcnt(0)
	s_barrier
	ds_read_b128 v[32:35], v205 offset:16384
	ds_read_b128 v[36:39], v205 offset:24576
	s_add_u32 s68, s98, 0x18000
	s_addc_u32 s69, s99, 0
	s_add_i32 s49, 0, s57
	s_mov_b32 m0, s49
	s_nop 0
	global_load_lds_dwordx4 v198, s[68:69]
	s_add_i32 m0, s49, 0x400
	s_nop 0
	global_load_lds_dwordx4 v194, s[68:69]
	s_add_u32 s44, s100, 0x80
	s_addc_u32 s45, s101, 0
	s_add_i32 s49, s58, 0x4000
	s_add_i32 m0, s49, 0xc000
	s_nop 0
	global_load_lds_dwordx4 v196, s[44:45]
	s_add_i32 m0, s49, 0xc400
	s_nop 0
	global_load_lds_dwordx4 v192, s[44:45]
	v_exp_f32_e32 v144, v112
	s_waitcnt lgkmcnt(0)
	v_mfma_f32_32x32x16_bf16 v[48:63], v[32:35], v[160:163], 0
	ds_read_b128 v[132:135], v211 offset:16384
	ds_read_b128 v[136:139], v211 offset:24576
	ds_read_b128 v[140:143], v212 offset:16384
	v_exp_f32_e32 v145, v113
	v_exp_f32_e32 v146, v114
	v_exp_f32_e32 v147, v115
	ds_read_b128 v[112:115], v212 offset:24576
	v_mfma_f32_32x32x16_bf16 v[32:47], v[36:39], v[160:163], 0
	v_exp_f32_e32 v148, v116
	v_exp_f32_e32 v149, v117
	v_exp_f32_e32 v150, v118
	v_exp_f32_e32 v151, v119
	s_waitcnt lgkmcnt(0)
	v_mfma_f32_32x32x16_bf16 v[48:63], v[132:135], v[164:167], v[48:63]
	ds_read_b128 v[116:119], v213 offset:16384
	v_exp_f32_e32 v152, v120
	v_exp_f32_e32 v153, v121
	v_exp_f32_e32 v154, v122
	v_exp_f32_e32 v155, v123
	v_mfma_f32_32x32x16_bf16 v[32:47], v[136:139], v[164:167], v[32:47]
	ds_read_b128 v[120:123], v213 offset:24576
	v_exp_f32_e32 v156, v124
	v_exp_f32_e32 v157, v125
	v_exp_f32_e32 v158, v126
	v_exp_f32_e32 v159, v127
	v_mfma_f32_32x32x16_bf16 v[48:63], v[140:143], v[168:171], v[48:63]
	ds_read_b128 v[124:127], v236 offset:32768
	v_exp_f32_e32 v136, v96
	v_exp_f32_e32 v137, v97
	v_exp_f32_e32 v138, v98
	v_exp_f32_e32 v139, v99
	v_mfma_f32_32x32x16_bf16 v[32:47], v[112:115], v[168:171], v[32:47]
	ds_read_b128 v[96:99], v236 offset:36864
	v_exp_f32_e32 v140, v100
	v_exp_f32_e32 v141, v101
	v_exp_f32_e32 v142, v102
	v_exp_f32_e32 v143, v103
	s_waitcnt lgkmcnt(0)
	v_mfma_f32_32x32x16_bf16 v[48:63], v[116:119], v[172:175], v[48:63]
	ds_read_b128 v[100:103], v236 offset:40960
	v_exp_f32_e32 v178, v104
	v_exp_f32_e32 v179, v105
	v_exp_f32_e32 v180, v106
	v_exp_f32_e32 v181, v107
	v_mfma_f32_32x32x16_bf16 v[32:47], v[120:123], v[172:175], v[32:47]
	ds_read_b128 v[104:107], v236 offset:45056
	v_exp_f32_e32 v182, v108
	v_exp_f32_e32 v183, v109
	v_exp_f32_e32 v184, v110
	v_exp_f32_e32 v185, v111
	v_cvt_pk_bf16_f32 v108, v144, v145
	v_cvt_pk_bf16_f32 v109, v146, v147
	v_cvt_pk_bf16_f32 v110, v148, v149
	v_cvt_pk_bf16_f32 v111, v150, v151
	s_nop 1
	v_mfma_f32_32x32x16_bf16 v[80:95], v[124:127], v[108:111], v[80:95]
	ds_read_b128 v[112:115], v237 offset:32768
	v_cvt_pk_bf16_f32 v116, v152, v153
	v_cvt_pk_bf16_f32 v117, v154, v155
	v_cvt_pk_bf16_f32 v118, v156, v157
	v_cvt_pk_bf16_f32 v119, v158, v159
	v_mfma_f32_32x32x16_bf16 v[64:79], v[96:99], v[108:111], v[64:79]
	ds_read_b128 v[120:123], v237 offset:36864
	v_pk_add_f32 v[126:127], v[150:151], v[146:147]
	v_pk_add_f32 v[124:125], v[148:149], v[144:145]
	s_waitcnt lgkmcnt(0)
	v_mfma_f32_32x32x16_bf16 v[16:31], v[100:103], v[108:111], v[16:31]
	ds_read_b128 v[132:135], v237 offset:40960
	v_add_f32_e64 v98, v154, v126
	v_add_f32_e64 v99, v155, v127
	v_add_f32_e64 v96, v152, v124
	v_add_f32_e64 v97, v153, v125
	v_pk_add_f32 v[98:99], v[158:159], v[98:99]
	v_pk_add_f32 v[96:97], v[156:157], v[96:97]
	v_mfma_f32_32x32x16_bf16 v[0:15], v[104:107], v[108:111], v[0:15]
	ds_read_b128 v[100:103], v237 offset:45056
	v_mfma_f32_32x32x16_bf16 v[80:95], v[112:115], v[116:119], v[80:95]
	ds_read_b128 v[104:107], v238 offset:32768
	v_cvt_pk_bf16_f32 v108, v136, v137
	v_cvt_pk_bf16_f32 v109, v138, v139
	v_cvt_pk_bf16_f32 v110, v140, v141
	v_cvt_pk_bf16_f32 v111, v142, v143
	v_mfma_f32_32x32x16_bf16 v[64:79], v[120:123], v[116:119], v[64:79]
	ds_read_b128 v[112:115], v238 offset:36864
	v_add_f32_e64 v98, v138, v98
	v_add_f32_e64 v99, v139, v99
	v_add_f32_e64 v96, v136, v96
	v_add_f32_e64 v97, v137, v97
	v_pk_add_f32 v[98:99], v[142:143], v[98:99]
	v_pk_add_f32 v[96:97], v[140:141], v[96:97]
	s_waitcnt lgkmcnt(0)
	v_mfma_f32_32x32x16_bf16 v[16:31], v[132:135], v[116:119], v[16:31]
	ds_read_b128 v[120:123], v238 offset:40960
	v_add_f32_e64 v98, v180, v98
	v_add_f32_e64 v99, v181, v99
	v_add_f32_e64 v96, v178, v96
	v_add_f32_e64 v97, v179, v97
	v_pk_add_f32 v[98:99], v[184:185], v[98:99]
	v_pk_add_f32 v[96:97], v[182:183], v[96:97]
	v_mfma_f32_32x32x16_bf16 v[0:15], v[100:103], v[116:119], v[0:15]
	ds_read_b128 v[124:127], v238 offset:45056
	v_mfma_f32_32x32x16_bf16 v[80:95], v[104:107], v[108:111], v[80:95]
	ds_read_b128 v[100:103], v239 offset:32768
	v_cvt_pk_bf16_f32 v116, v178, v179
	v_cvt_pk_bf16_f32 v117, v180, v181
	v_cvt_pk_bf16_f32 v118, v182, v183
	v_cvt_pk_bf16_f32 v119, v184, v185
	v_mfma_f32_32x32x16_bf16 v[64:79], v[112:115], v[108:111], v[64:79]
	ds_read_b128 v[104:107], v239 offset:36864
	s_waitcnt lgkmcnt(0)
	v_mfma_f32_32x32x16_bf16 v[16:31], v[120:123], v[108:111], v[16:31]
	ds_read_b128 v[112:115], v239 offset:40960
	v_mfma_f32_32x32x16_bf16 v[0:15], v[124:127], v[108:111], v[0:15]
	ds_read_b128 v[120:123], v239 offset:45056
	v_mfma_f32_32x32x16_bf16 v[80:95], v[100:103], v[116:119], v[80:95]
	v_mfma_f32_32x32x16_bf16 v[64:79], v[104:107], v[116:119], v[64:79]
	s_waitcnt lgkmcnt(0)
	v_mfma_f32_32x32x16_bf16 v[16:31], v[112:115], v[116:119], v[16:31]
	v_mfma_f32_32x32x16_bf16 v[0:15], v[120:123], v[116:119], v[0:15]
	s_waitcnt vmcnt(4) lgkmcnt(0)
	v_add_f32_e32 v100, v128, v129
	v_add_f32_e32 v101, v130, v131
	v_add_f32_e32 v100, v100, v101
	v_add_f32_e32 v96, v96, v97
	v_add_f32_e32 v97, v98, v99
	s_barrier
	v_add_f32_e32 v100, v177, v100
	v_add_f32_e32 v96, v96, v97
	v_add_f32_e32 v177, v100, v96
	ds_read_b128 v[96:99], v205 offset:32768
	ds_read_b128 v[100:103], v205 offset:40960
	s_add_u32 s98, s98, 0x30000
	s_addc_u32 s99, s99, 0
	s_add_u32 s100, s100, 0x100
	s_addc_u32 s101, s101, 0
	s_add_i32 s46, s58, 0x4000
	s_mov_b32 m0, s46
	s_nop 0
	global_load_lds_dwordx4 v198, s[98:99]
	s_add_i32 m0, s46, 0x400
	s_nop 0
	global_load_lds_dwordx4 v194, s[98:99]
	s_add_i32 s48, s58, 0x8000
	s_add_i32 m0, s48, 0xc000
	s_nop 0
	global_load_lds_dwordx4 v196, s[100:101]
	s_add_i32 m0, s48, 0xc400
	s_nop 0
	global_load_lds_dwordx4 v192, s[100:101]
	s_waitcnt lgkmcnt(0)
	v_mfma_f32_32x32x16_bf16 v[112:127], v[96:99], v[160:163], 0
	ds_read_b128 v[128:131], v211 offset:32768
	ds_read_b128 v[132:135], v211 offset:40960
	ds_read_b128 v[136:139], v212 offset:32768
	v_exp_f32_e32 v140, v48
	v_exp_f32_e32 v141, v49
	v_exp_f32_e32 v142, v50
	v_exp_f32_e32 v143, v51
	ds_read_b128 v[48:51], v212 offset:40960
	v_mfma_f32_32x32x16_bf16 v[96:111], v[100:103], v[160:163], 0
	v_exp_f32_e32 v144, v52
	v_exp_f32_e32 v145, v53
	v_exp_f32_e32 v146, v54
	v_exp_f32_e32 v147, v55
	s_waitcnt lgkmcnt(0)
	v_mfma_f32_32x32x16_bf16 v[112:127], v[128:131], v[164:167], v[112:127]
	ds_read_b128 v[52:55], v213 offset:32768
	v_exp_f32_e32 v148, v56
	v_exp_f32_e32 v149, v57
	v_exp_f32_e32 v150, v58
	v_exp_f32_e32 v151, v59
	v_mfma_f32_32x32x16_bf16 v[96:111], v[132:135], v[164:167], v[96:111]
	ds_read_b128 v[56:59], v213 offset:40960
	v_exp_f32_e32 v128, v60
	v_exp_f32_e32 v129, v61
	v_exp_f32_e32 v130, v62
	v_exp_f32_e32 v131, v63
	v_mfma_f32_32x32x16_bf16 v[112:127], v[136:139], v[168:171], v[112:127]
	ds_read_b128 v[60:63], v206 offset:49152
	v_exp_f32_e32 v132, v32
	v_exp_f32_e32 v133, v33
	v_exp_f32_e32 v134, v34
	v_exp_f32_e32 v135, v35
	v_mfma_f32_32x32x16_bf16 v[96:111], v[48:51], v[168:171], v[96:111]
	ds_read_b128 v[32:35], v206 offset:53248
	v_exp_f32_e32 v136, v36
	v_exp_f32_e32 v137, v37
	v_exp_f32_e32 v138, v38
	v_exp_f32_e32 v139, v39
	s_waitcnt lgkmcnt(0)
	v_mfma_f32_32x32x16_bf16 v[112:127], v[52:55], v[172:175], v[112:127]
	ds_read_b128 v[36:39], v206 offset:57344
	v_exp_f32_e32 v152, v40
	v_exp_f32_e32 v153, v41
	v_exp_f32_e32 v154, v42
	v_exp_f32_e32 v155, v43
	v_mfma_f32_32x32x16_bf16 v[96:111], v[56:59], v[172:175], v[96:111]
	ds_read_b128 v[40:43], v206 offset:61440
	v_exp_f32_e32 v156, v44
	v_exp_f32_e32 v157, v45
	v_exp_f32_e32 v158, v46
	v_exp_f32_e32 v159, v47
	v_cvt_pk_bf16_f32 v44, v140, v141
	v_cvt_pk_bf16_f32 v45, v142, v143
	v_cvt_pk_bf16_f32 v46, v144, v145
	v_cvt_pk_bf16_f32 v47, v146, v147
	s_nop 1
	v_mfma_f32_32x32x16_bf16 v[80:95], v[60:63], v[44:47], v[80:95]
	ds_read_b128 v[48:51], v207 offset:49152
	v_cvt_pk_bf16_f32 v52, v148, v149
	v_cvt_pk_bf16_f32 v53, v150, v151
	v_cvt_pk_bf16_f32 v54, v128, v129
	v_cvt_pk_bf16_f32 v55, v130, v131
	v_mfma_f32_32x32x16_bf16 v[64:79], v[32:35], v[44:47], v[64:79]
	ds_read_b128 v[56:59], v207 offset:53248
	v_pk_add_f32 v[62:63], v[146:147], v[142:143]
	v_pk_add_f32 v[60:61], v[144:145], v[140:141]
	s_waitcnt lgkmcnt(0)
	v_mfma_f32_32x32x16_bf16 v[16:31], v[36:39], v[44:47], v[16:31]
	ds_read_b128 v[32:35], v207 offset:57344
	v_add_f32_e64 v62, v150, v62
	v_add_f32_e64 v63, v151, v63
	v_add_f32_e64 v60, v148, v60
	v_add_f32_e64 v61, v149, v61
	v_pk_add_f32 v[62:63], v[130:131], v[62:63]
	v_pk_add_f32 v[60:61], v[128:129], v[60:61]
	v_mfma_f32_32x32x16_bf16 v[0:15], v[40:43], v[44:47], v[0:15]
	ds_read_b128 v[36:39], v207 offset:61440
	v_mfma_f32_32x32x16_bf16 v[80:95], v[48:51], v[52:55], v[80:95]
	ds_read_b128 v[40:43], v208 offset:49152
	v_cvt_pk_bf16_f32 v44, v132, v133
	v_cvt_pk_bf16_f32 v45, v134, v135
	v_cvt_pk_bf16_f32 v46, v136, v137
	v_cvt_pk_bf16_f32 v47, v138, v139
	v_mfma_f32_32x32x16_bf16 v[64:79], v[56:59], v[52:55], v[64:79]
	ds_read_b128 v[48:51], v208 offset:53248
	v_add_f32_e64 v62, v134, v62
	v_add_f32_e64 v63, v135, v63
	v_add_f32_e64 v60, v132, v60
	v_add_f32_e64 v61, v133, v61
	v_pk_add_f32 v[62:63], v[138:139], v[62:63]
	v_pk_add_f32 v[60:61], v[136:137], v[60:61]
	s_waitcnt lgkmcnt(0)
	v_mfma_f32_32x32x16_bf16 v[16:31], v[32:35], v[52:55], v[16:31]
	ds_read_b128 v[56:59], v208 offset:57344
	v_add_f32_e64 v62, v154, v62
	v_add_f32_e64 v63, v155, v63
	v_add_f32_e64 v60, v152, v60
	v_add_f32_e64 v61, v153, v61
	v_pk_add_f32 v[130:131], v[158:159], v[62:63]
	v_pk_add_f32 v[128:129], v[156:157], v[60:61]
	v_mfma_f32_32x32x16_bf16 v[0:15], v[36:39], v[52:55], v[0:15]
	ds_read_b128 v[32:35], v208 offset:61440
	v_mfma_f32_32x32x16_bf16 v[80:95], v[40:43], v[44:47], v[80:95]
	ds_read_b128 v[36:39], v209 offset:49152
	v_cvt_pk_bf16_f32 v52, v152, v153
	v_cvt_pk_bf16_f32 v53, v154, v155
	v_cvt_pk_bf16_f32 v54, v156, v157
	v_cvt_pk_bf16_f32 v55, v158, v159
	v_mfma_f32_32x32x16_bf16 v[64:79], v[48:51], v[44:47], v[64:79]
	ds_read_b128 v[40:43], v209 offset:53248
	s_waitcnt lgkmcnt(0)
	v_mfma_f32_32x32x16_bf16 v[16:31], v[56:59], v[44:47], v[16:31]
	ds_read_b128 v[48:51], v209 offset:57344
	v_mfma_f32_32x32x16_bf16 v[0:15], v[32:35], v[44:47], v[0:15]
	ds_read_b128 v[56:59], v209 offset:61440
	v_mfma_f32_32x32x16_bf16 v[80:95], v[36:39], v[52:55], v[80:95]
	v_mfma_f32_32x32x16_bf16 v[64:79], v[40:43], v[52:55], v[64:79]
	s_waitcnt lgkmcnt(0)
	v_mfma_f32_32x32x16_bf16 v[16:31], v[48:51], v[52:55], v[16:31]
	v_mfma_f32_32x32x16_bf16 v[0:15], v[56:59], v[52:55], v[0:15]
	s_waitcnt vmcnt(4) lgkmcnt(0)
	s_barrier
	ds_read_b128 v[32:35], v205
	ds_read_b128 v[36:39], v205 offset:8192
	s_add_u32 s68, s98, 0x18000
	s_addc_u32 s69, s99, 0
	s_add_i32 s49, 0x8000, s57
	s_mov_b32 m0, s49
	s_nop 0
	global_load_lds_dwordx4 v198, s[68:69]
	s_add_i32 m0, s49, 0x400
	s_nop 0
	global_load_lds_dwordx4 v194, s[68:69]
	s_add_u32 s44, s100, 0x80
	s_addc_u32 s45, s101, 0
	s_add_i32 s49, s58, 0xc000
	s_add_i32 m0, s49, 0xc000
	s_nop 0
	global_load_lds_dwordx4 v196, s[44:45]
	s_add_i32 m0, s49, 0xc400
	s_nop 0
	global_load_lds_dwordx4 v192, s[44:45]
	v_exp_f32_e32 v144, v112
	s_waitcnt lgkmcnt(0)
	v_mfma_f32_32x32x16_bf16 v[48:63], v[32:35], v[160:163], 0
	ds_read_b128 v[132:135], v211
	ds_read_b128 v[136:139], v211 offset:8192
	ds_read_b128 v[140:143], v212
	v_exp_f32_e32 v145, v113
	v_exp_f32_e32 v146, v114
	v_exp_f32_e32 v147, v115
	ds_read_b128 v[112:115], v212 offset:8192
	v_mfma_f32_32x32x16_bf16 v[32:47], v[36:39], v[160:163], 0
	v_exp_f32_e32 v148, v116
	v_exp_f32_e32 v149, v117
	v_exp_f32_e32 v150, v118
	v_exp_f32_e32 v151, v119
	s_waitcnt lgkmcnt(0)
	v_mfma_f32_32x32x16_bf16 v[48:63], v[132:135], v[164:167], v[48:63]
	ds_read_b128 v[116:119], v213
	v_exp_f32_e32 v152, v120
	v_exp_f32_e32 v153, v121
	v_exp_f32_e32 v154, v122
	v_exp_f32_e32 v155, v123
	v_mfma_f32_32x32x16_bf16 v[32:47], v[136:139], v[164:167], v[32:47]
	ds_read_b128 v[120:123], v213 offset:8192
	v_exp_f32_e32 v156, v124
	v_exp_f32_e32 v157, v125
	v_exp_f32_e32 v158, v126
	v_exp_f32_e32 v159, v127
	v_mfma_f32_32x32x16_bf16 v[48:63], v[140:143], v[168:171], v[48:63]
	ds_read_b128 v[124:127], v236
	v_exp_f32_e32 v136, v96
	v_exp_f32_e32 v137, v97
	v_exp_f32_e32 v138, v98
	v_exp_f32_e32 v139, v99
	v_mfma_f32_32x32x16_bf16 v[32:47], v[112:115], v[168:171], v[32:47]
	ds_read_b128 v[96:99], v236 offset:4096
	v_exp_f32_e32 v140, v100
	v_exp_f32_e32 v141, v101
	v_exp_f32_e32 v142, v102
	v_exp_f32_e32 v143, v103
	s_waitcnt lgkmcnt(0)
	v_mfma_f32_32x32x16_bf16 v[48:63], v[116:119], v[172:175], v[48:63]
	ds_read_b128 v[100:103], v236 offset:8192
	v_exp_f32_e32 v178, v104
	v_exp_f32_e32 v179, v105
	v_exp_f32_e32 v180, v106
	v_exp_f32_e32 v181, v107
	v_mfma_f32_32x32x16_bf16 v[32:47], v[120:123], v[172:175], v[32:47]
	ds_read_b128 v[104:107], v236 offset:12288
	v_exp_f32_e32 v182, v108
	v_exp_f32_e32 v183, v109
	v_exp_f32_e32 v184, v110
	v_exp_f32_e32 v185, v111
	v_cvt_pk_bf16_f32 v108, v144, v145
	v_cvt_pk_bf16_f32 v109, v146, v147
	v_cvt_pk_bf16_f32 v110, v148, v149
	v_cvt_pk_bf16_f32 v111, v150, v151
	s_nop 1
	v_mfma_f32_32x32x16_bf16 v[80:95], v[124:127], v[108:111], v[80:95]
	ds_read_b128 v[112:115], v237
	v_cvt_pk_bf16_f32 v116, v152, v153
	v_cvt_pk_bf16_f32 v117, v154, v155
	v_cvt_pk_bf16_f32 v118, v156, v157
	v_cvt_pk_bf16_f32 v119, v158, v159
	v_mfma_f32_32x32x16_bf16 v[64:79], v[96:99], v[108:111], v[64:79]
	ds_read_b128 v[120:123], v237 offset:4096
	v_pk_add_f32 v[126:127], v[150:151], v[146:147]
	v_pk_add_f32 v[124:125], v[148:149], v[144:145]
	s_waitcnt lgkmcnt(0)
	v_mfma_f32_32x32x16_bf16 v[16:31], v[100:103], v[108:111], v[16:31]
	ds_read_b128 v[132:135], v237 offset:8192
	v_add_f32_e64 v98, v154, v126
	v_add_f32_e64 v99, v155, v127
	v_add_f32_e64 v96, v152, v124
	v_add_f32_e64 v97, v153, v125
	v_pk_add_f32 v[98:99], v[158:159], v[98:99]
	v_pk_add_f32 v[96:97], v[156:157], v[96:97]
	v_mfma_f32_32x32x16_bf16 v[0:15], v[104:107], v[108:111], v[0:15]
	ds_read_b128 v[100:103], v237 offset:12288
	v_mfma_f32_32x32x16_bf16 v[80:95], v[112:115], v[116:119], v[80:95]
	ds_read_b128 v[104:107], v238
	v_cvt_pk_bf16_f32 v108, v136, v137
	v_cvt_pk_bf16_f32 v109, v138, v139
	v_cvt_pk_bf16_f32 v110, v140, v141
	v_cvt_pk_bf16_f32 v111, v142, v143
	v_mfma_f32_32x32x16_bf16 v[64:79], v[120:123], v[116:119], v[64:79]
	ds_read_b128 v[112:115], v238 offset:4096
	v_add_f32_e64 v98, v138, v98
	v_add_f32_e64 v99, v139, v99
	v_add_f32_e64 v96, v136, v96
	v_add_f32_e64 v97, v137, v97
	v_pk_add_f32 v[98:99], v[142:143], v[98:99]
	v_pk_add_f32 v[96:97], v[140:141], v[96:97]
	s_waitcnt lgkmcnt(0)
	v_mfma_f32_32x32x16_bf16 v[16:31], v[132:135], v[116:119], v[16:31]
	ds_read_b128 v[120:123], v238 offset:8192
	v_add_f32_e64 v98, v180, v98
	v_add_f32_e64 v99, v181, v99
	v_add_f32_e64 v96, v178, v96
	v_add_f32_e64 v97, v179, v97
	v_pk_add_f32 v[98:99], v[184:185], v[98:99]
	v_pk_add_f32 v[96:97], v[182:183], v[96:97]
	v_mfma_f32_32x32x16_bf16 v[0:15], v[100:103], v[116:119], v[0:15]
	ds_read_b128 v[124:127], v238 offset:12288
	v_mfma_f32_32x32x16_bf16 v[80:95], v[104:107], v[108:111], v[80:95]
	ds_read_b128 v[100:103], v239
	v_cvt_pk_bf16_f32 v116, v178, v179
	v_cvt_pk_bf16_f32 v117, v180, v181
	v_cvt_pk_bf16_f32 v118, v182, v183
	v_cvt_pk_bf16_f32 v119, v184, v185
	v_mfma_f32_32x32x16_bf16 v[64:79], v[112:115], v[108:111], v[64:79]
	ds_read_b128 v[104:107], v239 offset:4096
	s_waitcnt lgkmcnt(0)
	v_mfma_f32_32x32x16_bf16 v[16:31], v[120:123], v[108:111], v[16:31]
	ds_read_b128 v[112:115], v239 offset:8192
	v_mfma_f32_32x32x16_bf16 v[0:15], v[124:127], v[108:111], v[0:15]
	ds_read_b128 v[120:123], v239 offset:12288
	v_mfma_f32_32x32x16_bf16 v[80:95], v[100:103], v[116:119], v[80:95]
	v_mfma_f32_32x32x16_bf16 v[64:79], v[104:107], v[116:119], v[64:79]
	s_waitcnt lgkmcnt(0)
	v_mfma_f32_32x32x16_bf16 v[16:31], v[112:115], v[116:119], v[16:31]
	v_mfma_f32_32x32x16_bf16 v[0:15], v[120:123], v[116:119], v[0:15]
	s_waitcnt vmcnt(4) lgkmcnt(0)
	v_add_f32_e32 v100, v128, v129
	v_add_f32_e32 v101, v130, v131
	v_add_f32_e32 v100, v100, v101
	v_add_f32_e32 v96, v96, v97
	v_add_f32_e32 v97, v98, v99
	s_barrier
	v_add_f32_e32 v100, v177, v100
	v_add_f32_e32 v96, v96, v97
	v_add_f32_e32 v177, v100, v96
	ds_read_b128 v[96:99], v205 offset:16384
	ds_read_b128 v[100:103], v205 offset:24576
	s_add_u32 s98, s98, 0x30000
	s_addc_u32 s99, s99, 0
	s_add_u32 s100, s100, 0x100
	s_addc_u32 s101, s101, 0
	s_add_i32 s46, s58, 0
	s_mov_b32 m0, s46
	s_nop 0
	global_load_lds_dwordx4 v198, s[98:99]
	s_add_i32 m0, s46, 0x400
	s_nop 0
	global_load_lds_dwordx4 v194, s[98:99]
	s_add_i32 s48, s58, 0
	s_add_i32 m0, s48, 0xc000
	s_nop 0
	global_load_lds_dwordx4 v196, s[100:101]
	s_add_i32 m0, s48, 0xc400
	s_nop 0
	global_load_lds_dwordx4 v192, s[100:101]
	s_waitcnt lgkmcnt(0)
	v_mfma_f32_32x32x16_bf16 v[112:127], v[96:99], v[160:163], 0
	ds_read_b128 v[128:131], v211 offset:16384
	ds_read_b128 v[132:135], v211 offset:24576
	ds_read_b128 v[136:139], v212 offset:16384
	v_exp_f32_e32 v140, v48
	v_exp_f32_e32 v141, v49
	v_exp_f32_e32 v142, v50
	v_exp_f32_e32 v143, v51
	ds_read_b128 v[48:51], v212 offset:24576
	v_mfma_f32_32x32x16_bf16 v[96:111], v[100:103], v[160:163], 0
	v_exp_f32_e32 v144, v52
	v_exp_f32_e32 v145, v53
	v_exp_f32_e32 v146, v54
	v_exp_f32_e32 v147, v55
	s_waitcnt lgkmcnt(0)
	v_mfma_f32_32x32x16_bf16 v[112:127], v[128:131], v[164:167], v[112:127]
	ds_read_b128 v[52:55], v213 offset:16384
	v_exp_f32_e32 v148, v56
	v_exp_f32_e32 v149, v57
	v_exp_f32_e32 v150, v58
	v_exp_f32_e32 v151, v59
	v_mfma_f32_32x32x16_bf16 v[96:111], v[132:135], v[164:167], v[96:111]
	ds_read_b128 v[56:59], v213 offset:24576
	v_exp_f32_e32 v128, v60
	v_exp_f32_e32 v129, v61
	v_exp_f32_e32 v130, v62
	v_exp_f32_e32 v131, v63
	v_mfma_f32_32x32x16_bf16 v[112:127], v[136:139], v[168:171], v[112:127]
	ds_read_b128 v[60:63], v236 offset:16384
	v_exp_f32_e32 v132, v32
	v_exp_f32_e32 v133, v33
	v_exp_f32_e32 v134, v34
	v_exp_f32_e32 v135, v35
	v_mfma_f32_32x32x16_bf16 v[96:111], v[48:51], v[168:171], v[96:111]
	ds_read_b128 v[32:35], v236 offset:20480
	v_exp_f32_e32 v136, v36
	v_exp_f32_e32 v137, v37
	v_exp_f32_e32 v138, v38
	v_exp_f32_e32 v139, v39
	s_waitcnt lgkmcnt(0)
	v_mfma_f32_32x32x16_bf16 v[112:127], v[52:55], v[172:175], v[112:127]
	ds_read_b128 v[36:39], v236 offset:24576
	v_exp_f32_e32 v152, v40
	v_exp_f32_e32 v153, v41
	v_exp_f32_e32 v154, v42
	v_exp_f32_e32 v155, v43
	v_mfma_f32_32x32x16_bf16 v[96:111], v[56:59], v[172:175], v[96:111]
	ds_read_b128 v[40:43], v236 offset:28672
	v_exp_f32_e32 v156, v44
	v_exp_f32_e32 v157, v45
	v_exp_f32_e32 v158, v46
	v_exp_f32_e32 v159, v47
	v_cvt_pk_bf16_f32 v44, v140, v141
	v_cvt_pk_bf16_f32 v45, v142, v143
	v_cvt_pk_bf16_f32 v46, v144, v145
	v_cvt_pk_bf16_f32 v47, v146, v147
	s_nop 1
	v_mfma_f32_32x32x16_bf16 v[80:95], v[60:63], v[44:47], v[80:95]
	ds_read_b128 v[48:51], v237 offset:16384
	v_cvt_pk_bf16_f32 v52, v148, v149
	v_cvt_pk_bf16_f32 v53, v150, v151
	v_cvt_pk_bf16_f32 v54, v128, v129
	v_cvt_pk_bf16_f32 v55, v130, v131
	v_mfma_f32_32x32x16_bf16 v[64:79], v[32:35], v[44:47], v[64:79]
	ds_read_b128 v[56:59], v237 offset:20480
	v_pk_add_f32 v[62:63], v[146:147], v[142:143]
	v_pk_add_f32 v[60:61], v[144:145], v[140:141]
	s_waitcnt lgkmcnt(0)
	v_mfma_f32_32x32x16_bf16 v[16:31], v[36:39], v[44:47], v[16:31]
	ds_read_b128 v[32:35], v237 offset:24576
	v_add_f32_e64 v62, v150, v62
	v_add_f32_e64 v63, v151, v63
	v_add_f32_e64 v60, v148, v60
	v_add_f32_e64 v61, v149, v61
	v_pk_add_f32 v[62:63], v[130:131], v[62:63]
	v_pk_add_f32 v[60:61], v[128:129], v[60:61]
	v_mfma_f32_32x32x16_bf16 v[0:15], v[40:43], v[44:47], v[0:15]
	ds_read_b128 v[36:39], v237 offset:28672
	v_mfma_f32_32x32x16_bf16 v[80:95], v[48:51], v[52:55], v[80:95]
	ds_read_b128 v[40:43], v238 offset:16384
	v_cvt_pk_bf16_f32 v44, v132, v133
	v_cvt_pk_bf16_f32 v45, v134, v135
	v_cvt_pk_bf16_f32 v46, v136, v137
	v_cvt_pk_bf16_f32 v47, v138, v139
	v_mfma_f32_32x32x16_bf16 v[64:79], v[56:59], v[52:55], v[64:79]
	ds_read_b128 v[48:51], v238 offset:20480
	v_add_f32_e64 v62, v134, v62
	v_add_f32_e64 v63, v135, v63
	v_add_f32_e64 v60, v132, v60
	v_add_f32_e64 v61, v133, v61
	v_pk_add_f32 v[62:63], v[138:139], v[62:63]
	v_pk_add_f32 v[60:61], v[136:137], v[60:61]
	s_waitcnt lgkmcnt(0)
	v_mfma_f32_32x32x16_bf16 v[16:31], v[32:35], v[52:55], v[16:31]
	ds_read_b128 v[56:59], v238 offset:24576
	v_add_f32_e64 v62, v154, v62
	v_add_f32_e64 v63, v155, v63
	v_add_f32_e64 v60, v152, v60
	v_add_f32_e64 v61, v153, v61
	v_pk_add_f32 v[130:131], v[158:159], v[62:63]
	v_pk_add_f32 v[128:129], v[156:157], v[60:61]
	v_mfma_f32_32x32x16_bf16 v[0:15], v[36:39], v[52:55], v[0:15]
	ds_read_b128 v[32:35], v238 offset:28672
	v_mfma_f32_32x32x16_bf16 v[80:95], v[40:43], v[44:47], v[80:95]
	ds_read_b128 v[36:39], v239 offset:16384
	v_cvt_pk_bf16_f32 v52, v152, v153
	v_cvt_pk_bf16_f32 v53, v154, v155
	v_cvt_pk_bf16_f32 v54, v156, v157
	v_cvt_pk_bf16_f32 v55, v158, v159
	v_mfma_f32_32x32x16_bf16 v[64:79], v[48:51], v[44:47], v[64:79]
	ds_read_b128 v[40:43], v239 offset:20480
	s_waitcnt lgkmcnt(0)
	v_mfma_f32_32x32x16_bf16 v[16:31], v[56:59], v[44:47], v[16:31]
	ds_read_b128 v[48:51], v239 offset:24576
	v_mfma_f32_32x32x16_bf16 v[0:15], v[32:35], v[44:47], v[0:15]
	ds_read_b128 v[56:59], v239 offset:28672
	v_mfma_f32_32x32x16_bf16 v[80:95], v[36:39], v[52:55], v[80:95]
	v_mfma_f32_32x32x16_bf16 v[64:79], v[40:43], v[52:55], v[64:79]
	s_waitcnt lgkmcnt(0)
	v_mfma_f32_32x32x16_bf16 v[16:31], v[48:51], v[52:55], v[16:31]
	v_mfma_f32_32x32x16_bf16 v[0:15], v[56:59], v[52:55], v[0:15]
	s_waitcnt vmcnt(4) lgkmcnt(0)
	s_barrier
	ds_read_b128 v[32:35], v205 offset:32768
	ds_read_b128 v[36:39], v205 offset:40960
	s_add_u32 s68, s98, 0x18000
	s_addc_u32 s69, s99, 0
	s_add_i32 s49, 0x4000, s57
	s_mov_b32 m0, s49
	s_nop 0
	global_load_lds_dwordx4 v198, s[68:69]
	s_add_i32 m0, s49, 0x400
	s_nop 0
	global_load_lds_dwordx4 v194, s[68:69]
	s_add_u32 s44, s100, 0x80
	s_addc_u32 s45, s101, 0
	s_add_i32 s49, s58, 0x4000
	s_add_i32 m0, s49, 0xc000
	s_nop 0
	global_load_lds_dwordx4 v196, s[44:45]
	s_add_i32 m0, s49, 0xc400
	s_nop 0
	global_load_lds_dwordx4 v192, s[44:45]
	v_exp_f32_e32 v144, v112
	s_waitcnt lgkmcnt(0)
	v_mfma_f32_32x32x16_bf16 v[48:63], v[32:35], v[160:163], 0
	ds_read_b128 v[132:135], v211 offset:32768
	ds_read_b128 v[136:139], v211 offset:40960
	ds_read_b128 v[140:143], v212 offset:32768
	v_exp_f32_e32 v145, v113
	v_exp_f32_e32 v146, v114
	v_exp_f32_e32 v147, v115
	ds_read_b128 v[112:115], v212 offset:40960
	v_mfma_f32_32x32x16_bf16 v[32:47], v[36:39], v[160:163], 0
	v_exp_f32_e32 v148, v116
	v_exp_f32_e32 v149, v117
	v_exp_f32_e32 v150, v118
	v_exp_f32_e32 v151, v119
	s_waitcnt lgkmcnt(0)
	v_mfma_f32_32x32x16_bf16 v[48:63], v[132:135], v[164:167], v[48:63]
	ds_read_b128 v[116:119], v213 offset:32768
	v_exp_f32_e32 v152, v120
	v_exp_f32_e32 v153, v121
	v_exp_f32_e32 v154, v122
	v_exp_f32_e32 v155, v123
	v_mfma_f32_32x32x16_bf16 v[32:47], v[136:139], v[164:167], v[32:47]
	ds_read_b128 v[120:123], v213 offset:40960
	v_exp_f32_e32 v156, v124
	v_exp_f32_e32 v157, v125
	v_exp_f32_e32 v158, v126
	v_exp_f32_e32 v159, v127
	v_mfma_f32_32x32x16_bf16 v[48:63], v[140:143], v[168:171], v[48:63]
	ds_read_b128 v[124:127], v236 offset:32768
	v_exp_f32_e32 v136, v96
	v_exp_f32_e32 v137, v97
	v_exp_f32_e32 v138, v98
	v_exp_f32_e32 v139, v99
	v_mfma_f32_32x32x16_bf16 v[32:47], v[112:115], v[168:171], v[32:47]
	ds_read_b128 v[96:99], v236 offset:36864
	v_exp_f32_e32 v140, v100
	v_exp_f32_e32 v141, v101
	v_exp_f32_e32 v142, v102
	v_exp_f32_e32 v143, v103
	s_waitcnt lgkmcnt(0)
	v_mfma_f32_32x32x16_bf16 v[48:63], v[116:119], v[172:175], v[48:63]
	ds_read_b128 v[100:103], v236 offset:40960
	v_exp_f32_e32 v178, v104
	v_exp_f32_e32 v179, v105
	v_exp_f32_e32 v180, v106
	v_exp_f32_e32 v181, v107
	v_mfma_f32_32x32x16_bf16 v[32:47], v[120:123], v[172:175], v[32:47]
	ds_read_b128 v[104:107], v236 offset:45056
	v_exp_f32_e32 v182, v108
	v_exp_f32_e32 v183, v109
	v_exp_f32_e32 v184, v110
	v_exp_f32_e32 v185, v111
	v_cvt_pk_bf16_f32 v108, v144, v145
	v_cvt_pk_bf16_f32 v109, v146, v147
	v_cvt_pk_bf16_f32 v110, v148, v149
	v_cvt_pk_bf16_f32 v111, v150, v151
	s_nop 1
	v_mfma_f32_32x32x16_bf16 v[80:95], v[124:127], v[108:111], v[80:95]
	ds_read_b128 v[112:115], v237 offset:32768
	v_cvt_pk_bf16_f32 v116, v152, v153
	v_cvt_pk_bf16_f32 v117, v154, v155
	v_cvt_pk_bf16_f32 v118, v156, v157
	v_cvt_pk_bf16_f32 v119, v158, v159
	v_mfma_f32_32x32x16_bf16 v[64:79], v[96:99], v[108:111], v[64:79]
	ds_read_b128 v[120:123], v237 offset:36864
	v_pk_add_f32 v[126:127], v[150:151], v[146:147]
	v_pk_add_f32 v[124:125], v[148:149], v[144:145]
	s_waitcnt lgkmcnt(0)
	v_mfma_f32_32x32x16_bf16 v[16:31], v[100:103], v[108:111], v[16:31]
	ds_read_b128 v[132:135], v237 offset:40960
	v_add_f32_e64 v98, v154, v126
	v_add_f32_e64 v99, v155, v127
	v_add_f32_e64 v96, v152, v124
	v_add_f32_e64 v97, v153, v125
	v_pk_add_f32 v[98:99], v[158:159], v[98:99]
	v_pk_add_f32 v[96:97], v[156:157], v[96:97]
	v_mfma_f32_32x32x16_bf16 v[0:15], v[104:107], v[108:111], v[0:15]
	ds_read_b128 v[100:103], v237 offset:45056
	v_mfma_f32_32x32x16_bf16 v[80:95], v[112:115], v[116:119], v[80:95]
	ds_read_b128 v[104:107], v238 offset:32768
	v_cvt_pk_bf16_f32 v108, v136, v137
	v_cvt_pk_bf16_f32 v109, v138, v139
	v_cvt_pk_bf16_f32 v110, v140, v141
	v_cvt_pk_bf16_f32 v111, v142, v143
	v_mfma_f32_32x32x16_bf16 v[64:79], v[120:123], v[116:119], v[64:79]
	ds_read_b128 v[112:115], v238 offset:36864
	v_add_f32_e64 v98, v138, v98
	v_add_f32_e64 v99, v139, v99
	v_add_f32_e64 v96, v136, v96
	v_add_f32_e64 v97, v137, v97
	v_pk_add_f32 v[98:99], v[142:143], v[98:99]
	v_pk_add_f32 v[96:97], v[140:141], v[96:97]
	s_waitcnt lgkmcnt(0)
	v_mfma_f32_32x32x16_bf16 v[16:31], v[132:135], v[116:119], v[16:31]
	ds_read_b128 v[120:123], v238 offset:40960
	v_add_f32_e64 v98, v180, v98
	v_add_f32_e64 v99, v181, v99
	v_add_f32_e64 v96, v178, v96
	v_add_f32_e64 v97, v179, v97
	v_pk_add_f32 v[98:99], v[184:185], v[98:99]
	v_pk_add_f32 v[96:97], v[182:183], v[96:97]
	v_mfma_f32_32x32x16_bf16 v[0:15], v[100:103], v[116:119], v[0:15]
	ds_read_b128 v[124:127], v238 offset:45056
	v_mfma_f32_32x32x16_bf16 v[80:95], v[104:107], v[108:111], v[80:95]
	ds_read_b128 v[100:103], v239 offset:32768
	v_cvt_pk_bf16_f32 v116, v178, v179
	v_cvt_pk_bf16_f32 v117, v180, v181
	v_cvt_pk_bf16_f32 v118, v182, v183
	v_cvt_pk_bf16_f32 v119, v184, v185
	v_mfma_f32_32x32x16_bf16 v[64:79], v[112:115], v[108:111], v[64:79]
	ds_read_b128 v[104:107], v239 offset:36864
	s_waitcnt lgkmcnt(0)
	v_mfma_f32_32x32x16_bf16 v[16:31], v[120:123], v[108:111], v[16:31]
	ds_read_b128 v[112:115], v239 offset:40960
	v_mfma_f32_32x32x16_bf16 v[0:15], v[124:127], v[108:111], v[0:15]
	ds_read_b128 v[120:123], v239 offset:45056
	v_mfma_f32_32x32x16_bf16 v[80:95], v[100:103], v[116:119], v[80:95]
	v_mfma_f32_32x32x16_bf16 v[64:79], v[104:107], v[116:119], v[64:79]
	s_waitcnt lgkmcnt(0)
	v_mfma_f32_32x32x16_bf16 v[16:31], v[112:115], v[116:119], v[16:31]
	v_mfma_f32_32x32x16_bf16 v[0:15], v[120:123], v[116:119], v[0:15]
	s_waitcnt vmcnt(4) lgkmcnt(0)
	v_add_f32_e32 v100, v128, v129
	v_add_f32_e32 v101, v130, v131
	v_add_f32_e32 v100, v100, v101
	v_add_f32_e32 v96, v96, v97
	v_add_f32_e32 v97, v98, v99
	s_barrier
	v_add_f32_e32 v100, v177, v100
	v_add_f32_e32 v96, v96, v97
	v_add_f32_e32 v177, v100, v96
	ds_read_b128 v[96:99], v205
	ds_read_b128 v[100:103], v205 offset:8192
	s_add_u32 s98, s98, 0x30000
	s_addc_u32 s99, s99, 0
	s_add_u32 s100, s100, 0x100
	s_addc_u32 s101, s101, 0
	s_add_i32 s46, s58, 0x8000
	s_mov_b32 m0, s46
	s_nop 0
	global_load_lds_dwordx4 v198, s[98:99]
	s_add_i32 m0, s46, 0x400
	s_nop 0
	global_load_lds_dwordx4 v194, s[98:99]
	s_add_i32 s48, s58, 0x8000
	s_add_i32 m0, s48, 0xc000
	s_nop 0
	global_load_lds_dwordx4 v196, s[100:101]
	s_add_i32 m0, s48, 0xc400
	s_nop 0
	global_load_lds_dwordx4 v192, s[100:101]
	s_waitcnt lgkmcnt(0)
	v_mfma_f32_32x32x16_bf16 v[112:127], v[96:99], v[160:163], 0
	ds_read_b128 v[128:131], v211
	ds_read_b128 v[132:135], v211 offset:8192
	ds_read_b128 v[136:139], v212
	v_exp_f32_e32 v140, v48
	v_exp_f32_e32 v141, v49
	v_exp_f32_e32 v142, v50
	v_exp_f32_e32 v143, v51
	ds_read_b128 v[48:51], v212 offset:8192
	v_mfma_f32_32x32x16_bf16 v[96:111], v[100:103], v[160:163], 0
	v_exp_f32_e32 v144, v52
	v_exp_f32_e32 v145, v53
	v_exp_f32_e32 v146, v54
	v_exp_f32_e32 v147, v55
	s_waitcnt lgkmcnt(0)
	v_mfma_f32_32x32x16_bf16 v[112:127], v[128:131], v[164:167], v[112:127]
	ds_read_b128 v[52:55], v213
	v_exp_f32_e32 v148, v56
	v_exp_f32_e32 v149, v57
	v_exp_f32_e32 v150, v58
	v_exp_f32_e32 v151, v59
	v_mfma_f32_32x32x16_bf16 v[96:111], v[132:135], v[164:167], v[96:111]
	ds_read_b128 v[56:59], v213 offset:8192
	v_exp_f32_e32 v128, v60
	v_exp_f32_e32 v129, v61
	v_exp_f32_e32 v130, v62
	v_exp_f32_e32 v131, v63
	v_mfma_f32_32x32x16_bf16 v[112:127], v[136:139], v[168:171], v[112:127]
	ds_read_b128 v[60:63], v206 offset:49152
	v_exp_f32_e32 v132, v32
	v_exp_f32_e32 v133, v33
	v_exp_f32_e32 v134, v34
	v_exp_f32_e32 v135, v35
	v_mfma_f32_32x32x16_bf16 v[96:111], v[48:51], v[168:171], v[96:111]
	ds_read_b128 v[32:35], v206 offset:53248
	v_exp_f32_e32 v136, v36
	v_exp_f32_e32 v137, v37
	v_exp_f32_e32 v138, v38
	v_exp_f32_e32 v139, v39
	s_waitcnt lgkmcnt(0)
	v_mfma_f32_32x32x16_bf16 v[112:127], v[52:55], v[172:175], v[112:127]
	ds_read_b128 v[36:39], v206 offset:57344
	v_exp_f32_e32 v152, v40
	v_exp_f32_e32 v153, v41
	v_exp_f32_e32 v154, v42
	v_exp_f32_e32 v155, v43
	v_mfma_f32_32x32x16_bf16 v[96:111], v[56:59], v[172:175], v[96:111]
	ds_read_b128 v[40:43], v206 offset:61440
	v_exp_f32_e32 v156, v44
	v_exp_f32_e32 v157, v45
	v_exp_f32_e32 v158, v46
	v_exp_f32_e32 v159, v47
	v_cvt_pk_bf16_f32 v44, v140, v141
	v_cvt_pk_bf16_f32 v45, v142, v143
	v_cvt_pk_bf16_f32 v46, v144, v145
	v_cvt_pk_bf16_f32 v47, v146, v147
	s_nop 1
	v_mfma_f32_32x32x16_bf16 v[80:95], v[60:63], v[44:47], v[80:95]
	ds_read_b128 v[48:51], v207 offset:49152
	v_cvt_pk_bf16_f32 v52, v148, v149
	v_cvt_pk_bf16_f32 v53, v150, v151
	v_cvt_pk_bf16_f32 v54, v128, v129
	v_cvt_pk_bf16_f32 v55, v130, v131
	v_mfma_f32_32x32x16_bf16 v[64:79], v[32:35], v[44:47], v[64:79]
	ds_read_b128 v[56:59], v207 offset:53248
	v_pk_add_f32 v[62:63], v[146:147], v[142:143]
	v_pk_add_f32 v[60:61], v[144:145], v[140:141]
	s_waitcnt lgkmcnt(0)
	v_mfma_f32_32x32x16_bf16 v[16:31], v[36:39], v[44:47], v[16:31]
	ds_read_b128 v[32:35], v207 offset:57344
	v_add_f32_e64 v62, v150, v62
	v_add_f32_e64 v63, v151, v63
	v_add_f32_e64 v60, v148, v60
	v_add_f32_e64 v61, v149, v61
	v_pk_add_f32 v[62:63], v[130:131], v[62:63]
	v_pk_add_f32 v[60:61], v[128:129], v[60:61]
	v_mfma_f32_32x32x16_bf16 v[0:15], v[40:43], v[44:47], v[0:15]
	ds_read_b128 v[36:39], v207 offset:61440
	v_mfma_f32_32x32x16_bf16 v[80:95], v[48:51], v[52:55], v[80:95]
	ds_read_b128 v[40:43], v208 offset:49152
	v_cvt_pk_bf16_f32 v44, v132, v133
	v_cvt_pk_bf16_f32 v45, v134, v135
	v_cvt_pk_bf16_f32 v46, v136, v137
	v_cvt_pk_bf16_f32 v47, v138, v139
	v_mfma_f32_32x32x16_bf16 v[64:79], v[56:59], v[52:55], v[64:79]
	ds_read_b128 v[48:51], v208 offset:53248
	v_add_f32_e64 v62, v134, v62
	v_add_f32_e64 v63, v135, v63
	v_add_f32_e64 v60, v132, v60
	v_add_f32_e64 v61, v133, v61
	v_pk_add_f32 v[62:63], v[138:139], v[62:63]
	v_pk_add_f32 v[60:61], v[136:137], v[60:61]
	s_waitcnt lgkmcnt(0)
	v_mfma_f32_32x32x16_bf16 v[16:31], v[32:35], v[52:55], v[16:31]
	ds_read_b128 v[56:59], v208 offset:57344
	v_add_f32_e64 v62, v154, v62
	v_add_f32_e64 v63, v155, v63
	v_add_f32_e64 v60, v152, v60
	v_add_f32_e64 v61, v153, v61
	v_pk_add_f32 v[130:131], v[158:159], v[62:63]
	v_pk_add_f32 v[128:129], v[156:157], v[60:61]
	v_mfma_f32_32x32x16_bf16 v[0:15], v[36:39], v[52:55], v[0:15]
	ds_read_b128 v[32:35], v208 offset:61440
	v_mfma_f32_32x32x16_bf16 v[80:95], v[40:43], v[44:47], v[80:95]
	ds_read_b128 v[36:39], v209 offset:49152
	v_cvt_pk_bf16_f32 v52, v152, v153
	v_cvt_pk_bf16_f32 v53, v154, v155
	v_cvt_pk_bf16_f32 v54, v156, v157
	v_cvt_pk_bf16_f32 v55, v158, v159
	v_mfma_f32_32x32x16_bf16 v[64:79], v[48:51], v[44:47], v[64:79]
	ds_read_b128 v[40:43], v209 offset:53248
	s_waitcnt lgkmcnt(0)
	v_mfma_f32_32x32x16_bf16 v[16:31], v[56:59], v[44:47], v[16:31]
	ds_read_b128 v[48:51], v209 offset:57344
	v_mfma_f32_32x32x16_bf16 v[0:15], v[32:35], v[44:47], v[0:15]
	ds_read_b128 v[56:59], v209 offset:61440
	v_mfma_f32_32x32x16_bf16 v[80:95], v[36:39], v[52:55], v[80:95]
	v_mfma_f32_32x32x16_bf16 v[64:79], v[40:43], v[52:55], v[64:79]
	s_waitcnt lgkmcnt(0)
	v_mfma_f32_32x32x16_bf16 v[16:31], v[48:51], v[52:55], v[16:31]
	v_mfma_f32_32x32x16_bf16 v[0:15], v[56:59], v[52:55], v[0:15]
	s_waitcnt vmcnt(4) lgkmcnt(0)
	s_barrier
	ds_read_b128 v[32:35], v205 offset:16384
	ds_read_b128 v[36:39], v205 offset:24576
	s_add_u32 s68, s98, 0x18000
	s_addc_u32 s69, s99, 0
	s_add_i32 s49, 0, s57
	s_mov_b32 m0, s49
	s_nop 0
	global_load_lds_dwordx4 v198, s[68:69]
	s_add_i32 m0, s49, 0x400
	s_nop 0
	global_load_lds_dwordx4 v194, s[68:69]
	s_add_u32 s44, s100, 0x80
	s_addc_u32 s45, s101, 0
	s_add_i32 s49, s58, 0xc000
	s_add_i32 m0, s49, 0xc000
	s_nop 0
	global_load_lds_dwordx4 v196, s[44:45]
	s_add_i32 m0, s49, 0xc400
	s_nop 0
	global_load_lds_dwordx4 v192, s[44:45]
	v_exp_f32_e32 v144, v112
	s_waitcnt lgkmcnt(0)
	v_mfma_f32_32x32x16_bf16 v[48:63], v[32:35], v[160:163], 0
	ds_read_b128 v[132:135], v211 offset:16384
	ds_read_b128 v[136:139], v211 offset:24576
	ds_read_b128 v[140:143], v212 offset:16384
	v_exp_f32_e32 v145, v113
	v_exp_f32_e32 v146, v114
	v_exp_f32_e32 v147, v115
	ds_read_b128 v[112:115], v212 offset:24576
	v_mfma_f32_32x32x16_bf16 v[32:47], v[36:39], v[160:163], 0
	v_exp_f32_e32 v148, v116
	v_exp_f32_e32 v149, v117
	v_exp_f32_e32 v150, v118
	v_exp_f32_e32 v151, v119
	s_waitcnt lgkmcnt(0)
	v_mfma_f32_32x32x16_bf16 v[48:63], v[132:135], v[164:167], v[48:63]
	ds_read_b128 v[116:119], v213 offset:16384
	v_exp_f32_e32 v152, v120
	v_exp_f32_e32 v153, v121
	v_exp_f32_e32 v154, v122
	v_exp_f32_e32 v155, v123
	v_mfma_f32_32x32x16_bf16 v[32:47], v[136:139], v[164:167], v[32:47]
	ds_read_b128 v[120:123], v213 offset:24576
	v_exp_f32_e32 v156, v124
	v_exp_f32_e32 v157, v125
	v_exp_f32_e32 v158, v126
	v_exp_f32_e32 v159, v127
	v_mfma_f32_32x32x16_bf16 v[48:63], v[140:143], v[168:171], v[48:63]
	ds_read_b128 v[124:127], v236
	v_exp_f32_e32 v136, v96
	v_exp_f32_e32 v137, v97
	v_exp_f32_e32 v138, v98
	v_exp_f32_e32 v139, v99
	v_mfma_f32_32x32x16_bf16 v[32:47], v[112:115], v[168:171], v[32:47]
	ds_read_b128 v[96:99], v236 offset:4096
	v_exp_f32_e32 v140, v100
	v_exp_f32_e32 v141, v101
	v_exp_f32_e32 v142, v102
	v_exp_f32_e32 v143, v103
	s_waitcnt lgkmcnt(0)
	v_mfma_f32_32x32x16_bf16 v[48:63], v[116:119], v[172:175], v[48:63]
	ds_read_b128 v[100:103], v236 offset:8192
	v_exp_f32_e32 v178, v104
	v_exp_f32_e32 v179, v105
	v_exp_f32_e32 v180, v106
	v_exp_f32_e32 v181, v107
	v_mfma_f32_32x32x16_bf16 v[32:47], v[120:123], v[172:175], v[32:47]
	ds_read_b128 v[104:107], v236 offset:12288
	v_exp_f32_e32 v182, v108
	v_exp_f32_e32 v183, v109
	v_exp_f32_e32 v184, v110
	v_exp_f32_e32 v185, v111
	v_cvt_pk_bf16_f32 v108, v144, v145
	v_cvt_pk_bf16_f32 v109, v146, v147
	v_cvt_pk_bf16_f32 v110, v148, v149
	v_cvt_pk_bf16_f32 v111, v150, v151
	s_nop 1
	v_mfma_f32_32x32x16_bf16 v[80:95], v[124:127], v[108:111], v[80:95]
	ds_read_b128 v[112:115], v237
	v_cvt_pk_bf16_f32 v116, v152, v153
	v_cvt_pk_bf16_f32 v117, v154, v155
	v_cvt_pk_bf16_f32 v118, v156, v157
	v_cvt_pk_bf16_f32 v119, v158, v159
	v_mfma_f32_32x32x16_bf16 v[64:79], v[96:99], v[108:111], v[64:79]
	ds_read_b128 v[120:123], v237 offset:4096
	v_pk_add_f32 v[126:127], v[150:151], v[146:147]
	v_pk_add_f32 v[124:125], v[148:149], v[144:145]
	s_waitcnt lgkmcnt(0)
	v_mfma_f32_32x32x16_bf16 v[16:31], v[100:103], v[108:111], v[16:31]
	ds_read_b128 v[132:135], v237 offset:8192
	v_add_f32_e64 v98, v154, v126
	v_add_f32_e64 v99, v155, v127
	v_add_f32_e64 v96, v152, v124
	v_add_f32_e64 v97, v153, v125
	v_pk_add_f32 v[98:99], v[158:159], v[98:99]
	v_pk_add_f32 v[96:97], v[156:157], v[96:97]
	v_mfma_f32_32x32x16_bf16 v[0:15], v[104:107], v[108:111], v[0:15]
	ds_read_b128 v[100:103], v237 offset:12288
	v_mfma_f32_32x32x16_bf16 v[80:95], v[112:115], v[116:119], v[80:95]
	ds_read_b128 v[104:107], v238
	v_cvt_pk_bf16_f32 v108, v136, v137
	v_cvt_pk_bf16_f32 v109, v138, v139
	v_cvt_pk_bf16_f32 v110, v140, v141
	v_cvt_pk_bf16_f32 v111, v142, v143
	v_mfma_f32_32x32x16_bf16 v[64:79], v[120:123], v[116:119], v[64:79]
	ds_read_b128 v[112:115], v238 offset:4096
	v_add_f32_e64 v98, v138, v98
	v_add_f32_e64 v99, v139, v99
	v_add_f32_e64 v96, v136, v96
	v_add_f32_e64 v97, v137, v97
	v_pk_add_f32 v[98:99], v[142:143], v[98:99]
	v_pk_add_f32 v[96:97], v[140:141], v[96:97]
	s_waitcnt lgkmcnt(0)
	v_mfma_f32_32x32x16_bf16 v[16:31], v[132:135], v[116:119], v[16:31]
	ds_read_b128 v[120:123], v238 offset:8192
	v_add_f32_e64 v98, v180, v98
	v_add_f32_e64 v99, v181, v99
	v_add_f32_e64 v96, v178, v96
	v_add_f32_e64 v97, v179, v97
	v_pk_add_f32 v[98:99], v[184:185], v[98:99]
	v_pk_add_f32 v[96:97], v[182:183], v[96:97]
	v_mfma_f32_32x32x16_bf16 v[0:15], v[100:103], v[116:119], v[0:15]
	ds_read_b128 v[124:127], v238 offset:12288
	v_mfma_f32_32x32x16_bf16 v[80:95], v[104:107], v[108:111], v[80:95]
	ds_read_b128 v[100:103], v239
	v_cvt_pk_bf16_f32 v116, v178, v179
	v_cvt_pk_bf16_f32 v117, v180, v181
	v_cvt_pk_bf16_f32 v118, v182, v183
	v_cvt_pk_bf16_f32 v119, v184, v185
	v_mfma_f32_32x32x16_bf16 v[64:79], v[112:115], v[108:111], v[64:79]
	ds_read_b128 v[104:107], v239 offset:4096
	s_waitcnt lgkmcnt(0)
	v_mfma_f32_32x32x16_bf16 v[16:31], v[120:123], v[108:111], v[16:31]
	ds_read_b128 v[112:115], v239 offset:8192
	v_mfma_f32_32x32x16_bf16 v[0:15], v[124:127], v[108:111], v[0:15]
	ds_read_b128 v[120:123], v239 offset:12288
	v_mfma_f32_32x32x16_bf16 v[80:95], v[100:103], v[116:119], v[80:95]
	v_mfma_f32_32x32x16_bf16 v[64:79], v[104:107], v[116:119], v[64:79]
	s_waitcnt lgkmcnt(0)
	v_mfma_f32_32x32x16_bf16 v[16:31], v[112:115], v[116:119], v[16:31]
	v_mfma_f32_32x32x16_bf16 v[0:15], v[120:123], v[116:119], v[0:15]
	s_waitcnt vmcnt(4) lgkmcnt(0)
	v_add_f32_e32 v100, v128, v129
	v_add_f32_e32 v101, v130, v131
	v_add_f32_e32 v100, v100, v101
	v_add_f32_e32 v96, v96, v97
	v_add_f32_e32 v97, v98, v99
	s_barrier
	v_add_f32_e32 v100, v177, v100
	v_add_f32_e32 v96, v96, v97
	v_add_f32_e32 v177, v100, v96
	ds_read_b128 v[96:99], v205 offset:32768
	ds_read_b128 v[100:103], v205 offset:40960
	s_add_u32 s98, s98, 0x30000
	s_addc_u32 s99, s99, 0
	s_add_u32 s100, s100, 0x100
	s_addc_u32 s101, s101, 0
	s_add_i32 s46, s58, 0x4000
	s_mov_b32 m0, s46
	s_nop 0
	global_load_lds_dwordx4 v198, s[98:99]
	s_add_i32 m0, s46, 0x400
	s_nop 0
	global_load_lds_dwordx4 v194, s[98:99]
	s_add_i32 s48, s58, 0
	s_add_i32 m0, s48, 0xc000
	s_nop 0
	global_load_lds_dwordx4 v196, s[100:101]
	s_add_i32 m0, s48, 0xc400
	s_nop 0
	global_load_lds_dwordx4 v192, s[100:101]
	s_waitcnt lgkmcnt(0)
	v_mfma_f32_32x32x16_bf16 v[112:127], v[96:99], v[160:163], 0
	ds_read_b128 v[128:131], v211 offset:32768
	ds_read_b128 v[132:135], v211 offset:40960
	ds_read_b128 v[136:139], v212 offset:32768
	v_exp_f32_e32 v140, v48
	v_exp_f32_e32 v141, v49
	v_exp_f32_e32 v142, v50
	v_exp_f32_e32 v143, v51
	ds_read_b128 v[48:51], v212 offset:40960
	v_mfma_f32_32x32x16_bf16 v[96:111], v[100:103], v[160:163], 0
	v_exp_f32_e32 v144, v52
	v_exp_f32_e32 v145, v53
	v_exp_f32_e32 v146, v54
	v_exp_f32_e32 v147, v55
	s_waitcnt lgkmcnt(0)
	v_mfma_f32_32x32x16_bf16 v[112:127], v[128:131], v[164:167], v[112:127]
	ds_read_b128 v[52:55], v213 offset:32768
	v_exp_f32_e32 v148, v56
	v_exp_f32_e32 v149, v57
	v_exp_f32_e32 v150, v58
	v_exp_f32_e32 v151, v59
	v_mfma_f32_32x32x16_bf16 v[96:111], v[132:135], v[164:167], v[96:111]
	ds_read_b128 v[56:59], v213 offset:40960
	v_exp_f32_e32 v128, v60
	v_exp_f32_e32 v129, v61
	v_exp_f32_e32 v130, v62
	v_exp_f32_e32 v131, v63
	v_mfma_f32_32x32x16_bf16 v[112:127], v[136:139], v[168:171], v[112:127]
	ds_read_b128 v[60:63], v236 offset:16384
	v_exp_f32_e32 v132, v32
	v_exp_f32_e32 v133, v33
	v_exp_f32_e32 v134, v34
	v_exp_f32_e32 v135, v35
	v_mfma_f32_32x32x16_bf16 v[96:111], v[48:51], v[168:171], v[96:111]
	ds_read_b128 v[32:35], v236 offset:20480
	v_exp_f32_e32 v136, v36
	v_exp_f32_e32 v137, v37
	v_exp_f32_e32 v138, v38
	v_exp_f32_e32 v139, v39
	s_waitcnt lgkmcnt(0)
	v_mfma_f32_32x32x16_bf16 v[112:127], v[52:55], v[172:175], v[112:127]
	ds_read_b128 v[36:39], v236 offset:24576
	v_exp_f32_e32 v152, v40
	v_exp_f32_e32 v153, v41
	v_exp_f32_e32 v154, v42
	v_exp_f32_e32 v155, v43
	v_mfma_f32_32x32x16_bf16 v[96:111], v[56:59], v[172:175], v[96:111]
	ds_read_b128 v[40:43], v236 offset:28672
	v_exp_f32_e32 v156, v44
	v_exp_f32_e32 v157, v45
	v_exp_f32_e32 v158, v46
	v_exp_f32_e32 v159, v47
	v_cvt_pk_bf16_f32 v44, v140, v141
	v_cvt_pk_bf16_f32 v45, v142, v143
	v_cvt_pk_bf16_f32 v46, v144, v145
	v_cvt_pk_bf16_f32 v47, v146, v147
	s_nop 1
	v_mfma_f32_32x32x16_bf16 v[80:95], v[60:63], v[44:47], v[80:95]
	ds_read_b128 v[48:51], v237 offset:16384
	v_cvt_pk_bf16_f32 v52, v148, v149
	v_cvt_pk_bf16_f32 v53, v150, v151
	v_cvt_pk_bf16_f32 v54, v128, v129
	v_cvt_pk_bf16_f32 v55, v130, v131
	v_mfma_f32_32x32x16_bf16 v[64:79], v[32:35], v[44:47], v[64:79]
	ds_read_b128 v[56:59], v237 offset:20480
	v_pk_add_f32 v[62:63], v[146:147], v[142:143]
	v_pk_add_f32 v[60:61], v[144:145], v[140:141]
	s_waitcnt lgkmcnt(0)
	v_mfma_f32_32x32x16_bf16 v[16:31], v[36:39], v[44:47], v[16:31]
	ds_read_b128 v[32:35], v237 offset:24576
	v_add_f32_e64 v62, v150, v62
	v_add_f32_e64 v63, v151, v63
	v_add_f32_e64 v60, v148, v60
	v_add_f32_e64 v61, v149, v61
	v_pk_add_f32 v[62:63], v[130:131], v[62:63]
	v_pk_add_f32 v[60:61], v[128:129], v[60:61]
	v_mfma_f32_32x32x16_bf16 v[0:15], v[40:43], v[44:47], v[0:15]
	ds_read_b128 v[36:39], v237 offset:28672
	v_mfma_f32_32x32x16_bf16 v[80:95], v[48:51], v[52:55], v[80:95]
	ds_read_b128 v[40:43], v238 offset:16384
	v_cvt_pk_bf16_f32 v44, v132, v133
	v_cvt_pk_bf16_f32 v45, v134, v135
	v_cvt_pk_bf16_f32 v46, v136, v137
	v_cvt_pk_bf16_f32 v47, v138, v139
	v_mfma_f32_32x32x16_bf16 v[64:79], v[56:59], v[52:55], v[64:79]
	ds_read_b128 v[48:51], v238 offset:20480
	v_add_f32_e64 v62, v134, v62
	v_add_f32_e64 v63, v135, v63
	v_add_f32_e64 v60, v132, v60
	v_add_f32_e64 v61, v133, v61
	v_pk_add_f32 v[62:63], v[138:139], v[62:63]
	v_pk_add_f32 v[60:61], v[136:137], v[60:61]
	s_waitcnt lgkmcnt(0)
	v_mfma_f32_32x32x16_bf16 v[16:31], v[32:35], v[52:55], v[16:31]
	ds_read_b128 v[56:59], v238 offset:24576
	v_add_f32_e64 v62, v154, v62
	v_add_f32_e64 v63, v155, v63
	v_add_f32_e64 v60, v152, v60
	v_add_f32_e64 v61, v153, v61
	v_pk_add_f32 v[130:131], v[158:159], v[62:63]
	v_pk_add_f32 v[128:129], v[156:157], v[60:61]
	v_mfma_f32_32x32x16_bf16 v[0:15], v[36:39], v[52:55], v[0:15]
	ds_read_b128 v[32:35], v238 offset:28672
	v_mfma_f32_32x32x16_bf16 v[80:95], v[40:43], v[44:47], v[80:95]
	ds_read_b128 v[36:39], v239 offset:16384
	v_cvt_pk_bf16_f32 v52, v152, v153
	v_cvt_pk_bf16_f32 v53, v154, v155
	v_cvt_pk_bf16_f32 v54, v156, v157
	v_cvt_pk_bf16_f32 v55, v158, v159
	v_mfma_f32_32x32x16_bf16 v[64:79], v[48:51], v[44:47], v[64:79]
	ds_read_b128 v[40:43], v239 offset:20480
	s_waitcnt lgkmcnt(0)
	v_mfma_f32_32x32x16_bf16 v[16:31], v[56:59], v[44:47], v[16:31]
	ds_read_b128 v[48:51], v239 offset:24576
	v_mfma_f32_32x32x16_bf16 v[0:15], v[32:35], v[44:47], v[0:15]
	ds_read_b128 v[56:59], v239 offset:28672
	v_mfma_f32_32x32x16_bf16 v[80:95], v[36:39], v[52:55], v[80:95]
	v_mfma_f32_32x32x16_bf16 v[64:79], v[40:43], v[52:55], v[64:79]
	s_waitcnt lgkmcnt(0)
	v_mfma_f32_32x32x16_bf16 v[16:31], v[48:51], v[52:55], v[16:31]
	v_mfma_f32_32x32x16_bf16 v[0:15], v[56:59], v[52:55], v[0:15]
	s_waitcnt vmcnt(4) lgkmcnt(0)
	s_barrier
	ds_read_b128 v[32:35], v205
	ds_read_b128 v[36:39], v205 offset:8192
	s_add_u32 s68, s98, 0x18000
	s_addc_u32 s69, s99, 0
	s_add_i32 s49, 0x8000, s57
	s_mov_b32 m0, s49
	s_nop 0
	global_load_lds_dwordx4 v198, s[68:69]
	s_add_i32 m0, s49, 0x400
	s_nop 0
	global_load_lds_dwordx4 v194, s[68:69]
	s_add_u32 s44, s100, 0x80
	s_addc_u32 s45, s101, 0
	s_add_i32 s49, s58, 0x4000
	s_add_i32 m0, s49, 0xc000
	s_nop 0
	global_load_lds_dwordx4 v196, s[44:45]
	s_add_i32 m0, s49, 0xc400
	s_nop 0
	global_load_lds_dwordx4 v192, s[44:45]
	v_exp_f32_e32 v144, v112
	s_waitcnt lgkmcnt(0)
	v_mfma_f32_32x32x16_bf16 v[48:63], v[32:35], v[160:163], 0
	ds_read_b128 v[132:135], v211
	ds_read_b128 v[136:139], v211 offset:8192
	ds_read_b128 v[140:143], v212
	v_exp_f32_e32 v145, v113
	v_exp_f32_e32 v146, v114
	v_exp_f32_e32 v147, v115
	ds_read_b128 v[112:115], v212 offset:8192
	v_mfma_f32_32x32x16_bf16 v[32:47], v[36:39], v[160:163], 0
	v_exp_f32_e32 v148, v116
	v_exp_f32_e32 v149, v117
	v_exp_f32_e32 v150, v118
	v_exp_f32_e32 v151, v119
	s_waitcnt lgkmcnt(0)
	v_mfma_f32_32x32x16_bf16 v[48:63], v[132:135], v[164:167], v[48:63]
	ds_read_b128 v[116:119], v213
	v_exp_f32_e32 v152, v120
	v_exp_f32_e32 v153, v121
	v_exp_f32_e32 v154, v122
	v_exp_f32_e32 v155, v123
	v_mfma_f32_32x32x16_bf16 v[32:47], v[136:139], v[164:167], v[32:47]
	ds_read_b128 v[120:123], v213 offset:8192
	v_exp_f32_e32 v156, v124
	v_exp_f32_e32 v157, v125
	v_exp_f32_e32 v158, v126
	v_exp_f32_e32 v159, v127
	v_mfma_f32_32x32x16_bf16 v[48:63], v[140:143], v[168:171], v[48:63]
	ds_read_b128 v[124:127], v236 offset:32768
	v_exp_f32_e32 v136, v96
	v_exp_f32_e32 v137, v97
	v_exp_f32_e32 v138, v98
	v_exp_f32_e32 v139, v99
	v_mfma_f32_32x32x16_bf16 v[32:47], v[112:115], v[168:171], v[32:47]
	ds_read_b128 v[96:99], v236 offset:36864
	v_exp_f32_e32 v140, v100
	v_exp_f32_e32 v141, v101
	v_exp_f32_e32 v142, v102
	v_exp_f32_e32 v143, v103
	s_waitcnt lgkmcnt(0)
	v_mfma_f32_32x32x16_bf16 v[48:63], v[116:119], v[172:175], v[48:63]
	ds_read_b128 v[100:103], v236 offset:40960
	v_exp_f32_e32 v178, v104
	v_exp_f32_e32 v179, v105
	v_exp_f32_e32 v180, v106
	v_exp_f32_e32 v181, v107
	v_mfma_f32_32x32x16_bf16 v[32:47], v[120:123], v[172:175], v[32:47]
	ds_read_b128 v[104:107], v236 offset:45056
	v_exp_f32_e32 v182, v108
	v_exp_f32_e32 v183, v109
	v_exp_f32_e32 v184, v110
	v_exp_f32_e32 v185, v111
	v_cvt_pk_bf16_f32 v108, v144, v145
	v_cvt_pk_bf16_f32 v109, v146, v147
	v_cvt_pk_bf16_f32 v110, v148, v149
	v_cvt_pk_bf16_f32 v111, v150, v151
	s_nop 1
	v_mfma_f32_32x32x16_bf16 v[80:95], v[124:127], v[108:111], v[80:95]
	ds_read_b128 v[112:115], v237 offset:32768
	v_cvt_pk_bf16_f32 v116, v152, v153
	v_cvt_pk_bf16_f32 v117, v154, v155
	v_cvt_pk_bf16_f32 v118, v156, v157
	v_cvt_pk_bf16_f32 v119, v158, v159
	v_mfma_f32_32x32x16_bf16 v[64:79], v[96:99], v[108:111], v[64:79]
	ds_read_b128 v[120:123], v237 offset:36864
	v_pk_add_f32 v[126:127], v[150:151], v[146:147]
	v_pk_add_f32 v[124:125], v[148:149], v[144:145]
	s_waitcnt lgkmcnt(0)
	v_mfma_f32_32x32x16_bf16 v[16:31], v[100:103], v[108:111], v[16:31]
	ds_read_b128 v[132:135], v237 offset:40960
	v_add_f32_e64 v98, v154, v126
	v_add_f32_e64 v99, v155, v127
	v_add_f32_e64 v96, v152, v124
	v_add_f32_e64 v97, v153, v125
	v_pk_add_f32 v[98:99], v[158:159], v[98:99]
	v_pk_add_f32 v[96:97], v[156:157], v[96:97]
	v_mfma_f32_32x32x16_bf16 v[0:15], v[104:107], v[108:111], v[0:15]
	ds_read_b128 v[100:103], v237 offset:45056
	v_mfma_f32_32x32x16_bf16 v[80:95], v[112:115], v[116:119], v[80:95]
	ds_read_b128 v[104:107], v238 offset:32768
	v_cvt_pk_bf16_f32 v108, v136, v137
	v_cvt_pk_bf16_f32 v109, v138, v139
	v_cvt_pk_bf16_f32 v110, v140, v141
	v_cvt_pk_bf16_f32 v111, v142, v143
	v_mfma_f32_32x32x16_bf16 v[64:79], v[120:123], v[116:119], v[64:79]
	ds_read_b128 v[112:115], v238 offset:36864
	v_add_f32_e64 v98, v138, v98
	v_add_f32_e64 v99, v139, v99
	v_add_f32_e64 v96, v136, v96
	v_add_f32_e64 v97, v137, v97
	v_pk_add_f32 v[98:99], v[142:143], v[98:99]
	v_pk_add_f32 v[96:97], v[140:141], v[96:97]
	s_waitcnt lgkmcnt(0)
	v_mfma_f32_32x32x16_bf16 v[16:31], v[132:135], v[116:119], v[16:31]
	ds_read_b128 v[120:123], v238 offset:40960
	v_add_f32_e64 v98, v180, v98
	v_add_f32_e64 v99, v181, v99
	v_add_f32_e64 v96, v178, v96
	v_add_f32_e64 v97, v179, v97
	v_pk_add_f32 v[98:99], v[184:185], v[98:99]
	v_pk_add_f32 v[96:97], v[182:183], v[96:97]
	v_mfma_f32_32x32x16_bf16 v[0:15], v[100:103], v[116:119], v[0:15]
	ds_read_b128 v[124:127], v238 offset:45056
	v_mfma_f32_32x32x16_bf16 v[80:95], v[104:107], v[108:111], v[80:95]
	ds_read_b128 v[100:103], v239 offset:32768
	v_cvt_pk_bf16_f32 v116, v178, v179
	v_cvt_pk_bf16_f32 v117, v180, v181
	v_cvt_pk_bf16_f32 v118, v182, v183
	v_cvt_pk_bf16_f32 v119, v184, v185
	v_mfma_f32_32x32x16_bf16 v[64:79], v[112:115], v[108:111], v[64:79]
	ds_read_b128 v[104:107], v239 offset:36864
	s_waitcnt lgkmcnt(0)
	v_mfma_f32_32x32x16_bf16 v[16:31], v[120:123], v[108:111], v[16:31]
	ds_read_b128 v[112:115], v239 offset:40960
	v_mfma_f32_32x32x16_bf16 v[0:15], v[124:127], v[108:111], v[0:15]
	ds_read_b128 v[120:123], v239 offset:45056
	v_mfma_f32_32x32x16_bf16 v[80:95], v[100:103], v[116:119], v[80:95]
	v_mfma_f32_32x32x16_bf16 v[64:79], v[104:107], v[116:119], v[64:79]
	s_waitcnt lgkmcnt(0)
	v_mfma_f32_32x32x16_bf16 v[16:31], v[112:115], v[116:119], v[16:31]
	v_mfma_f32_32x32x16_bf16 v[0:15], v[120:123], v[116:119], v[0:15]
	s_waitcnt vmcnt(4) lgkmcnt(0)
	v_add_f32_e32 v100, v128, v129
	v_add_f32_e32 v101, v130, v131
	v_add_f32_e32 v100, v100, v101
	v_add_f32_e32 v96, v96, v97
	v_add_f32_e32 v97, v98, v99
	s_barrier
	v_add_f32_e32 v100, v177, v100
	v_add_f32_e32 v96, v96, v97
	v_add_f32_e32 v177, v100, v96
	s_add_u32 s98, s98, 0x30000
	s_addc_u32 s99, s99, 0
	s_add_u32 s100, s100, 0x100
	s_addc_u32 s101, s101, 0
	s_add_i32 s21, s21, 12
	s_addk_i32 s15, 0x300
	s_add_i32 s20, s20, 0x30000
	s_cmp_lt_u32 s21, 50
	s_cbranch_scc1 .Lst0_u6_loop
	s_cmp_lt_u32 s21, 60
	s_cbranch_scc1 .Lst0_single
.Lst0_exit:
	ds_read_b128 v[96:99], v205 offset:16384
	ds_read_b128 v[100:103], v205 offset:24576
	s_cmp_lg_u32 s21, 60
	s_cbranch_scc1 .Lst0_orig
	s_cmp_lg_u32 s41, 0
	s_cbranch_scc1 .Lst0_orig
	s_and_b32 s2, s20, 0xffff
	s_cmp_lg_u32 s2, 0xc000
	s_cbranch_scc1 .Lst0_orig
	s_mov_b32 s2, s40
	s_add_i32 s2, s2, s15
	s_sub_i32 s2, s2, 64
	s_mul_hi_i32 s3, s2, 0x600
	s_mulk_i32 s2, 0x600
	s_add_u32 s2, s12, s2
	s_addc_u32 s3, s13, s3
	s_add_i32 s46, s58, 0
	s_mov_b32 m0, s46
	s_nop 0
	global_load_lds_dwordx4 v198, s[2:3]
	s_add_i32 m0, s46, 0x400
	s_nop 0
	global_load_lds_dwordx4 v194, s[2:3]
	s_mov_b32 s46, s40
	s_add_i32 s46, s46, s15
	s_addk_i32 s46, 0xff80
	s_ashr_i32 s47, s46, 31
	s_lshl_b64 s[46:47], s[46:47], 1
	s_add_u32 s46, s39, s46
	s_addc_u32 s47, s67, s47
	s_add_i32 s48, s20, 0xffffc000
	s_add_i32 s48, s58, 0x8000
	s_add_i32 m0, s48, 0xc000
	s_nop 0
	global_load_lds_dwordx4 v196, s[46:47]
	s_add_i32 m0, s48, 0xc400
	s_nop 0
	global_load_lds_dwordx4 v192, s[46:47]
	s_add_i32 s46, s20, 0xffff4000
	s_waitcnt lgkmcnt(0)
	v_mfma_f32_32x32x16_bf16 v[112:127], v[96:99], v[160:163], 0
	ds_read_b128 v[128:131], v211 offset:16384
	ds_read_b128 v[132:135], v211 offset:24576
	ds_read_b128 v[136:139], v212 offset:16384
	v_exp_f32_e32 v140, v48
	v_exp_f32_e32 v141, v49
	v_exp_f32_e32 v142, v50
	v_exp_f32_e32 v143, v51
	ds_read_b128 v[48:51], v212 offset:24576
	v_mfma_f32_32x32x16_bf16 v[96:111], v[100:103], v[160:163], 0
	v_exp_f32_e32 v144, v52
	v_exp_f32_e32 v145, v53
	v_exp_f32_e32 v146, v54
	v_exp_f32_e32 v147, v55
	s_waitcnt lgkmcnt(0)
	v_mfma_f32_32x32x16_bf16 v[112:127], v[128:131], v[164:167], v[112:127]
	ds_read_b128 v[52:55], v213 offset:16384
	v_exp_f32_e32 v148, v56
	v_exp_f32_e32 v149, v57
	v_exp_f32_e32 v150, v58
	v_exp_f32_e32 v151, v59
	v_mfma_f32_32x32x16_bf16 v[96:111], v[132:135], v[164:167], v[96:111]
	ds_read_b128 v[56:59], v213 offset:24576
	v_exp_f32_e32 v128, v60
	v_exp_f32_e32 v129, v61
	v_exp_f32_e32 v130, v62
	v_exp_f32_e32 v131, v63
	v_mfma_f32_32x32x16_bf16 v[112:127], v[136:139], v[168:171], v[112:127]
	ds_read_b128 v[60:63], v206 offset:49152
	v_exp_f32_e32 v132, v32
	v_exp_f32_e32 v133, v33
	v_exp_f32_e32 v134, v34
	v_exp_f32_e32 v135, v35
	v_mfma_f32_32x32x16_bf16 v[96:111], v[48:51], v[168:171], v[96:111]
	ds_read_b128 v[32:35], v206 offset:53248
	v_exp_f32_e32 v136, v36
	v_exp_f32_e32 v137, v37
	v_exp_f32_e32 v138, v38
	v_exp_f32_e32 v139, v39
	s_waitcnt lgkmcnt(0)
	v_mfma_f32_32x32x16_bf16 v[112:127], v[52:55], v[172:175], v[112:127]
	ds_read_b128 v[36:39], v206 offset:57344
	v_exp_f32_e32 v152, v40
	v_exp_f32_e32 v153, v41
	v_exp_f32_e32 v154, v42
	v_exp_f32_e32 v155, v43
	v_mfma_f32_32x32x16_bf16 v[96:111], v[56:59], v[172:175], v[96:111]
	ds_read_b128 v[40:43], v206 offset:61440
	v_exp_f32_e32 v156, v44
	v_exp_f32_e32 v157, v45
	v_exp_f32_e32 v158, v46
	v_exp_f32_e32 v159, v47
	v_cvt_pk_bf16_f32 v44, v140, v141
	v_cvt_pk_bf16_f32 v45, v142, v143
	v_cvt_pk_bf16_f32 v46, v144, v145
	v_cvt_pk_bf16_f32 v47, v146, v147
	s_nop 1
	v_mfma_f32_32x32x16_bf16 v[80:95], v[60:63], v[44:47], v[80:95]
	ds_read_b128 v[48:51], v207 offset:49152
	v_cvt_pk_bf16_f32 v52, v148, v149
	v_cvt_pk_bf16_f32 v53, v150, v151
	v_cvt_pk_bf16_f32 v54, v128, v129
	v_cvt_pk_bf16_f32 v55, v130, v131
	v_mfma_f32_32x32x16_bf16 v[64:79], v[32:35], v[44:47], v[64:79]
	ds_read_b128 v[56:59], v207 offset:53248
	v_pk_add_f32 v[62:63], v[146:147], v[142:143]
	v_pk_add_f32 v[60:61], v[144:145], v[140:141]
	s_waitcnt lgkmcnt(0)
	v_mfma_f32_32x32x16_bf16 v[16:31], v[36:39], v[44:47], v[16:31]
	ds_read_b128 v[32:35], v207 offset:57344
	v_add_f32_e64 v62, v150, v62
	v_add_f32_e64 v63, v151, v63
	v_add_f32_e64 v60, v148, v60
	v_add_f32_e64 v61, v149, v61
	v_pk_add_f32 v[62:63], v[130:131], v[62:63]
	v_pk_add_f32 v[60:61], v[128:129], v[60:61]
	v_mfma_f32_32x32x16_bf16 v[0:15], v[40:43], v[44:47], v[0:15]
	ds_read_b128 v[36:39], v207 offset:61440
	v_mfma_f32_32x32x16_bf16 v[80:95], v[48:51], v[52:55], v[80:95]
	ds_read_b128 v[40:43], v208 offset:49152
	v_cvt_pk_bf16_f32 v44, v132, v133
	v_cvt_pk_bf16_f32 v45, v134, v135
	v_cvt_pk_bf16_f32 v46, v136, v137
	v_cvt_pk_bf16_f32 v47, v138, v139
	v_mfma_f32_32x32x16_bf16 v[64:79], v[56:59], v[52:55], v[64:79]
	ds_read_b128 v[48:51], v208 offset:53248
	v_add_f32_e64 v62, v134, v62
	v_add_f32_e64 v63, v135, v63
	v_add_f32_e64 v60, v132, v60
	v_add_f32_e64 v61, v133, v61
	v_pk_add_f32 v[62:63], v[138:139], v[62:63]
	v_pk_add_f32 v[60:61], v[136:137], v[60:61]
	s_waitcnt lgkmcnt(0)
	v_mfma_f32_32x32x16_bf16 v[16:31], v[32:35], v[52:55], v[16:31]
	ds_read_b128 v[56:59], v208 offset:57344
	v_add_f32_e64 v62, v154, v62
	v_add_f32_e64 v63, v155, v63
	v_add_f32_e64 v60, v152, v60
	v_add_f32_e64 v61, v153, v61
	v_pk_add_f32 v[130:131], v[158:159], v[62:63]
	v_pk_add_f32 v[128:129], v[156:157], v[60:61]
	v_mfma_f32_32x32x16_bf16 v[0:15], v[36:39], v[52:55], v[0:15]
	ds_read_b128 v[32:35], v208 offset:61440
	v_mfma_f32_32x32x16_bf16 v[80:95], v[40:43], v[44:47], v[80:95]
	ds_read_b128 v[36:39], v209 offset:49152
	v_cvt_pk_bf16_f32 v52, v152, v153
	v_cvt_pk_bf16_f32 v53, v154, v155
	v_cvt_pk_bf16_f32 v54, v156, v157
	v_cvt_pk_bf16_f32 v55, v158, v159
	v_mfma_f32_32x32x16_bf16 v[64:79], v[48:51], v[44:47], v[64:79]
	ds_read_b128 v[40:43], v209 offset:53248
	s_waitcnt lgkmcnt(0)
	v_mfma_f32_32x32x16_bf16 v[16:31], v[56:59], v[44:47], v[16:31]
	ds_read_b128 v[48:51], v209 offset:57344
	v_mfma_f32_32x32x16_bf16 v[0:15], v[32:35], v[44:47], v[0:15]
	ds_read_b128 v[56:59], v209 offset:61440
	v_mfma_f32_32x32x16_bf16 v[80:95], v[36:39], v[52:55], v[80:95]
	v_mfma_f32_32x32x16_bf16 v[64:79], v[40:43], v[52:55], v[64:79]
	s_waitcnt lgkmcnt(0)
	v_mfma_f32_32x32x16_bf16 v[16:31], v[48:51], v[52:55], v[16:31]
	v_mfma_f32_32x32x16_bf16 v[0:15], v[56:59], v[52:55], v[0:15]
	s_waitcnt vmcnt(4) lgkmcnt(0)
	s_barrier
	ds_read_b128 v[32:35], v205 offset:32768
	ds_read_b128 v[36:39], v205 offset:40960
	s_mov_b32 s68, s14
	s_add_i32 s68, s68, s15
	s_mul_hi_i32 s69, s68, 0x600
	s_mulk_i32 s68, 0x600
	s_add_u32 s68, s12, s68
	s_addc_u32 s69, s13, s69
	s_add_i32 s49, 0x4000, s57
	s_mov_b32 m0, s49
	s_nop 0
	global_load_lds_dwordx4 v198, s[68:69]
	s_add_i32 m0, s49, 0x400
	s_nop 0
	global_load_lds_dwordx4 v194, s[68:69]
	s_mov_b32 s44, s40
	s_add_i32 s44, s44, s15
	s_sub_i32 s44, s44, 64
	s_ashr_i32 s45, s44, 31
	s_lshl_b64 s[44:45], s[44:45], 1
	s_add_u32 s44, s39, s44
	s_addc_u32 s45, s67, s45
	s_add_i32 s49, s58, 0xc000
	s_add_i32 m0, s49, 0xc000
	s_nop 0
	global_load_lds_dwordx4 v196, s[44:45]
	s_add_i32 m0, s49, 0xc400
	s_nop 0
	global_load_lds_dwordx4 v192, s[44:45]
	v_exp_f32_e32 v144, v112
	s_waitcnt lgkmcnt(0)
	v_mfma_f32_32x32x16_bf16 v[48:63], v[32:35], v[160:163], 0
	ds_read_b128 v[132:135], v211 offset:32768
	ds_read_b128 v[136:139], v211 offset:40960
	ds_read_b128 v[140:143], v212 offset:32768
	v_exp_f32_e32 v145, v113
	v_exp_f32_e32 v146, v114
	v_exp_f32_e32 v147, v115
	ds_read_b128 v[112:115], v212 offset:40960
	v_mfma_f32_32x32x16_bf16 v[32:47], v[36:39], v[160:163], 0
	v_exp_f32_e32 v148, v116
	v_exp_f32_e32 v149, v117
	v_exp_f32_e32 v150, v118
	v_exp_f32_e32 v151, v119
	s_waitcnt lgkmcnt(0)
	v_mfma_f32_32x32x16_bf16 v[48:63], v[132:135], v[164:167], v[48:63]
	ds_read_b128 v[116:119], v213 offset:32768
	v_exp_f32_e32 v152, v120
	v_exp_f32_e32 v153, v121
	v_exp_f32_e32 v154, v122
	v_exp_f32_e32 v155, v123
	v_mfma_f32_32x32x16_bf16 v[32:47], v[136:139], v[164:167], v[32:47]
	ds_read_b128 v[120:123], v213 offset:40960
	v_exp_f32_e32 v156, v124
	v_exp_f32_e32 v157, v125
	v_exp_f32_e32 v158, v126
	v_exp_f32_e32 v159, v127
	v_mfma_f32_32x32x16_bf16 v[48:63], v[140:143], v[168:171], v[48:63]
	ds_read_b128 v[124:127], v236
	v_exp_f32_e32 v136, v96
	v_exp_f32_e32 v137, v97
	v_exp_f32_e32 v138, v98
	v_exp_f32_e32 v139, v99
	v_mfma_f32_32x32x16_bf16 v[32:47], v[112:115], v[168:171], v[32:47]
	ds_read_b128 v[96:99], v236 offset:4096
	v_exp_f32_e32 v140, v100
	v_exp_f32_e32 v141, v101
	v_exp_f32_e32 v142, v102
	v_exp_f32_e32 v143, v103
	s_waitcnt lgkmcnt(0)
	v_mfma_f32_32x32x16_bf16 v[48:63], v[116:119], v[172:175], v[48:63]
	ds_read_b128 v[100:103], v236 offset:8192
	v_exp_f32_e32 v178, v104
	v_exp_f32_e32 v179, v105
	v_exp_f32_e32 v180, v106
	v_exp_f32_e32 v181, v107
	v_mfma_f32_32x32x16_bf16 v[32:47], v[120:123], v[172:175], v[32:47]
	ds_read_b128 v[104:107], v236 offset:12288
	v_exp_f32_e32 v182, v108
	v_exp_f32_e32 v183, v109
	v_exp_f32_e32 v184, v110
	v_exp_f32_e32 v185, v111
	v_cvt_pk_bf16_f32 v108, v144, v145
	v_cvt_pk_bf16_f32 v109, v146, v147
	v_cvt_pk_bf16_f32 v110, v148, v149
	v_cvt_pk_bf16_f32 v111, v150, v151
	s_nop 1
	v_mfma_f32_32x32x16_bf16 v[80:95], v[124:127], v[108:111], v[80:95]
	ds_read_b128 v[112:115], v237
	v_cvt_pk_bf16_f32 v116, v152, v153
	v_cvt_pk_bf16_f32 v117, v154, v155
	v_cvt_pk_bf16_f32 v118, v156, v157
	v_cvt_pk_bf16_f32 v119, v158, v159
	v_mfma_f32_32x32x16_bf16 v[64:79], v[96:99], v[108:111], v[64:79]
	ds_read_b128 v[120:123], v237 offset:4096
	v_pk_add_f32 v[126:127], v[150:151], v[146:147]
	v_pk_add_f32 v[124:125], v[148:149], v[144:145]
	s_waitcnt lgkmcnt(0)
	v_mfma_f32_32x32x16_bf16 v[16:31], v[100:103], v[108:111], v[16:31]
	ds_read_b128 v[132:135], v237 offset:8192
	v_add_f32_e64 v98, v154, v126
	v_add_f32_e64 v99, v155, v127
	v_add_f32_e64 v96, v152, v124
	v_add_f32_e64 v97, v153, v125
	v_pk_add_f32 v[98:99], v[158:159], v[98:99]
	v_pk_add_f32 v[96:97], v[156:157], v[96:97]
	v_mfma_f32_32x32x16_bf16 v[0:15], v[104:107], v[108:111], v[0:15]
	ds_read_b128 v[100:103], v237 offset:12288
	v_mfma_f32_32x32x16_bf16 v[80:95], v[112:115], v[116:119], v[80:95]
	ds_read_b128 v[104:107], v238
	v_cvt_pk_bf16_f32 v108, v136, v137
	v_cvt_pk_bf16_f32 v109, v138, v139
	v_cvt_pk_bf16_f32 v110, v140, v141
	v_cvt_pk_bf16_f32 v111, v142, v143
	v_mfma_f32_32x32x16_bf16 v[64:79], v[120:123], v[116:119], v[64:79]
	ds_read_b128 v[112:115], v238 offset:4096
	v_add_f32_e64 v98, v138, v98
	v_add_f32_e64 v99, v139, v99
	v_add_f32_e64 v96, v136, v96
	v_add_f32_e64 v97, v137, v97
	v_pk_add_f32 v[98:99], v[142:143], v[98:99]
	v_pk_add_f32 v[96:97], v[140:141], v[96:97]
	s_waitcnt lgkmcnt(0)
	v_mfma_f32_32x32x16_bf16 v[16:31], v[132:135], v[116:119], v[16:31]
	ds_read_b128 v[120:123], v238 offset:8192
	v_add_f32_e64 v98, v180, v98
	v_add_f32_e64 v99, v181, v99
	v_add_f32_e64 v96, v178, v96
	v_add_f32_e64 v97, v179, v97
	v_pk_add_f32 v[98:99], v[184:185], v[98:99]
	v_pk_add_f32 v[96:97], v[182:183], v[96:97]
	v_mfma_f32_32x32x16_bf16 v[0:15], v[100:103], v[116:119], v[0:15]
	ds_read_b128 v[124:127], v238 offset:12288
	v_mfma_f32_32x32x16_bf16 v[80:95], v[104:107], v[108:111], v[80:95]
	ds_read_b128 v[100:103], v239
	v_cvt_pk_bf16_f32 v116, v178, v179
	v_cvt_pk_bf16_f32 v117, v180, v181
	v_cvt_pk_bf16_f32 v118, v182, v183
	v_cvt_pk_bf16_f32 v119, v184, v185
	v_mfma_f32_32x32x16_bf16 v[64:79], v[112:115], v[108:111], v[64:79]
	ds_read_b128 v[104:107], v239 offset:4096
	s_waitcnt lgkmcnt(0)
	v_mfma_f32_32x32x16_bf16 v[16:31], v[120:123], v[108:111], v[16:31]
	ds_read_b128 v[112:115], v239 offset:8192
	v_mfma_f32_32x32x16_bf16 v[0:15], v[124:127], v[108:111], v[0:15]
	ds_read_b128 v[120:123], v239 offset:12288
	v_mfma_f32_32x32x16_bf16 v[80:95], v[100:103], v[116:119], v[80:95]
	v_mfma_f32_32x32x16_bf16 v[64:79], v[104:107], v[116:119], v[64:79]
	s_waitcnt lgkmcnt(0)
	v_mfma_f32_32x32x16_bf16 v[16:31], v[112:115], v[116:119], v[16:31]
	v_mfma_f32_32x32x16_bf16 v[0:15], v[120:123], v[116:119], v[0:15]
	s_waitcnt vmcnt(4) lgkmcnt(0)
	v_add_f32_e32 v100, v128, v129
	v_add_f32_e32 v101, v130, v131
	v_add_f32_e32 v100, v100, v101
	v_add_f32_e32 v96, v96, v97
	v_add_f32_e32 v97, v98, v99
	s_barrier
	v_add_f32_e32 v100, v177, v100
	v_add_f32_e32 v96, v96, v97
	v_add_f32_e32 v177, v100, v96
	ds_read_b128 v[96:99], v205
	ds_read_b128 v[100:103], v205 offset:8192
	s_add_i32 s21, s21, 2
	s_addk_i32 s15, 0x80
	s_add_i32 s20, s20, 0x8000
	s_mov_b32 s2, s14
	s_add_i32 s2, s2, s15
	s_sub_i32 s2, s2, 64
	s_mul_hi_i32 s3, s2, 0x600
	s_mulk_i32 s2, 0x600
	s_add_u32 s2, s12, s2
	s_addc_u32 s3, s13, s3
	s_add_i32 s46, s58, 0x8000
	s_mov_b32 m0, s46
	s_nop 0
	global_load_lds_dwordx4 v198, s[2:3]
	s_add_i32 m0, s46, 0x400
	s_nop 0
	global_load_lds_dwordx4 v194, s[2:3]
	s_mov_b32 s46, s14
	s_add_i32 s46, s46, s15
	s_addk_i32 s46, 0xff80
	s_ashr_i32 s47, s46, 31
	s_lshl_b64 s[46:47], s[46:47], 1
	s_add_u32 s46, s39, s46
	s_addc_u32 s47, s67, s47
	s_add_i32 s48, s20, 0xffffc000
	s_add_i32 s48, s58, 0
	s_add_i32 m0, s48, 0xc000
	s_nop 0
	global_load_lds_dwordx4 v196, s[46:47]
	s_add_i32 m0, s48, 0xc400
	s_nop 0
	global_load_lds_dwordx4 v192, s[46:47]
	s_add_i32 s46, s20, 0xffff4000
	s_waitcnt lgkmcnt(0)
	v_mfma_f32_32x32x16_bf16 v[112:127], v[96:99], v[160:163], 0
	ds_read_b128 v[128:131], v211
	ds_read_b128 v[132:135], v211 offset:8192
	ds_read_b128 v[136:139], v212
	v_exp_f32_e32 v140, v48
	v_exp_f32_e32 v141, v49
	v_exp_f32_e32 v142, v50
	v_exp_f32_e32 v143, v51
	ds_read_b128 v[48:51], v212 offset:8192
	v_mfma_f32_32x32x16_bf16 v[96:111], v[100:103], v[160:163], 0
	v_exp_f32_e32 v144, v52
	v_exp_f32_e32 v145, v53
	v_exp_f32_e32 v146, v54
	v_exp_f32_e32 v147, v55
	s_waitcnt lgkmcnt(0)
	v_mfma_f32_32x32x16_bf16 v[112:127], v[128:131], v[164:167], v[112:127]
	ds_read_b128 v[52:55], v213
	v_exp_f32_e32 v148, v56
	v_exp_f32_e32 v149, v57
	v_exp_f32_e32 v150, v58
	v_exp_f32_e32 v151, v59
	v_mfma_f32_32x32x16_bf16 v[96:111], v[132:135], v[164:167], v[96:111]
	ds_read_b128 v[56:59], v213 offset:8192
	v_exp_f32_e32 v128, v60
	v_exp_f32_e32 v129, v61
	v_exp_f32_e32 v130, v62
	v_exp_f32_e32 v131, v63
	v_mfma_f32_32x32x16_bf16 v[112:127], v[136:139], v[168:171], v[112:127]
	ds_read_b128 v[60:63], v236 offset:16384
	v_exp_f32_e32 v132, v32
	v_exp_f32_e32 v133, v33
	v_exp_f32_e32 v134, v34
	v_exp_f32_e32 v135, v35
	v_mfma_f32_32x32x16_bf16 v[96:111], v[48:51], v[168:171], v[96:111]
	ds_read_b128 v[32:35], v236 offset:20480
	v_exp_f32_e32 v136, v36
	v_exp_f32_e32 v137, v37
	v_exp_f32_e32 v138, v38
	v_exp_f32_e32 v139, v39
	s_waitcnt lgkmcnt(0)
	v_mfma_f32_32x32x16_bf16 v[112:127], v[52:55], v[172:175], v[112:127]
	ds_read_b128 v[36:39], v236 offset:24576
	v_exp_f32_e32 v152, v40
	v_exp_f32_e32 v153, v41
	v_exp_f32_e32 v154, v42
	v_exp_f32_e32 v155, v43
	v_mfma_f32_32x32x16_bf16 v[96:111], v[56:59], v[172:175], v[96:111]
	ds_read_b128 v[40:43], v236 offset:28672
	v_exp_f32_e32 v156, v44
	v_exp_f32_e32 v157, v45
	v_exp_f32_e32 v158, v46
	v_exp_f32_e32 v159, v47
	v_cvt_pk_bf16_f32 v44, v140, v141
	v_cvt_pk_bf16_f32 v45, v142, v143
	v_cvt_pk_bf16_f32 v46, v144, v145
	v_cvt_pk_bf16_f32 v47, v146, v147
	s_nop 1
	v_mfma_f32_32x32x16_bf16 v[80:95], v[60:63], v[44:47], v[80:95]
	ds_read_b128 v[48:51], v237 offset:16384
	v_cvt_pk_bf16_f32 v52, v148, v149
	v_cvt_pk_bf16_f32 v53, v150, v151
	v_cvt_pk_bf16_f32 v54, v128, v129
	v_cvt_pk_bf16_f32 v55, v130, v131
	v_mfma_f32_32x32x16_bf16 v[64:79], v[32:35], v[44:47], v[64:79]
	ds_read_b128 v[56:59], v237 offset:20480
	v_pk_add_f32 v[62:63], v[146:147], v[142:143]
	v_pk_add_f32 v[60:61], v[144:145], v[140:141]
	s_waitcnt lgkmcnt(0)
	v_mfma_f32_32x32x16_bf16 v[16:31], v[36:39], v[44:47], v[16:31]
	ds_read_b128 v[32:35], v237 offset:24576
	v_add_f32_e64 v62, v150, v62
	v_add_f32_e64 v63, v151, v63
	v_add_f32_e64 v60, v148, v60
	v_add_f32_e64 v61, v149, v61
	v_pk_add_f32 v[62:63], v[130:131], v[62:63]
	v_pk_add_f32 v[60:61], v[128:129], v[60:61]
	v_mfma_f32_32x32x16_bf16 v[0:15], v[40:43], v[44:47], v[0:15]
	ds_read_b128 v[36:39], v237 offset:28672
	v_mfma_f32_32x32x16_bf16 v[80:95], v[48:51], v[52:55], v[80:95]
	ds_read_b128 v[40:43], v238 offset:16384
	v_cvt_pk_bf16_f32 v44, v132, v133
	v_cvt_pk_bf16_f32 v45, v134, v135
	v_cvt_pk_bf16_f32 v46, v136, v137
	v_cvt_pk_bf16_f32 v47, v138, v139
	v_mfma_f32_32x32x16_bf16 v[64:79], v[56:59], v[52:55], v[64:79]
	ds_read_b128 v[48:51], v238 offset:20480
	v_add_f32_e64 v62, v134, v62
	v_add_f32_e64 v63, v135, v63
	v_add_f32_e64 v60, v132, v60
	v_add_f32_e64 v61, v133, v61
	v_pk_add_f32 v[62:63], v[138:139], v[62:63]
	v_pk_add_f32 v[60:61], v[136:137], v[60:61]
	s_waitcnt lgkmcnt(0)
	v_mfma_f32_32x32x16_bf16 v[16:31], v[32:35], v[52:55], v[16:31]
	ds_read_b128 v[56:59], v238 offset:24576
	v_add_f32_e64 v62, v154, v62
	v_add_f32_e64 v63, v155, v63
	v_add_f32_e64 v60, v152, v60
	v_add_f32_e64 v61, v153, v61
	v_pk_add_f32 v[130:131], v[158:159], v[62:63]
	v_pk_add_f32 v[128:129], v[156:157], v[60:61]
	v_mfma_f32_32x32x16_bf16 v[0:15], v[36:39], v[52:55], v[0:15]
	ds_read_b128 v[32:35], v238 offset:28672
	v_mfma_f32_32x32x16_bf16 v[80:95], v[40:43], v[44:47], v[80:95]
	ds_read_b128 v[36:39], v239 offset:16384
	v_cvt_pk_bf16_f32 v52, v152, v153
	v_cvt_pk_bf16_f32 v53, v154, v155
	v_cvt_pk_bf16_f32 v54, v156, v157
	v_cvt_pk_bf16_f32 v55, v158, v159
	v_mfma_f32_32x32x16_bf16 v[64:79], v[48:51], v[44:47], v[64:79]
	ds_read_b128 v[40:43], v239 offset:20480
	s_waitcnt lgkmcnt(0)
	v_mfma_f32_32x32x16_bf16 v[16:31], v[56:59], v[44:47], v[16:31]
	ds_read_b128 v[48:51], v239 offset:24576
	v_mfma_f32_32x32x16_bf16 v[0:15], v[32:35], v[44:47], v[0:15]
	ds_read_b128 v[56:59], v239 offset:28672
	v_mfma_f32_32x32x16_bf16 v[80:95], v[36:39], v[52:55], v[80:95]
	v_mfma_f32_32x32x16_bf16 v[64:79], v[40:43], v[52:55], v[64:79]
	s_waitcnt lgkmcnt(0)
	v_mfma_f32_32x32x16_bf16 v[16:31], v[48:51], v[52:55], v[16:31]
	v_mfma_f32_32x32x16_bf16 v[0:15], v[56:59], v[52:55], v[0:15]
	s_waitcnt vmcnt(4) lgkmcnt(0)
	s_barrier
	ds_read_b128 v[32:35], v205 offset:16384
	ds_read_b128 v[36:39], v205 offset:24576
	s_mov_b32 s68, s14
	s_add_i32 s68, s68, s15
	s_mul_hi_i32 s69, s68, 0x600
	s_mulk_i32 s68, 0x600
	s_add_u32 s68, s12, s68
	s_addc_u32 s69, s13, s69
	s_add_i32 s49, 0, s57
	s_mov_b32 m0, s49
	s_nop 0
	global_load_lds_dwordx4 v198, s[68:69]
	s_add_i32 m0, s49, 0x400
	s_nop 0
	global_load_lds_dwordx4 v194, s[68:69]
	s_mov_b32 s44, s14
	s_add_i32 s44, s44, s15
	s_sub_i32 s44, s44, 64
	s_ashr_i32 s45, s44, 31
	s_lshl_b64 s[44:45], s[44:45], 1
	s_add_u32 s44, s39, s44
	s_addc_u32 s45, s67, s45
	s_add_i32 s49, s58, 0x4000
	s_add_i32 m0, s49, 0xc000
	s_nop 0
	global_load_lds_dwordx4 v196, s[44:45]
	s_add_i32 m0, s49, 0xc400
	s_nop 0
	global_load_lds_dwordx4 v192, s[44:45]
	v_exp_f32_e32 v144, v112
	s_waitcnt lgkmcnt(0)
	v_mfma_f32_32x32x16_bf16 v[48:63], v[32:35], v[160:163], 0
	ds_read_b128 v[132:135], v211 offset:16384
	ds_read_b128 v[136:139], v211 offset:24576
	ds_read_b128 v[140:143], v212 offset:16384
	v_exp_f32_e32 v145, v113
	v_exp_f32_e32 v146, v114
	v_exp_f32_e32 v147, v115
	ds_read_b128 v[112:115], v212 offset:24576
	v_mfma_f32_32x32x16_bf16 v[32:47], v[36:39], v[160:163], 0
	v_exp_f32_e32 v148, v116
	v_exp_f32_e32 v149, v117
	v_exp_f32_e32 v150, v118
	v_exp_f32_e32 v151, v119
	s_waitcnt lgkmcnt(0)
	v_mfma_f32_32x32x16_bf16 v[48:63], v[132:135], v[164:167], v[48:63]
	ds_read_b128 v[116:119], v213 offset:16384
	v_exp_f32_e32 v152, v120
	v_exp_f32_e32 v153, v121
	v_exp_f32_e32 v154, v122
	v_exp_f32_e32 v155, v123
	v_mfma_f32_32x32x16_bf16 v[32:47], v[136:139], v[164:167], v[32:47]
	ds_read_b128 v[120:123], v213 offset:24576
	v_exp_f32_e32 v156, v124
	v_exp_f32_e32 v157, v125
	v_exp_f32_e32 v158, v126
	v_exp_f32_e32 v159, v127
	v_mfma_f32_32x32x16_bf16 v[48:63], v[140:143], v[168:171], v[48:63]
	ds_read_b128 v[124:127], v236 offset:32768
	v_exp_f32_e32 v136, v96
	v_exp_f32_e32 v137, v97
	v_exp_f32_e32 v138, v98
	v_exp_f32_e32 v139, v99
	v_mfma_f32_32x32x16_bf16 v[32:47], v[112:115], v[168:171], v[32:47]
	ds_read_b128 v[96:99], v236 offset:36864
	v_exp_f32_e32 v140, v100
	v_exp_f32_e32 v141, v101
	v_exp_f32_e32 v142, v102
	v_exp_f32_e32 v143, v103
	s_waitcnt lgkmcnt(0)
	v_mfma_f32_32x32x16_bf16 v[48:63], v[116:119], v[172:175], v[48:63]
	ds_read_b128 v[100:103], v236 offset:40960
	v_exp_f32_e32 v178, v104
	v_exp_f32_e32 v179, v105
	v_exp_f32_e32 v180, v106
	v_exp_f32_e32 v181, v107
	v_mfma_f32_32x32x16_bf16 v[32:47], v[120:123], v[172:175], v[32:47]
	ds_read_b128 v[104:107], v236 offset:45056
	v_exp_f32_e32 v182, v108
	v_exp_f32_e32 v183, v109
	v_exp_f32_e32 v184, v110
	v_exp_f32_e32 v185, v111
	v_cvt_pk_bf16_f32 v108, v144, v145
	v_cvt_pk_bf16_f32 v109, v146, v147
	v_cvt_pk_bf16_f32 v110, v148, v149
	v_cvt_pk_bf16_f32 v111, v150, v151
	s_nop 1
	v_mfma_f32_32x32x16_bf16 v[80:95], v[124:127], v[108:111], v[80:95]
	ds_read_b128 v[112:115], v237 offset:32768
	v_cvt_pk_bf16_f32 v116, v152, v153
	v_cvt_pk_bf16_f32 v117, v154, v155
	v_cvt_pk_bf16_f32 v118, v156, v157
	v_cvt_pk_bf16_f32 v119, v158, v159
	v_mfma_f32_32x32x16_bf16 v[64:79], v[96:99], v[108:111], v[64:79]
	ds_read_b128 v[120:123], v237 offset:36864
	v_pk_add_f32 v[126:127], v[150:151], v[146:147]
	v_pk_add_f32 v[124:125], v[148:149], v[144:145]
	s_waitcnt lgkmcnt(0)
	v_mfma_f32_32x32x16_bf16 v[16:31], v[100:103], v[108:111], v[16:31]
	ds_read_b128 v[132:135], v237 offset:40960
	v_add_f32_e64 v98, v154, v126
	v_add_f32_e64 v99, v155, v127
	v_add_f32_e64 v96, v152, v124
	v_add_f32_e64 v97, v153, v125
	v_pk_add_f32 v[98:99], v[158:159], v[98:99]
	v_pk_add_f32 v[96:97], v[156:157], v[96:97]
	v_mfma_f32_32x32x16_bf16 v[0:15], v[104:107], v[108:111], v[0:15]
	ds_read_b128 v[100:103], v237 offset:45056
	v_mfma_f32_32x32x16_bf16 v[80:95], v[112:115], v[116:119], v[80:95]
	ds_read_b128 v[104:107], v238 offset:32768
	v_cvt_pk_bf16_f32 v108, v136, v137
	v_cvt_pk_bf16_f32 v109, v138, v139
	v_cvt_pk_bf16_f32 v110, v140, v141
	v_cvt_pk_bf16_f32 v111, v142, v143
	v_mfma_f32_32x32x16_bf16 v[64:79], v[120:123], v[116:119], v[64:79]
	ds_read_b128 v[112:115], v238 offset:36864
	v_add_f32_e64 v98, v138, v98
	v_add_f32_e64 v99, v139, v99
	v_add_f32_e64 v96, v136, v96
	v_add_f32_e64 v97, v137, v97
	v_pk_add_f32 v[98:99], v[142:143], v[98:99]
	v_pk_add_f32 v[96:97], v[140:141], v[96:97]
	s_waitcnt lgkmcnt(0)
	v_mfma_f32_32x32x16_bf16 v[16:31], v[132:135], v[116:119], v[16:31]
	ds_read_b128 v[120:123], v238 offset:40960
	v_add_f32_e64 v98, v180, v98
	v_add_f32_e64 v99, v181, v99
	v_add_f32_e64 v96, v178, v96
	v_add_f32_e64 v97, v179, v97
	v_pk_add_f32 v[98:99], v[184:185], v[98:99]
	v_pk_add_f32 v[96:97], v[182:183], v[96:97]
	v_mfma_f32_32x32x16_bf16 v[0:15], v[100:103], v[116:119], v[0:15]
	ds_read_b128 v[124:127], v238 offset:45056
	v_mfma_f32_32x32x16_bf16 v[80:95], v[104:107], v[108:111], v[80:95]
	ds_read_b128 v[100:103], v239 offset:32768
	v_cvt_pk_bf16_f32 v116, v178, v179
	v_cvt_pk_bf16_f32 v117, v180, v181
	v_cvt_pk_bf16_f32 v118, v182, v183
	v_cvt_pk_bf16_f32 v119, v184, v185
	v_mfma_f32_32x32x16_bf16 v[64:79], v[112:115], v[108:111], v[64:79]
	ds_read_b128 v[104:107], v239 offset:36864
	s_waitcnt lgkmcnt(0)
	v_mfma_f32_32x32x16_bf16 v[16:31], v[120:123], v[108:111], v[16:31]
	ds_read_b128 v[112:115], v239 offset:40960
	v_mfma_f32_32x32x16_bf16 v[0:15], v[124:127], v[108:111], v[0:15]
	ds_read_b128 v[120:123], v239 offset:45056
	v_mfma_f32_32x32x16_bf16 v[80:95], v[100:103], v[116:119], v[80:95]
	v_mfma_f32_32x32x16_bf16 v[64:79], v[104:107], v[116:119], v[64:79]
	s_waitcnt lgkmcnt(0)
	v_mfma_f32_32x32x16_bf16 v[16:31], v[112:115], v[116:119], v[16:31]
	v_mfma_f32_32x32x16_bf16 v[0:15], v[120:123], v[116:119], v[0:15]
	s_waitcnt vmcnt(4) lgkmcnt(0)
	v_add_f32_e32 v100, v128, v129
	v_add_f32_e32 v101, v130, v131
	v_add_f32_e32 v100, v100, v101
	v_add_f32_e32 v96, v96, v97
	v_add_f32_e32 v97, v98, v99
	s_barrier
	v_add_f32_e32 v100, v177, v100
	v_add_f32_e32 v96, v96, v97
	v_add_f32_e32 v177, v100, v96
	ds_read_b128 v[96:99], v205 offset:32768
	ds_read_b128 v[100:103], v205 offset:40960
	s_add_i32 s21, s21, 2
	s_addk_i32 s15, 0x80
	s_add_i32 s20, s20, 0x8000
	s_mov_b32 s2, s14
	s_add_i32 s2, s2, s15
	s_sub_i32 s2, s2, 64
	s_mul_hi_i32 s3, s2, 0x600
	s_mulk_i32 s2, 0x600
	s_add_u32 s2, s12, s2
	s_addc_u32 s3, s13, s3
	s_add_i32 s46, s58, 0x4000
	s_mov_b32 m0, s46
	s_nop 0
	global_load_lds_dwordx4 v198, s[2:3]
	s_add_i32 m0, s46, 0x400
	s_nop 0
	global_load_lds_dwordx4 v194, s[2:3]
	s_mov_b32 s46, s14
	s_add_i32 s46, s46, s15
	s_addk_i32 s46, 0xff80
	s_ashr_i32 s47, s46, 31
	s_lshl_b64 s[46:47], s[46:47], 1
	s_add_u32 s46, s39, s46
	s_addc_u32 s47, s67, s47
	s_add_i32 s48, s20, 0xffffc000
	s_add_i32 s48, s58, 0x8000
	s_add_i32 m0, s48, 0xc000
	s_nop 0
	global_load_lds_dwordx4 v196, s[46:47]
	s_add_i32 m0, s48, 0xc400
	s_nop 0
	global_load_lds_dwordx4 v192, s[46:47]
	s_add_i32 s46, s20, 0xffff4000
	s_waitcnt lgkmcnt(0)
	v_mfma_f32_32x32x16_bf16 v[112:127], v[96:99], v[160:163], 0
	ds_read_b128 v[128:131], v211 offset:32768
	ds_read_b128 v[132:135], v211 offset:40960
	ds_read_b128 v[136:139], v212 offset:32768
	v_exp_f32_e32 v140, v48
	v_exp_f32_e32 v141, v49
	v_exp_f32_e32 v142, v50
	v_exp_f32_e32 v143, v51
	ds_read_b128 v[48:51], v212 offset:40960
	v_mfma_f32_32x32x16_bf16 v[96:111], v[100:103], v[160:163], 0
	v_exp_f32_e32 v144, v52
	v_exp_f32_e32 v145, v53
	v_exp_f32_e32 v146, v54
	v_exp_f32_e32 v147, v55
	s_waitcnt lgkmcnt(0)
	v_mfma_f32_32x32x16_bf16 v[112:127], v[128:131], v[164:167], v[112:127]
	ds_read_b128 v[52:55], v213 offset:32768
	v_exp_f32_e32 v148, v56
	v_exp_f32_e32 v149, v57
	v_exp_f32_e32 v150, v58
	v_exp_f32_e32 v151, v59
	v_mfma_f32_32x32x16_bf16 v[96:111], v[132:135], v[164:167], v[96:111]
	ds_read_b128 v[56:59], v213 offset:40960
	v_exp_f32_e32 v128, v60
	v_exp_f32_e32 v129, v61
	v_exp_f32_e32 v130, v62
	v_exp_f32_e32 v131, v63
	v_mfma_f32_32x32x16_bf16 v[112:127], v[136:139], v[168:171], v[112:127]
	ds_read_b128 v[60:63], v206 offset:49152
	v_exp_f32_e32 v132, v32
	v_exp_f32_e32 v133, v33
	v_exp_f32_e32 v134, v34
	v_exp_f32_e32 v135, v35
	v_mfma_f32_32x32x16_bf16 v[96:111], v[48:51], v[168:171], v[96:111]
	ds_read_b128 v[32:35], v206 offset:53248
	v_exp_f32_e32 v136, v36
	v_exp_f32_e32 v137, v37
	v_exp_f32_e32 v138, v38
	v_exp_f32_e32 v139, v39
	s_waitcnt lgkmcnt(0)
	v_mfma_f32_32x32x16_bf16 v[112:127], v[52:55], v[172:175], v[112:127]
	ds_read_b128 v[36:39], v206 offset:57344
	v_exp_f32_e32 v152, v40
	v_exp_f32_e32 v153, v41
	v_exp_f32_e32 v154, v42
	v_exp_f32_e32 v155, v43
	v_mfma_f32_32x32x16_bf16 v[96:111], v[56:59], v[172:175], v[96:111]
	ds_read_b128 v[40:43], v206 offset:61440
	v_exp_f32_e32 v156, v44
	v_exp_f32_e32 v157, v45
	v_exp_f32_e32 v158, v46
	v_exp_f32_e32 v159, v47
	v_cvt_pk_bf16_f32 v44, v140, v141
	v_cvt_pk_bf16_f32 v45, v142, v143
	v_cvt_pk_bf16_f32 v46, v144, v145
	v_cvt_pk_bf16_f32 v47, v146, v147
	s_nop 1
	v_mfma_f32_32x32x16_bf16 v[80:95], v[60:63], v[44:47], v[80:95]
	ds_read_b128 v[48:51], v207 offset:49152
	v_cvt_pk_bf16_f32 v52, v148, v149
	v_cvt_pk_bf16_f32 v53, v150, v151
	v_cvt_pk_bf16_f32 v54, v128, v129
	v_cvt_pk_bf16_f32 v55, v130, v131
	v_mfma_f32_32x32x16_bf16 v[64:79], v[32:35], v[44:47], v[64:79]
	ds_read_b128 v[56:59], v207 offset:53248
	v_pk_add_f32 v[62:63], v[146:147], v[142:143]
	v_pk_add_f32 v[60:61], v[144:145], v[140:141]
	s_waitcnt lgkmcnt(0)
	v_mfma_f32_32x32x16_bf16 v[16:31], v[36:39], v[44:47], v[16:31]
	ds_read_b128 v[32:35], v207 offset:57344
	v_add_f32_e64 v62, v150, v62
	v_add_f32_e64 v63, v151, v63
	v_add_f32_e64 v60, v148, v60
	v_add_f32_e64 v61, v149, v61
	v_pk_add_f32 v[62:63], v[130:131], v[62:63]
	v_pk_add_f32 v[60:61], v[128:129], v[60:61]
	v_mfma_f32_32x32x16_bf16 v[0:15], v[40:43], v[44:47], v[0:15]
	ds_read_b128 v[36:39], v207 offset:61440
	v_mfma_f32_32x32x16_bf16 v[80:95], v[48:51], v[52:55], v[80:95]
	ds_read_b128 v[40:43], v208 offset:49152
	v_cvt_pk_bf16_f32 v44, v132, v133
	v_cvt_pk_bf16_f32 v45, v134, v135
	v_cvt_pk_bf16_f32 v46, v136, v137
	v_cvt_pk_bf16_f32 v47, v138, v139
	v_mfma_f32_32x32x16_bf16 v[64:79], v[56:59], v[52:55], v[64:79]
	ds_read_b128 v[48:51], v208 offset:53248
	v_add_f32_e64 v62, v134, v62
	v_add_f32_e64 v63, v135, v63
	v_add_f32_e64 v60, v132, v60
	v_add_f32_e64 v61, v133, v61
	v_pk_add_f32 v[62:63], v[138:139], v[62:63]
	v_pk_add_f32 v[60:61], v[136:137], v[60:61]
	s_waitcnt lgkmcnt(0)
	v_mfma_f32_32x32x16_bf16 v[16:31], v[32:35], v[52:55], v[16:31]
	ds_read_b128 v[56:59], v208 offset:57344
	v_add_f32_e64 v62, v154, v62
	v_add_f32_e64 v63, v155, v63
	v_add_f32_e64 v60, v152, v60
	v_add_f32_e64 v61, v153, v61
	v_pk_add_f32 v[130:131], v[158:159], v[62:63]
	v_pk_add_f32 v[128:129], v[156:157], v[60:61]
	v_mfma_f32_32x32x16_bf16 v[0:15], v[36:39], v[52:55], v[0:15]
	ds_read_b128 v[32:35], v208 offset:61440
	v_mfma_f32_32x32x16_bf16 v[80:95], v[40:43], v[44:47], v[80:95]
	ds_read_b128 v[36:39], v209 offset:49152
	v_cvt_pk_bf16_f32 v52, v152, v153
	v_cvt_pk_bf16_f32 v53, v154, v155
	v_cvt_pk_bf16_f32 v54, v156, v157
	v_cvt_pk_bf16_f32 v55, v158, v159
	v_mfma_f32_32x32x16_bf16 v[64:79], v[48:51], v[44:47], v[64:79]
	ds_read_b128 v[40:43], v209 offset:53248
	s_waitcnt lgkmcnt(0)
	v_mfma_f32_32x32x16_bf16 v[16:31], v[56:59], v[44:47], v[16:31]
	ds_read_b128 v[48:51], v209 offset:57344
	v_mfma_f32_32x32x16_bf16 v[0:15], v[32:35], v[44:47], v[0:15]
	ds_read_b128 v[56:59], v209 offset:61440
	v_mfma_f32_32x32x16_bf16 v[80:95], v[36:39], v[52:55], v[80:95]
	v_mfma_f32_32x32x16_bf16 v[64:79], v[40:43], v[52:55], v[64:79]
	s_waitcnt lgkmcnt(0)
	v_mfma_f32_32x32x16_bf16 v[16:31], v[48:51], v[52:55], v[16:31]
	v_mfma_f32_32x32x16_bf16 v[0:15], v[56:59], v[52:55], v[0:15]
	s_waitcnt vmcnt(4) lgkmcnt(0)
	s_barrier
	ds_read_b128 v[32:35], v205
	ds_read_b128 v[36:39], v205 offset:8192
	s_mov_b32 s44, s14
	s_add_i32 s44, s44, s15
	s_sub_i32 s44, s44, 64
	s_ashr_i32 s45, s44, 31
	s_lshl_b64 s[44:45], s[44:45], 1
	s_add_u32 s44, s39, s44
	s_addc_u32 s45, s67, s45
	s_add_i32 s49, s58, 0xc000
	s_add_i32 m0, s49, 0xc000
	s_nop 0
	global_load_lds_dwordx4 v196, s[44:45]
	s_add_i32 m0, s49, 0xc400
	s_nop 0
	global_load_lds_dwordx4 v192, s[44:45]
	v_exp_f32_e32 v144, v112
	s_waitcnt lgkmcnt(0)
	v_mfma_f32_32x32x16_bf16 v[48:63], v[32:35], v[160:163], 0
	ds_read_b128 v[132:135], v211
	ds_read_b128 v[136:139], v211 offset:8192
	ds_read_b128 v[140:143], v212
	v_exp_f32_e32 v145, v113
	v_exp_f32_e32 v146, v114
	v_exp_f32_e32 v147, v115
	ds_read_b128 v[112:115], v212 offset:8192
	v_mfma_f32_32x32x16_bf16 v[32:47], v[36:39], v[160:163], 0
	v_exp_f32_e32 v148, v116
	v_exp_f32_e32 v149, v117
	v_exp_f32_e32 v150, v118
	v_exp_f32_e32 v151, v119
	s_waitcnt lgkmcnt(0)
	v_mfma_f32_32x32x16_bf16 v[48:63], v[132:135], v[164:167], v[48:63]
	ds_read_b128 v[116:119], v213
	v_exp_f32_e32 v152, v120
	v_exp_f32_e32 v153, v121
	v_exp_f32_e32 v154, v122
	v_exp_f32_e32 v155, v123
	v_mfma_f32_32x32x16_bf16 v[32:47], v[136:139], v[164:167], v[32:47]
	ds_read_b128 v[120:123], v213 offset:8192
	v_exp_f32_e32 v156, v124
	v_exp_f32_e32 v157, v125
	v_exp_f32_e32 v158, v126
	v_exp_f32_e32 v159, v127
	v_mfma_f32_32x32x16_bf16 v[48:63], v[140:143], v[168:171], v[48:63]
	ds_read_b128 v[124:127], v236
	v_exp_f32_e32 v136, v96
	v_exp_f32_e32 v137, v97
	v_exp_f32_e32 v138, v98
	v_exp_f32_e32 v139, v99
	v_mfma_f32_32x32x16_bf16 v[32:47], v[112:115], v[168:171], v[32:47]
	ds_read_b128 v[96:99], v236 offset:4096
	v_exp_f32_e32 v140, v100
	v_exp_f32_e32 v141, v101
	v_exp_f32_e32 v142, v102
	v_exp_f32_e32 v143, v103
	s_waitcnt lgkmcnt(0)
	v_mfma_f32_32x32x16_bf16 v[48:63], v[116:119], v[172:175], v[48:63]
	ds_read_b128 v[100:103], v236 offset:8192
	v_exp_f32_e32 v178, v104
	v_exp_f32_e32 v179, v105
	v_exp_f32_e32 v180, v106
	v_exp_f32_e32 v181, v107
	v_mfma_f32_32x32x16_bf16 v[32:47], v[120:123], v[172:175], v[32:47]
	ds_read_b128 v[104:107], v236 offset:12288
	v_exp_f32_e32 v182, v108
	v_exp_f32_e32 v183, v109
	v_exp_f32_e32 v184, v110
	v_exp_f32_e32 v185, v111
	v_cvt_pk_bf16_f32 v108, v144, v145
	v_cvt_pk_bf16_f32 v109, v146, v147
	v_cvt_pk_bf16_f32 v110, v148, v149
	v_cvt_pk_bf16_f32 v111, v150, v151
	s_nop 1
	v_mfma_f32_32x32x16_bf16 v[80:95], v[124:127], v[108:111], v[80:95]
	ds_read_b128 v[112:115], v237
	v_cvt_pk_bf16_f32 v116, v152, v153
	v_cvt_pk_bf16_f32 v117, v154, v155
	v_cvt_pk_bf16_f32 v118, v156, v157
	v_cvt_pk_bf16_f32 v119, v158, v159
	v_mfma_f32_32x32x16_bf16 v[64:79], v[96:99], v[108:111], v[64:79]
	ds_read_b128 v[120:123], v237 offset:4096
	v_pk_add_f32 v[126:127], v[150:151], v[146:147]
	v_pk_add_f32 v[124:125], v[148:149], v[144:145]
	s_waitcnt lgkmcnt(0)
	v_mfma_f32_32x32x16_bf16 v[16:31], v[100:103], v[108:111], v[16:31]
	ds_read_b128 v[132:135], v237 offset:8192
	v_add_f32_e64 v98, v154, v126
	v_add_f32_e64 v99, v155, v127
	v_add_f32_e64 v96, v152, v124
	v_add_f32_e64 v97, v153, v125
	v_pk_add_f32 v[98:99], v[158:159], v[98:99]
	v_pk_add_f32 v[96:97], v[156:157], v[96:97]
	v_mfma_f32_32x32x16_bf16 v[0:15], v[104:107], v[108:111], v[0:15]
	ds_read_b128 v[100:103], v237 offset:12288
	v_mfma_f32_32x32x16_bf16 v[80:95], v[112:115], v[116:119], v[80:95]
	ds_read_b128 v[104:107], v238
	v_cvt_pk_bf16_f32 v108, v136, v137
	v_cvt_pk_bf16_f32 v109, v138, v139
	v_cvt_pk_bf16_f32 v110, v140, v141
	v_cvt_pk_bf16_f32 v111, v142, v143
	v_mfma_f32_32x32x16_bf16 v[64:79], v[120:123], v[116:119], v[64:79]
	ds_read_b128 v[112:115], v238 offset:4096
	v_add_f32_e64 v98, v138, v98
	v_add_f32_e64 v99, v139, v99
	v_add_f32_e64 v96, v136, v96
	v_add_f32_e64 v97, v137, v97
	v_pk_add_f32 v[98:99], v[142:143], v[98:99]
	v_pk_add_f32 v[96:97], v[140:141], v[96:97]
	s_waitcnt lgkmcnt(0)
	v_mfma_f32_32x32x16_bf16 v[16:31], v[132:135], v[116:119], v[16:31]
	ds_read_b128 v[120:123], v238 offset:8192
	v_add_f32_e64 v98, v180, v98
	v_add_f32_e64 v99, v181, v99
	v_add_f32_e64 v96, v178, v96
	v_add_f32_e64 v97, v179, v97
	v_pk_add_f32 v[98:99], v[184:185], v[98:99]
	v_pk_add_f32 v[96:97], v[182:183], v[96:97]
	v_mfma_f32_32x32x16_bf16 v[0:15], v[100:103], v[116:119], v[0:15]
	ds_read_b128 v[124:127], v238 offset:12288
	v_mfma_f32_32x32x16_bf16 v[80:95], v[104:107], v[108:111], v[80:95]
	ds_read_b128 v[100:103], v239
	v_cvt_pk_bf16_f32 v116, v178, v179
	v_cvt_pk_bf16_f32 v117, v180, v181
	v_cvt_pk_bf16_f32 v118, v182, v183
	v_cvt_pk_bf16_f32 v119, v184, v185
	v_mfma_f32_32x32x16_bf16 v[64:79], v[112:115], v[108:111], v[64:79]
	ds_read_b128 v[104:107], v239 offset:4096
	s_waitcnt lgkmcnt(0)
	v_mfma_f32_32x32x16_bf16 v[16:31], v[120:123], v[108:111], v[16:31]
	ds_read_b128 v[112:115], v239 offset:8192
	v_mfma_f32_32x32x16_bf16 v[0:15], v[124:127], v[108:111], v[0:15]
	ds_read_b128 v[120:123], v239 offset:12288
	v_mfma_f32_32x32x16_bf16 v[80:95], v[100:103], v[116:119], v[80:95]
	v_mfma_f32_32x32x16_bf16 v[64:79], v[104:107], v[116:119], v[64:79]
	s_waitcnt lgkmcnt(0)
	v_mfma_f32_32x32x16_bf16 v[16:31], v[112:115], v[116:119], v[16:31]
	v_mfma_f32_32x32x16_bf16 v[0:15], v[120:123], v[116:119], v[0:15]
	s_waitcnt vmcnt(2) lgkmcnt(0)
	v_add_f32_e32 v100, v128, v129
	v_add_f32_e32 v101, v130, v131
	v_add_f32_e32 v100, v100, v101
	v_add_f32_e32 v96, v96, v97
	v_add_f32_e32 v97, v98, v99
	s_barrier
	v_add_f32_e32 v100, v177, v100
	v_add_f32_e32 v96, v96, v97
	v_add_f32_e32 v177, v100, v96
	ds_read_b128 v[96:99], v205 offset:16384
	ds_read_b128 v[100:103], v205 offset:24576
	s_add_i32 s21, s21, 2
	s_addk_i32 s15, 0x80
	s_add_i32 s20, s20, 0x8000
	s_add_i32 s46, s20, 0xffff4000
	s_waitcnt lgkmcnt(0)
	v_mfma_f32_32x32x16_bf16 v[112:127], v[96:99], v[160:163], 0
	ds_read_b128 v[128:131], v211 offset:16384
	ds_read_b128 v[132:135], v211 offset:24576
	ds_read_b128 v[136:139], v212 offset:16384
	v_exp_f32_e32 v140, v48
	v_exp_f32_e32 v141, v49
	v_exp_f32_e32 v142, v50
	v_exp_f32_e32 v143, v51
	ds_read_b128 v[48:51], v212 offset:24576
	v_mfma_f32_32x32x16_bf16 v[96:111], v[100:103], v[160:163], 0
	v_exp_f32_e32 v144, v52
	v_exp_f32_e32 v145, v53
	v_exp_f32_e32 v146, v54
	v_exp_f32_e32 v147, v55
	s_waitcnt lgkmcnt(0)
	v_mfma_f32_32x32x16_bf16 v[112:127], v[128:131], v[164:167], v[112:127]
	ds_read_b128 v[52:55], v213 offset:16384
	v_exp_f32_e32 v148, v56
	v_exp_f32_e32 v149, v57
	v_exp_f32_e32 v150, v58
	v_exp_f32_e32 v151, v59
	v_mfma_f32_32x32x16_bf16 v[96:111], v[132:135], v[164:167], v[96:111]
	ds_read_b128 v[56:59], v213 offset:24576
	v_exp_f32_e32 v128, v60
	v_exp_f32_e32 v129, v61
	v_exp_f32_e32 v130, v62
	v_exp_f32_e32 v131, v63
	v_mfma_f32_32x32x16_bf16 v[112:127], v[136:139], v[168:171], v[112:127]
	ds_read_b128 v[60:63], v236 offset:16384
	v_exp_f32_e32 v132, v32
	v_exp_f32_e32 v133, v33
	v_exp_f32_e32 v134, v34
	v_exp_f32_e32 v135, v35
	v_mfma_f32_32x32x16_bf16 v[96:111], v[48:51], v[168:171], v[96:111]
	ds_read_b128 v[32:35], v236 offset:20480
	v_exp_f32_e32 v136, v36
	v_exp_f32_e32 v137, v37
	v_exp_f32_e32 v138, v38
	v_exp_f32_e32 v139, v39
	s_waitcnt lgkmcnt(0)
	v_mfma_f32_32x32x16_bf16 v[112:127], v[52:55], v[172:175], v[112:127]
	ds_read_b128 v[36:39], v236 offset:24576
	v_exp_f32_e32 v152, v40
	v_exp_f32_e32 v153, v41
	v_exp_f32_e32 v154, v42
	v_exp_f32_e32 v155, v43
	v_mfma_f32_32x32x16_bf16 v[96:111], v[56:59], v[172:175], v[96:111]
	ds_read_b128 v[40:43], v236 offset:28672
	v_exp_f32_e32 v156, v44
	v_exp_f32_e32 v157, v45
	v_exp_f32_e32 v158, v46
	v_exp_f32_e32 v159, v47
	v_cvt_pk_bf16_f32 v44, v140, v141
	v_cvt_pk_bf16_f32 v45, v142, v143
	v_cvt_pk_bf16_f32 v46, v144, v145
	v_cvt_pk_bf16_f32 v47, v146, v147
	s_nop 1
	v_mfma_f32_32x32x16_bf16 v[80:95], v[60:63], v[44:47], v[80:95]
	ds_read_b128 v[48:51], v237 offset:16384
	v_cvt_pk_bf16_f32 v52, v148, v149
	v_cvt_pk_bf16_f32 v53, v150, v151
	v_cvt_pk_bf16_f32 v54, v128, v129
	v_cvt_pk_bf16_f32 v55, v130, v131
	v_mfma_f32_32x32x16_bf16 v[64:79], v[32:35], v[44:47], v[64:79]
	ds_read_b128 v[56:59], v237 offset:20480
	v_pk_add_f32 v[62:63], v[146:147], v[142:143]
	v_pk_add_f32 v[60:61], v[144:145], v[140:141]
	s_waitcnt lgkmcnt(0)
	v_mfma_f32_32x32x16_bf16 v[16:31], v[36:39], v[44:47], v[16:31]
	ds_read_b128 v[32:35], v237 offset:24576
	v_add_f32_e64 v62, v150, v62
	v_add_f32_e64 v63, v151, v63
	v_add_f32_e64 v60, v148, v60
	v_add_f32_e64 v61, v149, v61
	v_pk_add_f32 v[62:63], v[130:131], v[62:63]
	v_pk_add_f32 v[60:61], v[128:129], v[60:61]
	v_mfma_f32_32x32x16_bf16 v[0:15], v[40:43], v[44:47], v[0:15]
	ds_read_b128 v[36:39], v237 offset:28672
	v_mfma_f32_32x32x16_bf16 v[80:95], v[48:51], v[52:55], v[80:95]
	ds_read_b128 v[40:43], v238 offset:16384
	v_cvt_pk_bf16_f32 v44, v132, v133
	v_cvt_pk_bf16_f32 v45, v134, v135
	v_cvt_pk_bf16_f32 v46, v136, v137
	v_cvt_pk_bf16_f32 v47, v138, v139
	v_mfma_f32_32x32x16_bf16 v[64:79], v[56:59], v[52:55], v[64:79]
	ds_read_b128 v[48:51], v238 offset:20480
	v_add_f32_e64 v62, v134, v62
	v_add_f32_e64 v63, v135, v63
	v_add_f32_e64 v60, v132, v60
	v_add_f32_e64 v61, v133, v61
	v_pk_add_f32 v[62:63], v[138:139], v[62:63]
	v_pk_add_f32 v[60:61], v[136:137], v[60:61]
	s_waitcnt lgkmcnt(0)
	v_mfma_f32_32x32x16_bf16 v[16:31], v[32:35], v[52:55], v[16:31]
	ds_read_b128 v[56:59], v238 offset:24576
	v_add_f32_e64 v62, v154, v62
	v_add_f32_e64 v63, v155, v63
	v_add_f32_e64 v60, v152, v60
	v_add_f32_e64 v61, v153, v61
	v_pk_add_f32 v[130:131], v[158:159], v[62:63]
	v_pk_add_f32 v[128:129], v[156:157], v[60:61]
	v_mfma_f32_32x32x16_bf16 v[0:15], v[36:39], v[52:55], v[0:15]
	ds_read_b128 v[32:35], v238 offset:28672
	v_mfma_f32_32x32x16_bf16 v[80:95], v[40:43], v[44:47], v[80:95]
	ds_read_b128 v[36:39], v239 offset:16384
	v_cvt_pk_bf16_f32 v52, v152, v153
	v_cvt_pk_bf16_f32 v53, v154, v155
	v_cvt_pk_bf16_f32 v54, v156, v157
	v_cvt_pk_bf16_f32 v55, v158, v159
	v_mfma_f32_32x32x16_bf16 v[64:79], v[48:51], v[44:47], v[64:79]
	ds_read_b128 v[40:43], v239 offset:20480
	s_waitcnt lgkmcnt(0)
	v_mfma_f32_32x32x16_bf16 v[16:31], v[56:59], v[44:47], v[16:31]
	ds_read_b128 v[48:51], v239 offset:24576
	v_mfma_f32_32x32x16_bf16 v[0:15], v[32:35], v[44:47], v[0:15]
	ds_read_b128 v[56:59], v239 offset:28672
	v_mfma_f32_32x32x16_bf16 v[80:95], v[36:39], v[52:55], v[80:95]
	v_mfma_f32_32x32x16_bf16 v[64:79], v[40:43], v[52:55], v[64:79]
	s_waitcnt lgkmcnt(0)
	v_mfma_f32_32x32x16_bf16 v[16:31], v[48:51], v[52:55], v[16:31]
	v_mfma_f32_32x32x16_bf16 v[0:15], v[56:59], v[52:55], v[0:15]
	s_waitcnt vmcnt(0) lgkmcnt(0)
	s_barrier
	ds_read_b128 v[32:35], v205 offset:32768
	ds_read_b128 v[36:39], v205 offset:40960
	v_exp_f32_e32 v144, v112
	s_waitcnt lgkmcnt(0)
	v_mfma_f32_32x32x16_bf16 v[48:63], v[32:35], v[160:163], 0
	ds_read_b128 v[132:135], v211 offset:32768
	ds_read_b128 v[136:139], v211 offset:40960
	ds_read_b128 v[140:143], v212 offset:32768
	v_exp_f32_e32 v145, v113
	v_exp_f32_e32 v146, v114
	v_exp_f32_e32 v147, v115
	ds_read_b128 v[112:115], v212 offset:40960
	v_mfma_f32_32x32x16_bf16 v[32:47], v[36:39], v[160:163], 0
	v_exp_f32_e32 v148, v116
	v_exp_f32_e32 v149, v117
	v_exp_f32_e32 v150, v118
	v_exp_f32_e32 v151, v119
	s_waitcnt lgkmcnt(0)
	v_mfma_f32_32x32x16_bf16 v[48:63], v[132:135], v[164:167], v[48:63]
	ds_read_b128 v[116:119], v213 offset:32768
	v_exp_f32_e32 v152, v120
	v_exp_f32_e32 v153, v121
	v_exp_f32_e32 v154, v122
	v_exp_f32_e32 v155, v123
	v_mfma_f32_32x32x16_bf16 v[32:47], v[136:139], v[164:167], v[32:47]
	ds_read_b128 v[120:123], v213 offset:40960
	v_exp_f32_e32 v156, v124
	v_exp_f32_e32 v157, v125
	v_exp_f32_e32 v158, v126
	v_exp_f32_e32 v159, v127
	v_mfma_f32_32x32x16_bf16 v[48:63], v[140:143], v[168:171], v[48:63]
	ds_read_b128 v[124:127], v236 offset:32768
	v_exp_f32_e32 v136, v96
	v_exp_f32_e32 v137, v97
	v_exp_f32_e32 v138, v98
	v_exp_f32_e32 v139, v99
	v_mfma_f32_32x32x16_bf16 v[32:47], v[112:115], v[168:171], v[32:47]
	ds_read_b128 v[96:99], v236 offset:36864
	v_exp_f32_e32 v140, v100
	v_exp_f32_e32 v141, v101
	v_exp_f32_e32 v142, v102
	v_exp_f32_e32 v143, v103
	s_waitcnt lgkmcnt(0)
	v_mfma_f32_32x32x16_bf16 v[48:63], v[116:119], v[172:175], v[48:63]
	ds_read_b128 v[100:103], v236 offset:40960
	v_exp_f32_e32 v178, v104
	v_exp_f32_e32 v179, v105
	v_exp_f32_e32 v180, v106
	v_exp_f32_e32 v181, v107
	v_mfma_f32_32x32x16_bf16 v[32:47], v[120:123], v[172:175], v[32:47]
	ds_read_b128 v[104:107], v236 offset:45056
	v_exp_f32_e32 v182, v108
	v_exp_f32_e32 v183, v109
	v_exp_f32_e32 v184, v110
	v_exp_f32_e32 v185, v111
	v_cvt_pk_bf16_f32 v108, v144, v145
	v_cvt_pk_bf16_f32 v109, v146, v147
	v_cvt_pk_bf16_f32 v110, v148, v149
	v_cvt_pk_bf16_f32 v111, v150, v151
	s_nop 1
	v_mfma_f32_32x32x16_bf16 v[80:95], v[124:127], v[108:111], v[80:95]
	ds_read_b128 v[112:115], v237 offset:32768
	v_cvt_pk_bf16_f32 v116, v152, v153
	v_cvt_pk_bf16_f32 v117, v154, v155
	v_cvt_pk_bf16_f32 v118, v156, v157
	v_cvt_pk_bf16_f32 v119, v158, v159
	v_mfma_f32_32x32x16_bf16 v[64:79], v[96:99], v[108:111], v[64:79]
	ds_read_b128 v[120:123], v237 offset:36864
	v_pk_add_f32 v[126:127], v[150:151], v[146:147]
	v_pk_add_f32 v[124:125], v[148:149], v[144:145]
	s_waitcnt lgkmcnt(0)
	v_mfma_f32_32x32x16_bf16 v[16:31], v[100:103], v[108:111], v[16:31]
	ds_read_b128 v[132:135], v237 offset:40960
	v_add_f32_e64 v98, v154, v126
	v_add_f32_e64 v99, v155, v127
	v_add_f32_e64 v96, v152, v124
	v_add_f32_e64 v97, v153, v125
	v_pk_add_f32 v[98:99], v[158:159], v[98:99]
	v_pk_add_f32 v[96:97], v[156:157], v[96:97]
	v_mfma_f32_32x32x16_bf16 v[0:15], v[104:107], v[108:111], v[0:15]
	ds_read_b128 v[100:103], v237 offset:45056
	v_mfma_f32_32x32x16_bf16 v[80:95], v[112:115], v[116:119], v[80:95]
	ds_read_b128 v[104:107], v238 offset:32768
	v_cvt_pk_bf16_f32 v108, v136, v137
	v_cvt_pk_bf16_f32 v109, v138, v139
	v_cvt_pk_bf16_f32 v110, v140, v141
	v_cvt_pk_bf16_f32 v111, v142, v143
	v_mfma_f32_32x32x16_bf16 v[64:79], v[120:123], v[116:119], v[64:79]
	ds_read_b128 v[112:115], v238 offset:36864
	v_add_f32_e64 v98, v138, v98
	v_add_f32_e64 v99, v139, v99
	v_add_f32_e64 v96, v136, v96
	v_add_f32_e64 v97, v137, v97
	v_pk_add_f32 v[98:99], v[142:143], v[98:99]
	v_pk_add_f32 v[96:97], v[140:141], v[96:97]
	s_waitcnt lgkmcnt(0)
	v_mfma_f32_32x32x16_bf16 v[16:31], v[132:135], v[116:119], v[16:31]
	ds_read_b128 v[120:123], v238 offset:40960
	v_add_f32_e64 v98, v180, v98
	v_add_f32_e64 v99, v181, v99
	v_add_f32_e64 v96, v178, v96
	v_add_f32_e64 v97, v179, v97
	v_pk_add_f32 v[98:99], v[184:185], v[98:99]
	v_pk_add_f32 v[96:97], v[182:183], v[96:97]
	v_mfma_f32_32x32x16_bf16 v[0:15], v[100:103], v[116:119], v[0:15]
	ds_read_b128 v[124:127], v238 offset:45056
	v_mfma_f32_32x32x16_bf16 v[80:95], v[104:107], v[108:111], v[80:95]
	ds_read_b128 v[100:103], v239 offset:32768
	v_cvt_pk_bf16_f32 v116, v178, v179
	v_cvt_pk_bf16_f32 v117, v180, v181
	v_cvt_pk_bf16_f32 v118, v182, v183
	v_cvt_pk_bf16_f32 v119, v184, v185
	v_mfma_f32_32x32x16_bf16 v[64:79], v[112:115], v[108:111], v[64:79]
	ds_read_b128 v[104:107], v239 offset:36864
	s_waitcnt lgkmcnt(0)
	v_mfma_f32_32x32x16_bf16 v[16:31], v[120:123], v[108:111], v[16:31]
	ds_read_b128 v[112:115], v239 offset:40960
	v_mfma_f32_32x32x16_bf16 v[0:15], v[124:127], v[108:111], v[0:15]
	ds_read_b128 v[120:123], v239 offset:45056
	v_mfma_f32_32x32x16_bf16 v[80:95], v[100:103], v[116:119], v[80:95]
	v_mfma_f32_32x32x16_bf16 v[64:79], v[104:107], v[116:119], v[64:79]
	s_waitcnt lgkmcnt(0)
	v_mfma_f32_32x32x16_bf16 v[16:31], v[112:115], v[116:119], v[16:31]
	v_mfma_f32_32x32x16_bf16 v[0:15], v[120:123], v[116:119], v[0:15]
	s_waitcnt vmcnt(0) lgkmcnt(0)
	v_add_f32_e32 v100, v128, v129
	v_add_f32_e32 v101, v130, v131
	v_add_f32_e32 v100, v100, v101
	v_add_f32_e32 v96, v96, v97
	v_add_f32_e32 v97, v98, v99
	s_barrier
	v_add_f32_e32 v100, v177, v100
	v_add_f32_e32 v96, v96, v97
	v_add_f32_e32 v177, v100, v96
	s_add_i32 s21, s21, 2
	s_addk_i32 s15, 0x80
	s_add_i32 s20, s20, 0x8000
	s_branch .LBB0_960

.Lst1_u6_loop:
	ds_read_b128 v[140:143], v206 offset:49152
	ds_read_b128 v[148:151], v206 offset:53248
	ds_read_b128 v[152:155], v206 offset:57344
	ds_read_b128 v[156:159], v206 offset:61440
	s_add_i32 s49, s58, 0x4000
	s_mov_b32 m0, s49
	s_nop 0
	global_load_lds_dwordx4 v198, s[98:99]
	s_add_i32 m0, s49, 0x400
	s_nop 0
	global_load_lds_dwordx4 v194, s[98:99]
	s_add_i32 s49, s58, 0xc000
	s_add_i32 m0, s49, 0xc000
	s_nop 0
	global_load_lds_dwordx4 v196, s[100:101]
	s_add_i32 m0, s49, 0xc400
	s_nop 0
	global_load_lds_dwordx4 v192, s[100:101]
	s_waitcnt lgkmcnt(0)
	v_mfma_f32_32x32x16_bf16 v[80:95], v[140:143], v[144:147], v[80:95]
	ds_read_b128 v[140:143], v207 offset:49152
	v_mfma_f32_32x32x16_bf16 v[64:79], v[148:151], v[144:147], v[64:79]
	ds_read_b128 v[148:151], v207 offset:53248
	v_mfma_f32_32x32x16_bf16 v[16:31], v[152:155], v[144:147], v[16:31]
	ds_read_b128 v[152:155], v207 offset:57344
	v_mfma_f32_32x32x16_bf16 v[0:15], v[156:159], v[144:147], v[0:15]
	ds_read_b128 v[144:147], v207 offset:61440
	s_waitcnt lgkmcnt(0)
	v_mfma_f32_32x32x16_bf16 v[80:95], v[140:143], v[128:131], v[80:95]
	ds_read_b128 v[140:143], v208 offset:49152
	v_mfma_f32_32x32x16_bf16 v[64:79], v[148:151], v[128:131], v[64:79]
	ds_read_b128 v[148:151], v208 offset:53248
	v_mfma_f32_32x32x16_bf16 v[16:31], v[152:155], v[128:131], v[16:31]
	ds_read_b128 v[152:155], v208 offset:57344
	v_mfma_f32_32x32x16_bf16 v[0:15], v[144:147], v[128:131], v[0:15]
	ds_read_b128 v[128:131], v208 offset:61440
	s_waitcnt lgkmcnt(0)
	v_mfma_f32_32x32x16_bf16 v[80:95], v[140:143], v[132:135], v[80:95]
	ds_read_b128 v[140:143], v209 offset:49152
	v_mfma_f32_32x32x16_bf16 v[64:79], v[148:151], v[132:135], v[64:79]
	ds_read_b128 v[144:147], v209 offset:53248
	v_mfma_f32_32x32x16_bf16 v[16:31], v[152:155], v[132:135], v[16:31]
	ds_read_b128 v[148:151], v209 offset:57344
	v_mfma_f32_32x32x16_bf16 v[0:15], v[128:131], v[132:135], v[0:15]
	ds_read_b128 v[128:131], v209 offset:61440
	s_waitcnt lgkmcnt(0)
	v_mfma_f32_32x32x16_bf16 v[80:95], v[140:143], v[136:139], v[80:95]
	ds_read_b128 v[132:135], v205 offset:32768
	v_mfma_f32_32x32x16_bf16 v[64:79], v[144:147], v[136:139], v[64:79]
	ds_read_b128 v[140:143], v205 offset:40960
	v_mfma_f32_32x32x16_bf16 v[16:31], v[148:151], v[136:139], v[16:31]
	ds_read_b128 v[176:179], v211 offset:32768
	v_mfma_f32_32x32x16_bf16 v[0:15], v[128:131], v[136:139], v[0:15]
	ds_read_b128 v[182:185], v211 offset:40960
	s_waitcnt lgkmcnt(0)
	v_mfma_f32_32x32x16_bf16 v[144:159], v[132:135], v[160:163], 0
	ds_read_b128 v[186:189], v212 offset:32768
	v_exp_f32_e32 v220, v112
	v_exp_f32_e32 v221, v113
	v_exp_f32_e32 v222, v114
	v_exp_f32_e32 v223, v115
	v_mfma_f32_32x32x16_bf16 v[128:143], v[140:143], v[160:163], 0
	ds_read_b128 v[216:219], v212 offset:40960
	v_exp_f32_e32 v224, v116
	v_exp_f32_e32 v225, v117
	v_exp_f32_e32 v226, v118
	v_exp_f32_e32 v227, v119
	v_mfma_f32_32x32x16_bf16 v[144:159], v[176:179], v[164:167], v[144:159]
	ds_read_b128 v[116:119], v213 offset:32768
	v_exp_f32_e32 v228, v120
	v_exp_f32_e32 v229, v121
	v_exp_f32_e32 v230, v122
	v_exp_f32_e32 v231, v123
	v_cvt_pk_bf16_f32 v112, v220, v221
	v_cvt_pk_bf16_f32 v113, v222, v223
	v_cvt_pk_bf16_f32 v114, v224, v225
	v_cvt_pk_bf16_f32 v115, v226, v227
	v_pk_add_f32 v[122:123], v[226:227], v[222:223]
	v_pk_add_f32 v[120:121], v[224:225], v[220:221]
	v_mfma_f32_32x32x16_bf16 v[128:143], v[182:185], v[164:167], v[128:143]
	ds_read_b128 v[176:179], v213 offset:40960
	v_exp_f32_e32 v124, v124
	v_exp_f32_e32 v125, v125
	v_exp_f32_e32 v126, v126
	v_exp_f32_e32 v127, v127
	s_waitcnt lgkmcnt(0)
	v_mfma_f32_32x32x16_bf16 v[144:159], v[186:189], v[168:171], v[144:159]
	v_add_f32_e64 v122, v230, v122
	v_add_f32_e64 v123, v231, v123
	v_add_f32_e64 v120, v228, v120
	v_add_f32_e64 v121, v229, v121
	v_exp_f32_e32 v182, v96
	v_exp_f32_e32 v183, v97
	v_exp_f32_e32 v184, v98
	v_exp_f32_e32 v185, v99
	v_cvt_pk_bf16_f32 v96, v228, v229
	v_cvt_pk_bf16_f32 v97, v230, v231
	v_cvt_pk_bf16_f32 v98, v124, v125
	v_cvt_pk_bf16_f32 v99, v126, v127
	v_pk_add_f32 v[122:123], v[126:127], v[122:123]
	v_pk_add_f32 v[120:121], v[124:125], v[120:121]
	v_mfma_f32_32x32x16_bf16 v[128:143], v[216:219], v[168:171], v[128:143]
	v_exp_f32_e32 v124, v100
	v_exp_f32_e32 v125, v101
	v_exp_f32_e32 v126, v102
	v_exp_f32_e32 v127, v103
	v_mfma_f32_32x32x16_bf16 v[144:159], v[116:119], v[172:175], v[144:159]
	v_exp_f32_e32 v186, v104
	v_exp_f32_e32 v187, v105
	v_exp_f32_e32 v188, v106
	v_exp_f32_e32 v189, v107
	v_pk_add_f32 v[106:107], v[184:185], v[122:123]
	v_pk_add_f32 v[104:105], v[182:183], v[120:121]
	v_cvt_pk_bf16_f32 v100, v182, v183
	v_cvt_pk_bf16_f32 v101, v184, v185
	v_cvt_pk_bf16_f32 v102, v124, v125
	v_cvt_pk_bf16_f32 v103, v126, v127
	v_pk_add_f32 v[118:119], v[126:127], v[106:107]
	v_pk_add_f32 v[116:117], v[124:125], v[104:105]
	v_mfma_f32_32x32x16_bf16 v[128:143], v[176:179], v[172:175], v[128:143]
	v_exp_f32_e32 v120, v108
	v_exp_f32_e32 v121, v109
	v_exp_f32_e32 v122, v110
	v_exp_f32_e32 v123, v111
	v_pk_add_f32 v[110:111], v[188:189], v[118:119]
	v_pk_add_f32 v[108:109], v[186:187], v[116:117]
	v_cvt_pk_bf16_f32 v104, v186, v187
	v_cvt_pk_bf16_f32 v105, v188, v189
	v_cvt_pk_bf16_f32 v106, v120, v121
	v_cvt_pk_bf16_f32 v107, v122, v123
	v_pk_add_f32 v[178:179], v[122:123], v[110:111]
	v_pk_add_f32 v[176:177], v[120:121], v[108:109]
	s_waitcnt vmcnt(4) lgkmcnt(0)
	s_barrier
	ds_read_b128 v[108:111], v236
	ds_read_b128 v[116:119], v236 offset:4096
	ds_read_b128 v[120:123], v236 offset:8192
	ds_read_b128 v[124:127], v236 offset:12288
	s_add_u32 s70, s98, 0x18000
	s_addc_u32 s71, s99, 0
	s_add_i32 s68, 0x8000, s57
	s_mov_b32 m0, s68
	s_nop 0
	global_load_lds_dwordx4 v198, s[70:71]
	s_add_i32 m0, s68, 0x400
	s_nop 0
	global_load_lds_dwordx4 v194, s[70:71]
	s_add_u32 s2, s100, 0x80
	s_addc_u32 s3, s101, 0
	s_add_i32 s49, s58, 0
	s_add_i32 m0, s49, 0xc000
	s_nop 0
	global_load_lds_dwordx4 v196, s[2:3]
	s_add_i32 m0, s49, 0xc400
	s_nop 0
	global_load_lds_dwordx4 v192, s[2:3]
	s_waitcnt lgkmcnt(0)
	v_mfma_f32_32x32x16_bf16 v[80:95], v[108:111], v[112:115], v[80:95]
	ds_read_b128 v[108:111], v237
	v_mfma_f32_32x32x16_bf16 v[64:79], v[116:119], v[112:115], v[64:79]
	ds_read_b128 v[116:119], v237 offset:4096
	v_mfma_f32_32x32x16_bf16 v[16:31], v[120:123], v[112:115], v[16:31]
	ds_read_b128 v[120:123], v237 offset:8192
	v_mfma_f32_32x32x16_bf16 v[0:15], v[124:127], v[112:115], v[0:15]
	ds_read_b128 v[112:115], v237 offset:12288
	s_waitcnt lgkmcnt(0)
	v_mfma_f32_32x32x16_bf16 v[80:95], v[108:111], v[96:99], v[80:95]
	ds_read_b128 v[108:111], v238
	v_mfma_f32_32x32x16_bf16 v[64:79], v[116:119], v[96:99], v[64:79]
	ds_read_b128 v[116:119], v238 offset:4096
	v_mfma_f32_32x32x16_bf16 v[16:31], v[120:123], v[96:99], v[16:31]
	ds_read_b128 v[120:123], v238 offset:8192
	v_mfma_f32_32x32x16_bf16 v[0:15], v[112:115], v[96:99], v[0:15]
	ds_read_b128 v[96:99], v238 offset:12288
	s_waitcnt lgkmcnt(0)
	v_mfma_f32_32x32x16_bf16 v[80:95], v[108:111], v[100:103], v[80:95]
	ds_read_b128 v[108:111], v239
	v_mfma_f32_32x32x16_bf16 v[64:79], v[116:119], v[100:103], v[64:79]
	ds_read_b128 v[112:115], v239 offset:4096
	v_mfma_f32_32x32x16_bf16 v[16:31], v[120:123], v[100:103], v[16:31]
	ds_read_b128 v[116:119], v239 offset:8192
	v_mfma_f32_32x32x16_bf16 v[0:15], v[96:99], v[100:103], v[0:15]
	ds_read_b128 v[120:123], v239 offset:12288
	s_waitcnt lgkmcnt(0)
	v_mfma_f32_32x32x16_bf16 v[80:95], v[108:111], v[104:107], v[80:95]
	ds_read_b128 v[96:99], v205
	v_mfma_f32_32x32x16_bf16 v[64:79], v[112:115], v[104:107], v[64:79]
	ds_read_b128 v[100:103], v205 offset:8192
	v_mfma_f32_32x32x16_bf16 v[16:31], v[116:119], v[104:107], v[16:31]
	ds_read_b128 v[182:185], v211
	v_mfma_f32_32x32x16_bf16 v[0:15], v[120:123], v[104:107], v[0:15]
	ds_read_b128 v[186:189], v211 offset:8192
	s_waitcnt lgkmcnt(0)
	v_mfma_f32_32x32x16_bf16 v[112:127], v[96:99], v[160:163], 0
	ds_read_b128 v[216:219], v212
	v_exp_f32_e32 v224, v144
	v_exp_f32_e32 v225, v145
	v_exp_f32_e32 v226, v146
	v_exp_f32_e32 v227, v147
	ds_read_b128 v[220:223], v212 offset:8192
	v_mfma_f32_32x32x16_bf16 v[96:111], v[100:103], v[160:163], 0
	v_exp_f32_e32 v228, v148
	v_exp_f32_e32 v229, v149
	v_exp_f32_e32 v230, v150
	v_exp_f32_e32 v231, v151
	v_mfma_f32_32x32x16_bf16 v[112:127], v[182:185], v[164:167], v[112:127]
	ds_read_b128 v[148:151], v213
	v_exp_f32_e32 v232, v152
	v_exp_f32_e32 v233, v153
	v_exp_f32_e32 v234, v154
	v_exp_f32_e32 v235, v155
	v_cvt_pk_bf16_f32 v144, v224, v225
	v_cvt_pk_bf16_f32 v145, v226, v227
	v_cvt_pk_bf16_f32 v146, v228, v229
	v_cvt_pk_bf16_f32 v147, v230, v231
	v_pk_add_f32 v[154:155], v[230:231], v[226:227]
	v_pk_add_f32 v[152:153], v[228:229], v[224:225]
	v_mfma_f32_32x32x16_bf16 v[96:111], v[186:189], v[164:167], v[96:111]
	ds_read_b128 v[182:185], v213 offset:8192
	v_exp_f32_e32 v156, v156
	v_exp_f32_e32 v157, v157
	v_exp_f32_e32 v158, v158
	v_exp_f32_e32 v159, v159
	s_waitcnt lgkmcnt(0)
	v_mfma_f32_32x32x16_bf16 v[112:127], v[216:219], v[168:171], v[112:127]
	v_add_f32_e64 v154, v234, v154
	v_add_f32_e64 v155, v235, v155
	v_add_f32_e64 v152, v232, v152
	v_add_f32_e64 v153, v233, v153
	v_exp_f32_e32 v186, v128
	v_exp_f32_e32 v187, v129
	v_exp_f32_e32 v188, v130
	v_exp_f32_e32 v189, v131
	v_cvt_pk_bf16_f32 v128, v232, v233
	v_cvt_pk_bf16_f32 v129, v234, v235
	v_cvt_pk_bf16_f32 v130, v156, v157
	v_cvt_pk_bf16_f32 v131, v158, v159
	v_pk_add_f32 v[154:155], v[158:159], v[154:155]
	v_pk_add_f32 v[152:153], v[156:157], v[152:153]
	v_mfma_f32_32x32x16_bf16 v[96:111], v[220:223], v[168:171], v[96:111]
	v_exp_f32_e32 v156, v132
	v_exp_f32_e32 v157, v133
	v_exp_f32_e32 v158, v134
	v_exp_f32_e32 v159, v135
	v_mfma_f32_32x32x16_bf16 v[112:127], v[148:151], v[172:175], v[112:127]
	v_exp_f32_e32 v216, v136
	v_exp_f32_e32 v217, v137
	v_exp_f32_e32 v218, v138
	v_exp_f32_e32 v219, v139
	v_pk_add_f32 v[138:139], v[188:189], v[154:155]
	v_pk_add_f32 v[136:137], v[186:187], v[152:153]
	v_cvt_pk_bf16_f32 v132, v186, v187
	v_cvt_pk_bf16_f32 v133, v188, v189
	v_cvt_pk_bf16_f32 v134, v156, v157
	v_cvt_pk_bf16_f32 v135, v158, v159
	v_pk_add_f32 v[150:151], v[158:159], v[138:139]
	v_pk_add_f32 v[148:149], v[156:157], v[136:137]
	v_mfma_f32_32x32x16_bf16 v[96:111], v[182:185], v[172:175], v[96:111]
	v_exp_f32_e32 v152, v140
	v_exp_f32_e32 v153, v141
	v_exp_f32_e32 v154, v142
	v_exp_f32_e32 v155, v143
	v_pk_add_f32 v[142:143], v[218:219], v[150:151]
	v_pk_add_f32 v[140:141], v[216:217], v[148:149]
	v_cvt_pk_bf16_f32 v136, v216, v217
	v_cvt_pk_bf16_f32 v137, v218, v219
	v_cvt_pk_bf16_f32 v138, v152, v153
	v_cvt_pk_bf16_f32 v139, v154, v155
	v_pk_add_f32 v[142:143], v[154:155], v[142:143]
	v_pk_add_f32 v[140:141], v[152:153], v[140:141]
	s_waitcnt vmcnt(4) lgkmcnt(0)
	v_add_f32_e32 v148, v176, v177
	v_add_f32_e32 v149, v178, v179
	v_add_f32_e32 v148, v148, v149
	v_add_f32_e32 v140, v140, v141
	v_add_f32_e32 v141, v142, v143
	s_barrier
	v_add_f32_e32 v148, v180, v148
	v_add_f32_e32 v140, v140, v141
	v_add_f32_e32 v180, v148, v140
	ds_read_b128 v[140:143], v236 offset:16384
	ds_read_b128 v[148:151], v236 offset:20480
	ds_read_b128 v[152:155], v236 offset:24576
	ds_read_b128 v[156:159], v236 offset:28672
	s_add_u32 s98, s98, 0x30000
	s_addc_u32 s99, s99, 0
	s_add_u32 s100, s100, 0x100
	s_addc_u32 s101, s101, 0
	s_add_i32 s49, s58, 0
	s_mov_b32 m0, s49
	s_nop 0
	global_load_lds_dwordx4 v198, s[98:99]
	s_add_i32 m0, s49, 0x400
	s_nop 0
	global_load_lds_dwordx4 v194, s[98:99]
	s_add_i32 s49, s58, 0x4000
	s_add_i32 m0, s49, 0xc000
	s_nop 0
	global_load_lds_dwordx4 v196, s[100:101]
	s_add_i32 m0, s49, 0xc400
	s_nop 0
	global_load_lds_dwordx4 v192, s[100:101]
	s_waitcnt lgkmcnt(0)
	v_mfma_f32_32x32x16_bf16 v[80:95], v[140:143], v[144:147], v[80:95]
	ds_read_b128 v[140:143], v237 offset:16384
	v_mfma_f32_32x32x16_bf16 v[64:79], v[148:151], v[144:147], v[64:79]
	ds_read_b128 v[148:151], v237 offset:20480
	v_mfma_f32_32x32x16_bf16 v[16:31], v[152:155], v[144:147], v[16:31]
	ds_read_b128 v[152:155], v237 offset:24576
	v_mfma_f32_32x32x16_bf16 v[0:15], v[156:159], v[144:147], v[0:15]
	ds_read_b128 v[144:147], v237 offset:28672
	s_waitcnt lgkmcnt(0)
	v_mfma_f32_32x32x16_bf16 v[80:95], v[140:143], v[128:131], v[80:95]
	ds_read_b128 v[140:143], v238 offset:16384
	v_mfma_f32_32x32x16_bf16 v[64:79], v[148:151], v[128:131], v[64:79]
	ds_read_b128 v[148:151], v238 offset:20480
	v_mfma_f32_32x32x16_bf16 v[16:31], v[152:155], v[128:131], v[16:31]
	ds_read_b128 v[152:155], v238 offset:24576
	v_mfma_f32_32x32x16_bf16 v[0:15], v[144:147], v[128:131], v[0:15]
	ds_read_b128 v[128:131], v238 offset:28672
	s_waitcnt lgkmcnt(0)
	v_mfma_f32_32x32x16_bf16 v[80:95], v[140:143], v[132:135], v[80:95]
	ds_read_b128 v[140:143], v239 offset:16384
	v_mfma_f32_32x32x16_bf16 v[64:79], v[148:151], v[132:135], v[64:79]
	ds_read_b128 v[144:147], v239 offset:20480
	v_mfma_f32_32x32x16_bf16 v[16:31], v[152:155], v[132:135], v[16:31]
	ds_read_b128 v[148:151], v239 offset:24576
	v_mfma_f32_32x32x16_bf16 v[0:15], v[128:131], v[132:135], v[0:15]
	ds_read_b128 v[128:131], v239 offset:28672
	s_waitcnt lgkmcnt(0)
	v_mfma_f32_32x32x16_bf16 v[80:95], v[140:143], v[136:139], v[80:95]
	ds_read_b128 v[132:135], v205 offset:16384
	v_mfma_f32_32x32x16_bf16 v[64:79], v[144:147], v[136:139], v[64:79]
	ds_read_b128 v[140:143], v205 offset:24576
	v_mfma_f32_32x32x16_bf16 v[16:31], v[148:151], v[136:139], v[16:31]
	ds_read_b128 v[176:179], v211 offset:16384
	v_mfma_f32_32x32x16_bf16 v[0:15], v[128:131], v[136:139], v[0:15]
	ds_read_b128 v[182:185], v211 offset:24576
	s_waitcnt lgkmcnt(0)
	v_mfma_f32_32x32x16_bf16 v[144:159], v[132:135], v[160:163], 0
	ds_read_b128 v[186:189], v212 offset:16384
	v_exp_f32_e32 v220, v112
	v_exp_f32_e32 v221, v113
	v_exp_f32_e32 v222, v114
	v_exp_f32_e32 v223, v115
	v_mfma_f32_32x32x16_bf16 v[128:143], v[140:143], v[160:163], 0
	ds_read_b128 v[216:219], v212 offset:24576
	v_exp_f32_e32 v224, v116
	v_exp_f32_e32 v225, v117
	v_exp_f32_e32 v226, v118
	v_exp_f32_e32 v227, v119
	v_mfma_f32_32x32x16_bf16 v[144:159], v[176:179], v[164:167], v[144:159]
	ds_read_b128 v[116:119], v213 offset:16384
	v_exp_f32_e32 v228, v120
	v_exp_f32_e32 v229, v121
	v_exp_f32_e32 v230, v122
	v_exp_f32_e32 v231, v123
	v_cvt_pk_bf16_f32 v112, v220, v221
	v_cvt_pk_bf16_f32 v113, v222, v223
	v_cvt_pk_bf16_f32 v114, v224, v225
	v_cvt_pk_bf16_f32 v115, v226, v227
	v_pk_add_f32 v[122:123], v[226:227], v[222:223]
	v_pk_add_f32 v[120:121], v[224:225], v[220:221]
	v_mfma_f32_32x32x16_bf16 v[128:143], v[182:185], v[164:167], v[128:143]
	ds_read_b128 v[176:179], v213 offset:24576
	v_exp_f32_e32 v124, v124
	v_exp_f32_e32 v125, v125
	v_exp_f32_e32 v126, v126
	v_exp_f32_e32 v127, v127
	s_waitcnt lgkmcnt(0)
	v_mfma_f32_32x32x16_bf16 v[144:159], v[186:189], v[168:171], v[144:159]
	v_add_f32_e64 v122, v230, v122
	v_add_f32_e64 v123, v231, v123
	v_add_f32_e64 v120, v228, v120
	v_add_f32_e64 v121, v229, v121
	v_exp_f32_e32 v182, v96
	v_exp_f32_e32 v183, v97
	v_exp_f32_e32 v184, v98
	v_exp_f32_e32 v185, v99
	v_cvt_pk_bf16_f32 v96, v228, v229
	v_cvt_pk_bf16_f32 v97, v230, v231
	v_cvt_pk_bf16_f32 v98, v124, v125
	v_cvt_pk_bf16_f32 v99, v126, v127
	v_pk_add_f32 v[122:123], v[126:127], v[122:123]
	v_pk_add_f32 v[120:121], v[124:125], v[120:121]
	v_mfma_f32_32x32x16_bf16 v[128:143], v[216:219], v[168:171], v[128:143]
	v_exp_f32_e32 v124, v100
	v_exp_f32_e32 v125, v101
	v_exp_f32_e32 v126, v102
	v_exp_f32_e32 v127, v103
	v_mfma_f32_32x32x16_bf16 v[144:159], v[116:119], v[172:175], v[144:159]
	v_exp_f32_e32 v186, v104
	v_exp_f32_e32 v187, v105
	v_exp_f32_e32 v188, v106
	v_exp_f32_e32 v189, v107
	v_pk_add_f32 v[106:107], v[184:185], v[122:123]
	v_pk_add_f32 v[104:105], v[182:183], v[120:121]
	v_cvt_pk_bf16_f32 v100, v182, v183
	v_cvt_pk_bf16_f32 v101, v184, v185
	v_cvt_pk_bf16_f32 v102, v124, v125
	v_cvt_pk_bf16_f32 v103, v126, v127
	v_pk_add_f32 v[118:119], v[126:127], v[106:107]
	v_pk_add_f32 v[116:117], v[124:125], v[104:105]
	v_mfma_f32_32x32x16_bf16 v[128:143], v[176:179], v[172:175], v[128:143]
	v_exp_f32_e32 v120, v108
	v_exp_f32_e32 v121, v109
	v_exp_f32_e32 v122, v110
	v_exp_f32_e32 v123, v111
	v_pk_add_f32 v[110:111], v[188:189], v[118:119]
	v_pk_add_f32 v[108:109], v[186:187], v[116:117]
	v_cvt_pk_bf16_f32 v104, v186, v187
	v_cvt_pk_bf16_f32 v105, v188, v189
	v_cvt_pk_bf16_f32 v106, v120, v121
	v_cvt_pk_bf16_f32 v107, v122, v123
	v_pk_add_f32 v[178:179], v[122:123], v[110:111]
	v_pk_add_f32 v[176:177], v[120:121], v[108:109]
	s_waitcnt vmcnt(4) lgkmcnt(0)
	s_barrier
	ds_read_b128 v[108:111], v236 offset:32768
	ds_read_b128 v[116:119], v236 offset:36864
	ds_read_b128 v[120:123], v236 offset:40960
	ds_read_b128 v[124:127], v236 offset:45056
	s_add_u32 s70, s98, 0x18000
	s_addc_u32 s71, s99, 0
	s_add_i32 s68, 0x4000, s57
	s_mov_b32 m0, s68
	s_nop 0
	global_load_lds_dwordx4 v198, s[70:71]
	s_add_i32 m0, s68, 0x400
	s_nop 0
	global_load_lds_dwordx4 v194, s[70:71]
	s_add_u32 s2, s100, 0x80
	s_addc_u32 s3, s101, 0
	s_add_i32 s49, s58, 0x8000
	s_add_i32 m0, s49, 0xc000
	s_nop 0
	global_load_lds_dwordx4 v196, s[2:3]
	s_add_i32 m0, s49, 0xc400
	s_nop 0
	global_load_lds_dwordx4 v192, s[2:3]
	s_waitcnt lgkmcnt(0)
	v_mfma_f32_32x32x16_bf16 v[80:95], v[108:111], v[112:115], v[80:95]
	ds_read_b128 v[108:111], v237 offset:32768
	v_mfma_f32_32x32x16_bf16 v[64:79], v[116:119], v[112:115], v[64:79]
	ds_read_b128 v[116:119], v237 offset:36864
	v_mfma_f32_32x32x16_bf16 v[16:31], v[120:123], v[112:115], v[16:31]
	ds_read_b128 v[120:123], v237 offset:40960
	v_mfma_f32_32x32x16_bf16 v[0:15], v[124:127], v[112:115], v[0:15]
	ds_read_b128 v[112:115], v237 offset:45056
	s_waitcnt lgkmcnt(0)
	v_mfma_f32_32x32x16_bf16 v[80:95], v[108:111], v[96:99], v[80:95]
	ds_read_b128 v[108:111], v238 offset:32768
	v_mfma_f32_32x32x16_bf16 v[64:79], v[116:119], v[96:99], v[64:79]
	ds_read_b128 v[116:119], v238 offset:36864
	v_mfma_f32_32x32x16_bf16 v[16:31], v[120:123], v[96:99], v[16:31]
	ds_read_b128 v[120:123], v238 offset:40960
	v_mfma_f32_32x32x16_bf16 v[0:15], v[112:115], v[96:99], v[0:15]
	ds_read_b128 v[96:99], v238 offset:45056
	s_waitcnt lgkmcnt(0)
	v_mfma_f32_32x32x16_bf16 v[80:95], v[108:111], v[100:103], v[80:95]
	ds_read_b128 v[108:111], v239 offset:32768
	v_mfma_f32_32x32x16_bf16 v[64:79], v[116:119], v[100:103], v[64:79]
	ds_read_b128 v[112:115], v239 offset:36864
	v_mfma_f32_32x32x16_bf16 v[16:31], v[120:123], v[100:103], v[16:31]
	ds_read_b128 v[116:119], v239 offset:40960
	v_mfma_f32_32x32x16_bf16 v[0:15], v[96:99], v[100:103], v[0:15]
	ds_read_b128 v[120:123], v239 offset:45056
	s_waitcnt lgkmcnt(0)
	v_mfma_f32_32x32x16_bf16 v[80:95], v[108:111], v[104:107], v[80:95]
	ds_read_b128 v[96:99], v205 offset:32768
	v_mfma_f32_32x32x16_bf16 v[64:79], v[112:115], v[104:107], v[64:79]
	ds_read_b128 v[100:103], v205 offset:40960
	v_mfma_f32_32x32x16_bf16 v[16:31], v[116:119], v[104:107], v[16:31]
	ds_read_b128 v[182:185], v211 offset:32768
	v_mfma_f32_32x32x16_bf16 v[0:15], v[120:123], v[104:107], v[0:15]
	ds_read_b128 v[186:189], v211 offset:40960
	s_waitcnt lgkmcnt(0)
	v_mfma_f32_32x32x16_bf16 v[112:127], v[96:99], v[160:163], 0
	ds_read_b128 v[216:219], v212 offset:32768
	v_exp_f32_e32 v224, v144
	v_exp_f32_e32 v225, v145
	v_exp_f32_e32 v226, v146
	v_exp_f32_e32 v227, v147
	ds_read_b128 v[220:223], v212 offset:40960
	v_mfma_f32_32x32x16_bf16 v[96:111], v[100:103], v[160:163], 0
	v_exp_f32_e32 v228, v148
	v_exp_f32_e32 v229, v149
	v_exp_f32_e32 v230, v150
	v_exp_f32_e32 v231, v151
	v_mfma_f32_32x32x16_bf16 v[112:127], v[182:185], v[164:167], v[112:127]
	ds_read_b128 v[148:151], v213 offset:32768
	v_exp_f32_e32 v232, v152
	v_exp_f32_e32 v233, v153
	v_exp_f32_e32 v234, v154
	v_exp_f32_e32 v235, v155
	v_cvt_pk_bf16_f32 v144, v224, v225
	v_cvt_pk_bf16_f32 v145, v226, v227
	v_cvt_pk_bf16_f32 v146, v228, v229
	v_cvt_pk_bf16_f32 v147, v230, v231
	v_pk_add_f32 v[154:155], v[230:231], v[226:227]
	v_pk_add_f32 v[152:153], v[228:229], v[224:225]
	v_mfma_f32_32x32x16_bf16 v[96:111], v[186:189], v[164:167], v[96:111]
	ds_read_b128 v[182:185], v213 offset:40960
	v_exp_f32_e32 v156, v156
	v_exp_f32_e32 v157, v157
	v_exp_f32_e32 v158, v158
	v_exp_f32_e32 v159, v159
	s_waitcnt lgkmcnt(0)
	v_mfma_f32_32x32x16_bf16 v[112:127], v[216:219], v[168:171], v[112:127]
	v_add_f32_e64 v154, v234, v154
	v_add_f32_e64 v155, v235, v155
	v_add_f32_e64 v152, v232, v152
	v_add_f32_e64 v153, v233, v153
	v_exp_f32_e32 v186, v128
	v_exp_f32_e32 v187, v129
	v_exp_f32_e32 v188, v130
	v_exp_f32_e32 v189, v131
	v_cvt_pk_bf16_f32 v128, v232, v233
	v_cvt_pk_bf16_f32 v129, v234, v235
	v_cvt_pk_bf16_f32 v130, v156, v157
	v_cvt_pk_bf16_f32 v131, v158, v159
	v_pk_add_f32 v[154:155], v[158:159], v[154:155]
	v_pk_add_f32 v[152:153], v[156:157], v[152:153]
	v_mfma_f32_32x32x16_bf16 v[96:111], v[220:223], v[168:171], v[96:111]
	v_exp_f32_e32 v156, v132
	v_exp_f32_e32 v157, v133
	v_exp_f32_e32 v158, v134
	v_exp_f32_e32 v159, v135
	v_mfma_f32_32x32x16_bf16 v[112:127], v[148:151], v[172:175], v[112:127]
	v_exp_f32_e32 v216, v136
	v_exp_f32_e32 v217, v137
	v_exp_f32_e32 v218, v138
	v_exp_f32_e32 v219, v139
	v_pk_add_f32 v[138:139], v[188:189], v[154:155]
	v_pk_add_f32 v[136:137], v[186:187], v[152:153]
	v_cvt_pk_bf16_f32 v132, v186, v187
	v_cvt_pk_bf16_f32 v133, v188, v189
	v_cvt_pk_bf16_f32 v134, v156, v157
	v_cvt_pk_bf16_f32 v135, v158, v159
	v_pk_add_f32 v[150:151], v[158:159], v[138:139]
	v_pk_add_f32 v[148:149], v[156:157], v[136:137]
	v_mfma_f32_32x32x16_bf16 v[96:111], v[182:185], v[172:175], v[96:111]
	v_exp_f32_e32 v152, v140
	v_exp_f32_e32 v153, v141
	v_exp_f32_e32 v154, v142
	v_exp_f32_e32 v155, v143
	v_pk_add_f32 v[142:143], v[218:219], v[150:151]
	v_pk_add_f32 v[140:141], v[216:217], v[148:149]
	v_cvt_pk_bf16_f32 v136, v216, v217
	v_cvt_pk_bf16_f32 v137, v218, v219
	v_cvt_pk_bf16_f32 v138, v152, v153
	v_cvt_pk_bf16_f32 v139, v154, v155
	v_pk_add_f32 v[142:143], v[154:155], v[142:143]
	v_pk_add_f32 v[140:141], v[152:153], v[140:141]
	s_waitcnt vmcnt(4) lgkmcnt(0)
	v_add_f32_e32 v148, v176, v177
	v_add_f32_e32 v149, v178, v179
	v_add_f32_e32 v148, v148, v149
	v_add_f32_e32 v140, v140, v141
	v_add_f32_e32 v141, v142, v143
	s_barrier
	v_add_f32_e32 v148, v180, v148
	v_add_f32_e32 v140, v140, v141
	v_add_f32_e32 v180, v148, v140
	ds_read_b128 v[140:143], v206 offset:49152
	ds_read_b128 v[148:151], v206 offset:53248
	ds_read_b128 v[152:155], v206 offset:57344
	ds_read_b128 v[156:159], v206 offset:61440
	s_add_u32 s98, s98, 0x30000
	s_addc_u32 s99, s99, 0
	s_add_u32 s100, s100, 0x100
	s_addc_u32 s101, s101, 0
	s_add_i32 s49, s58, 0x8000
	s_mov_b32 m0, s49
	s_nop 0
	global_load_lds_dwordx4 v198, s[98:99]
	s_add_i32 m0, s49, 0x400
	s_nop 0
	global_load_lds_dwordx4 v194, s[98:99]
	s_add_i32 s49, s58, 0xc000
	s_add_i32 m0, s49, 0xc000
	s_nop 0
	global_load_lds_dwordx4 v196, s[100:101]
	s_add_i32 m0, s49, 0xc400
	s_nop 0
	global_load_lds_dwordx4 v192, s[100:101]
	s_waitcnt lgkmcnt(0)
	v_mfma_f32_32x32x16_bf16 v[80:95], v[140:143], v[144:147], v[80:95]
	ds_read_b128 v[140:143], v207 offset:49152
	v_mfma_f32_32x32x16_bf16 v[64:79], v[148:151], v[144:147], v[64:79]
	ds_read_b128 v[148:151], v207 offset:53248
	v_mfma_f32_32x32x16_bf16 v[16:31], v[152:155], v[144:147], v[16:31]
	ds_read_b128 v[152:155], v207 offset:57344
	v_mfma_f32_32x32x16_bf16 v[0:15], v[156:159], v[144:147], v[0:15]
	ds_read_b128 v[144:147], v207 offset:61440
	s_waitcnt lgkmcnt(0)
	v_mfma_f32_32x32x16_bf16 v[80:95], v[140:143], v[128:131], v[80:95]
	ds_read_b128 v[140:143], v208 offset:49152
	v_mfma_f32_32x32x16_bf16 v[64:79], v[148:151], v[128:131], v[64:79]
	ds_read_b128 v[148:151], v208 offset:53248
	v_mfma_f32_32x32x16_bf16 v[16:31], v[152:155], v[128:131], v[16:31]
	ds_read_b128 v[152:155], v208 offset:57344
	v_mfma_f32_32x32x16_bf16 v[0:15], v[144:147], v[128:131], v[0:15]
	ds_read_b128 v[128:131], v208 offset:61440
	s_waitcnt lgkmcnt(0)
	v_mfma_f32_32x32x16_bf16 v[80:95], v[140:143], v[132:135], v[80:95]
	ds_read_b128 v[140:143], v209 offset:49152
	v_mfma_f32_32x32x16_bf16 v[64:79], v[148:151], v[132:135], v[64:79]
	ds_read_b128 v[144:147], v209 offset:53248
	v_mfma_f32_32x32x16_bf16 v[16:31], v[152:155], v[132:135], v[16:31]
	ds_read_b128 v[148:151], v209 offset:57344
	v_mfma_f32_32x32x16_bf16 v[0:15], v[128:131], v[132:135], v[0:15]
	ds_read_b128 v[128:131], v209 offset:61440
	s_waitcnt lgkmcnt(0)
	v_mfma_f32_32x32x16_bf16 v[80:95], v[140:143], v[136:139], v[80:95]
	ds_read_b128 v[132:135], v205
	v_mfma_f32_32x32x16_bf16 v[64:79], v[144:147], v[136:139], v[64:79]
	ds_read_b128 v[140:143], v205 offset:8192
	v_mfma_f32_32x32x16_bf16 v[16:31], v[148:151], v[136:139], v[16:31]
	ds_read_b128 v[176:179], v211
	v_mfma_f32_32x32x16_bf16 v[0:15], v[128:131], v[136:139], v[0:15]
	ds_read_b128 v[182:185], v211 offset:8192
	s_waitcnt lgkmcnt(0)
	v_mfma_f32_32x32x16_bf16 v[144:159], v[132:135], v[160:163], 0
	ds_read_b128 v[186:189], v212
	v_exp_f32_e32 v220, v112
	v_exp_f32_e32 v221, v113
	v_exp_f32_e32 v222, v114
	v_exp_f32_e32 v223, v115
	v_mfma_f32_32x32x16_bf16 v[128:143], v[140:143], v[160:163], 0
	ds_read_b128 v[216:219], v212 offset:8192
	v_exp_f32_e32 v224, v116
	v_exp_f32_e32 v225, v117
	v_exp_f32_e32 v226, v118
	v_exp_f32_e32 v227, v119
	v_mfma_f32_32x32x16_bf16 v[144:159], v[176:179], v[164:167], v[144:159]
	ds_read_b128 v[116:119], v213
	v_exp_f32_e32 v228, v120
	v_exp_f32_e32 v229, v121
	v_exp_f32_e32 v230, v122
	v_exp_f32_e32 v231, v123
	v_cvt_pk_bf16_f32 v112, v220, v221
	v_cvt_pk_bf16_f32 v113, v222, v223
	v_cvt_pk_bf16_f32 v114, v224, v225
	v_cvt_pk_bf16_f32 v115, v226, v227
	v_pk_add_f32 v[122:123], v[226:227], v[222:223]
	v_pk_add_f32 v[120:121], v[224:225], v[220:221]
	v_mfma_f32_32x32x16_bf16 v[128:143], v[182:185], v[164:167], v[128:143]
	ds_read_b128 v[176:179], v213 offset:8192
	v_exp_f32_e32 v124, v124
	v_exp_f32_e32 v125, v125
	v_exp_f32_e32 v126, v126
	v_exp_f32_e32 v127, v127
	s_waitcnt lgkmcnt(0)
	v_mfma_f32_32x32x16_bf16 v[144:159], v[186:189], v[168:171], v[144:159]
	v_add_f32_e64 v122, v230, v122
	v_add_f32_e64 v123, v231, v123
	v_add_f32_e64 v120, v228, v120
	v_add_f32_e64 v121, v229, v121
	v_exp_f32_e32 v182, v96
	v_exp_f32_e32 v183, v97
	v_exp_f32_e32 v184, v98
	v_exp_f32_e32 v185, v99
	v_cvt_pk_bf16_f32 v96, v228, v229
	v_cvt_pk_bf16_f32 v97, v230, v231
	v_cvt_pk_bf16_f32 v98, v124, v125
	v_cvt_pk_bf16_f32 v99, v126, v127
	v_pk_add_f32 v[122:123], v[126:127], v[122:123]
	v_pk_add_f32 v[120:121], v[124:125], v[120:121]
	v_mfma_f32_32x32x16_bf16 v[128:143], v[216:219], v[168:171], v[128:143]
	v_exp_f32_e32 v124, v100
	v_exp_f32_e32 v125, v101
	v_exp_f32_e32 v126, v102
	v_exp_f32_e32 v127, v103
	v_mfma_f32_32x32x16_bf16 v[144:159], v[116:119], v[172:175], v[144:159]
	v_exp_f32_e32 v186, v104
	v_exp_f32_e32 v187, v105
	v_exp_f32_e32 v188, v106
	v_exp_f32_e32 v189, v107
	v_pk_add_f32 v[106:107], v[184:185], v[122:123]
	v_pk_add_f32 v[104:105], v[182:183], v[120:121]
	v_cvt_pk_bf16_f32 v100, v182, v183
	v_cvt_pk_bf16_f32 v101, v184, v185
	v_cvt_pk_bf16_f32 v102, v124, v125
	v_cvt_pk_bf16_f32 v103, v126, v127
	v_pk_add_f32 v[118:119], v[126:127], v[106:107]
	v_pk_add_f32 v[116:117], v[124:125], v[104:105]
	v_mfma_f32_32x32x16_bf16 v[128:143], v[176:179], v[172:175], v[128:143]
	v_exp_f32_e32 v120, v108
	v_exp_f32_e32 v121, v109
	v_exp_f32_e32 v122, v110
	v_exp_f32_e32 v123, v111
	v_pk_add_f32 v[110:111], v[188:189], v[118:119]
	v_pk_add_f32 v[108:109], v[186:187], v[116:117]
	v_cvt_pk_bf16_f32 v104, v186, v187
	v_cvt_pk_bf16_f32 v105, v188, v189
	v_cvt_pk_bf16_f32 v106, v120, v121
	v_cvt_pk_bf16_f32 v107, v122, v123
	v_pk_add_f32 v[178:179], v[122:123], v[110:111]
	v_pk_add_f32 v[176:177], v[120:121], v[108:109]
	s_waitcnt vmcnt(4) lgkmcnt(0)
	s_barrier
	ds_read_b128 v[108:111], v236
	ds_read_b128 v[116:119], v236 offset:4096
	ds_read_b128 v[120:123], v236 offset:8192
	ds_read_b128 v[124:127], v236 offset:12288
	s_add_u32 s70, s98, 0x18000
	s_addc_u32 s71, s99, 0
	s_add_i32 s68, 0, s57
	s_mov_b32 m0, s68
	s_nop 0
	global_load_lds_dwordx4 v198, s[70:71]
	s_add_i32 m0, s68, 0x400
	s_nop 0
	global_load_lds_dwordx4 v194, s[70:71]
	s_add_u32 s2, s100, 0x80
	s_addc_u32 s3, s101, 0
	s_add_i32 s49, s58, 0
	s_add_i32 m0, s49, 0xc000
	s_nop 0
	global_load_lds_dwordx4 v196, s[2:3]
	s_add_i32 m0, s49, 0xc400
	s_nop 0
	global_load_lds_dwordx4 v192, s[2:3]
	s_waitcnt lgkmcnt(0)
	v_mfma_f32_32x32x16_bf16 v[80:95], v[108:111], v[112:115], v[80:95]
	ds_read_b128 v[108:111], v237
	v_mfma_f32_32x32x16_bf16 v[64:79], v[116:119], v[112:115], v[64:79]
	ds_read_b128 v[116:119], v237 offset:4096
	v_mfma_f32_32x32x16_bf16 v[16:31], v[120:123], v[112:115], v[16:31]
	ds_read_b128 v[120:123], v237 offset:8192
	v_mfma_f32_32x32x16_bf16 v[0:15], v[124:127], v[112:115], v[0:15]
	ds_read_b128 v[112:115], v237 offset:12288
	s_waitcnt lgkmcnt(0)
	v_mfma_f32_32x32x16_bf16 v[80:95], v[108:111], v[96:99], v[80:95]
	ds_read_b128 v[108:111], v238
	v_mfma_f32_32x32x16_bf16 v[64:79], v[116:119], v[96:99], v[64:79]
	ds_read_b128 v[116:119], v238 offset:4096
	v_mfma_f32_32x32x16_bf16 v[16:31], v[120:123], v[96:99], v[16:31]
	ds_read_b128 v[120:123], v238 offset:8192
	v_mfma_f32_32x32x16_bf16 v[0:15], v[112:115], v[96:99], v[0:15]
	ds_read_b128 v[96:99], v238 offset:12288
	s_waitcnt lgkmcnt(0)
	v_mfma_f32_32x32x16_bf16 v[80:95], v[108:111], v[100:103], v[80:95]
	ds_read_b128 v[108:111], v239
	v_mfma_f32_32x32x16_bf16 v[64:79], v[116:119], v[100:103], v[64:79]
	ds_read_b128 v[112:115], v239 offset:4096
	v_mfma_f32_32x32x16_bf16 v[16:31], v[120:123], v[100:103], v[16:31]
	ds_read_b128 v[116:119], v239 offset:8192
	v_mfma_f32_32x32x16_bf16 v[0:15], v[96:99], v[100:103], v[0:15]
	ds_read_b128 v[120:123], v239 offset:12288
	s_waitcnt lgkmcnt(0)
	v_mfma_f32_32x32x16_bf16 v[80:95], v[108:111], v[104:107], v[80:95]
	ds_read_b128 v[96:99], v205 offset:16384
	v_mfma_f32_32x32x16_bf16 v[64:79], v[112:115], v[104:107], v[64:79]
	ds_read_b128 v[100:103], v205 offset:24576
	v_mfma_f32_32x32x16_bf16 v[16:31], v[116:119], v[104:107], v[16:31]
	ds_read_b128 v[182:185], v211 offset:16384
	v_mfma_f32_32x32x16_bf16 v[0:15], v[120:123], v[104:107], v[0:15]
	ds_read_b128 v[186:189], v211 offset:24576
	s_waitcnt lgkmcnt(0)
	v_mfma_f32_32x32x16_bf16 v[112:127], v[96:99], v[160:163], 0
	ds_read_b128 v[216:219], v212 offset:16384
	v_exp_f32_e32 v224, v144
	v_exp_f32_e32 v225, v145
	v_exp_f32_e32 v226, v146
	v_exp_f32_e32 v227, v147
	ds_read_b128 v[220:223], v212 offset:24576
	v_mfma_f32_32x32x16_bf16 v[96:111], v[100:103], v[160:163], 0
	v_exp_f32_e32 v228, v148
	v_exp_f32_e32 v229, v149
	v_exp_f32_e32 v230, v150
	v_exp_f32_e32 v231, v151
	v_mfma_f32_32x32x16_bf16 v[112:127], v[182:185], v[164:167], v[112:127]
	ds_read_b128 v[148:151], v213 offset:16384
	v_exp_f32_e32 v232, v152
	v_exp_f32_e32 v233, v153
	v_exp_f32_e32 v234, v154
	v_exp_f32_e32 v235, v155
	v_cvt_pk_bf16_f32 v144, v224, v225
	v_cvt_pk_bf16_f32 v145, v226, v227
	v_cvt_pk_bf16_f32 v146, v228, v229
	v_cvt_pk_bf16_f32 v147, v230, v231
	v_pk_add_f32 v[154:155], v[230:231], v[226:227]
	v_pk_add_f32 v[152:153], v[228:229], v[224:225]
	v_mfma_f32_32x32x16_bf16 v[96:111], v[186:189], v[164:167], v[96:111]
	ds_read_b128 v[182:185], v213 offset:24576
	v_exp_f32_e32 v156, v156
	v_exp_f32_e32 v157, v157
	v_exp_f32_e32 v158, v158
	v_exp_f32_e32 v159, v159
	s_waitcnt lgkmcnt(0)
	v_mfma_f32_32x32x16_bf16 v[112:127], v[216:219], v[168:171], v[112:127]
	v_add_f32_e64 v154, v234, v154
	v_add_f32_e64 v155, v235, v155
	v_add_f32_e64 v152, v232, v152
	v_add_f32_e64 v153, v233, v153
	v_exp_f32_e32 v186, v128
	v_exp_f32_e32 v187, v129
	v_exp_f32_e32 v188, v130
	v_exp_f32_e32 v189, v131
	v_cvt_pk_bf16_f32 v128, v232, v233
	v_cvt_pk_bf16_f32 v129, v234, v235
	v_cvt_pk_bf16_f32 v130, v156, v157
	v_cvt_pk_bf16_f32 v131, v158, v159
	v_pk_add_f32 v[154:155], v[158:159], v[154:155]
	v_pk_add_f32 v[152:153], v[156:157], v[152:153]
	v_mfma_f32_32x32x16_bf16 v[96:111], v[220:223], v[168:171], v[96:111]
	v_exp_f32_e32 v156, v132
	v_exp_f32_e32 v157, v133
	v_exp_f32_e32 v158, v134
	v_exp_f32_e32 v159, v135
	v_mfma_f32_32x32x16_bf16 v[112:127], v[148:151], v[172:175], v[112:127]
	v_exp_f32_e32 v216, v136
	v_exp_f32_e32 v217, v137
	v_exp_f32_e32 v218, v138
	v_exp_f32_e32 v219, v139
	v_pk_add_f32 v[138:139], v[188:189], v[154:155]
	v_pk_add_f32 v[136:137], v[186:187], v[152:153]
	v_cvt_pk_bf16_f32 v132, v186, v187
	v_cvt_pk_bf16_f32 v133, v188, v189
	v_cvt_pk_bf16_f32 v134, v156, v157
	v_cvt_pk_bf16_f32 v135, v158, v159
	v_pk_add_f32 v[150:151], v[158:159], v[138:139]
	v_pk_add_f32 v[148:149], v[156:157], v[136:137]
	v_mfma_f32_32x32x16_bf16 v[96:111], v[182:185], v[172:175], v[96:111]
	v_exp_f32_e32 v152, v140
	v_exp_f32_e32 v153, v141
	v_exp_f32_e32 v154, v142
	v_exp_f32_e32 v155, v143
	v_pk_add_f32 v[142:143], v[218:219], v[150:151]
	v_pk_add_f32 v[140:141], v[216:217], v[148:149]
	v_cvt_pk_bf16_f32 v136, v216, v217
	v_cvt_pk_bf16_f32 v137, v218, v219
	v_cvt_pk_bf16_f32 v138, v152, v153
	v_cvt_pk_bf16_f32 v139, v154, v155
	v_pk_add_f32 v[142:143], v[154:155], v[142:143]
	v_pk_add_f32 v[140:141], v[152:153], v[140:141]
	s_waitcnt vmcnt(4) lgkmcnt(0)
	v_add_f32_e32 v148, v176, v177
	v_add_f32_e32 v149, v178, v179
	v_add_f32_e32 v148, v148, v149
	v_add_f32_e32 v140, v140, v141
	v_add_f32_e32 v141, v142, v143
	s_barrier
	v_add_f32_e32 v148, v180, v148
	v_add_f32_e32 v140, v140, v141
	v_add_f32_e32 v180, v148, v140
	ds_read_b128 v[140:143], v236 offset:16384
	ds_read_b128 v[148:151], v236 offset:20480
	ds_read_b128 v[152:155], v236 offset:24576
	ds_read_b128 v[156:159], v236 offset:28672
	s_add_u32 s98, s98, 0x30000
	s_addc_u32 s99, s99, 0
	s_add_u32 s100, s100, 0x100
	s_addc_u32 s101, s101, 0
	s_add_i32 s49, s58, 0x4000
	s_mov_b32 m0, s49
	s_nop 0
	global_load_lds_dwordx4 v198, s[98:99]
	s_add_i32 m0, s49, 0x400
	s_nop 0
	global_load_lds_dwordx4 v194, s[98:99]
	s_add_i32 s49, s58, 0x4000
	s_add_i32 m0, s49, 0xc000
	s_nop 0
	global_load_lds_dwordx4 v196, s[100:101]
	s_add_i32 m0, s49, 0xc400
	s_nop 0
	global_load_lds_dwordx4 v192, s[100:101]
	s_waitcnt lgkmcnt(0)
	v_mfma_f32_32x32x16_bf16 v[80:95], v[140:143], v[144:147], v[80:95]
	ds_read_b128 v[140:143], v237 offset:16384
	v_mfma_f32_32x32x16_bf16 v[64:79], v[148:151], v[144:147], v[64:79]
	ds_read_b128 v[148:151], v237 offset:20480
	v_mfma_f32_32x32x16_bf16 v[16:31], v[152:155], v[144:147], v[16:31]
	ds_read_b128 v[152:155], v237 offset:24576
	v_mfma_f32_32x32x16_bf16 v[0:15], v[156:159], v[144:147], v[0:15]
	ds_read_b128 v[144:147], v237 offset:28672
	s_waitcnt lgkmcnt(0)
	v_mfma_f32_32x32x16_bf16 v[80:95], v[140:143], v[128:131], v[80:95]
	ds_read_b128 v[140:143], v238 offset:16384
	v_mfma_f32_32x32x16_bf16 v[64:79], v[148:151], v[128:131], v[64:79]
	ds_read_b128 v[148:151], v238 offset:20480
	v_mfma_f32_32x32x16_bf16 v[16:31], v[152:155], v[128:131], v[16:31]
	ds_read_b128 v[152:155], v238 offset:24576
	v_mfma_f32_32x32x16_bf16 v[0:15], v[144:147], v[128:131], v[0:15]
	ds_read_b128 v[128:131], v238 offset:28672
	s_waitcnt lgkmcnt(0)
	v_mfma_f32_32x32x16_bf16 v[80:95], v[140:143], v[132:135], v[80:95]
	ds_read_b128 v[140:143], v239 offset:16384
	v_mfma_f32_32x32x16_bf16 v[64:79], v[148:151], v[132:135], v[64:79]
	ds_read_b128 v[144:147], v239 offset:20480
	v_mfma_f32_32x32x16_bf16 v[16:31], v[152:155], v[132:135], v[16:31]
	ds_read_b128 v[148:151], v239 offset:24576
	v_mfma_f32_32x32x16_bf16 v[0:15], v[128:131], v[132:135], v[0:15]
	ds_read_b128 v[128:131], v239 offset:28672
	s_waitcnt lgkmcnt(0)
	v_mfma_f32_32x32x16_bf16 v[80:95], v[140:143], v[136:139], v[80:95]
	ds_read_b128 v[132:135], v205 offset:32768
	v_mfma_f32_32x32x16_bf16 v[64:79], v[144:147], v[136:139], v[64:79]
	ds_read_b128 v[140:143], v205 offset:40960
	v_mfma_f32_32x32x16_bf16 v[16:31], v[148:151], v[136:139], v[16:31]
	ds_read_b128 v[176:179], v211 offset:32768
	v_mfma_f32_32x32x16_bf16 v[0:15], v[128:131], v[136:139], v[0:15]
	ds_read_b128 v[182:185], v211 offset:40960
	s_waitcnt lgkmcnt(0)
	v_mfma_f32_32x32x16_bf16 v[144:159], v[132:135], v[160:163], 0
	ds_read_b128 v[186:189], v212 offset:32768
	v_exp_f32_e32 v220, v112
	v_exp_f32_e32 v221, v113
	v_exp_f32_e32 v222, v114
	v_exp_f32_e32 v223, v115
	v_mfma_f32_32x32x16_bf16 v[128:143], v[140:143], v[160:163], 0
	ds_read_b128 v[216:219], v212 offset:40960
	v_exp_f32_e32 v224, v116
	v_exp_f32_e32 v225, v117
	v_exp_f32_e32 v226, v118
	v_exp_f32_e32 v227, v119
	v_mfma_f32_32x32x16_bf16 v[144:159], v[176:179], v[164:167], v[144:159]
	ds_read_b128 v[116:119], v213 offset:32768
	v_exp_f32_e32 v228, v120
	v_exp_f32_e32 v229, v121
	v_exp_f32_e32 v230, v122
	v_exp_f32_e32 v231, v123
	v_cvt_pk_bf16_f32 v112, v220, v221
	v_cvt_pk_bf16_f32 v113, v222, v223
	v_cvt_pk_bf16_f32 v114, v224, v225
	v_cvt_pk_bf16_f32 v115, v226, v227
	v_pk_add_f32 v[122:123], v[226:227], v[222:223]
	v_pk_add_f32 v[120:121], v[224:225], v[220:221]
	v_mfma_f32_32x32x16_bf16 v[128:143], v[182:185], v[164:167], v[128:143]
	ds_read_b128 v[176:179], v213 offset:40960
	v_exp_f32_e32 v124, v124
	v_exp_f32_e32 v125, v125
	v_exp_f32_e32 v126, v126
	v_exp_f32_e32 v127, v127
	s_waitcnt lgkmcnt(0)
	v_mfma_f32_32x32x16_bf16 v[144:159], v[186:189], v[168:171], v[144:159]
	v_add_f32_e64 v122, v230, v122
	v_add_f32_e64 v123, v231, v123
	v_add_f32_e64 v120, v228, v120
	v_add_f32_e64 v121, v229, v121
	v_exp_f32_e32 v182, v96
	v_exp_f32_e32 v183, v97
	v_exp_f32_e32 v184, v98
	v_exp_f32_e32 v185, v99
	v_cvt_pk_bf16_f32 v96, v228, v229
	v_cvt_pk_bf16_f32 v97, v230, v231
	v_cvt_pk_bf16_f32 v98, v124, v125
	v_cvt_pk_bf16_f32 v99, v126, v127
	v_pk_add_f32 v[122:123], v[126:127], v[122:123]
	v_pk_add_f32 v[120:121], v[124:125], v[120:121]
	v_mfma_f32_32x32x16_bf16 v[128:143], v[216:219], v[168:171], v[128:143]
	v_exp_f32_e32 v124, v100
	v_exp_f32_e32 v125, v101
	v_exp_f32_e32 v126, v102
	v_exp_f32_e32 v127, v103
	v_mfma_f32_32x32x16_bf16 v[144:159], v[116:119], v[172:175], v[144:159]
	v_exp_f32_e32 v186, v104
	v_exp_f32_e32 v187, v105
	v_exp_f32_e32 v188, v106
	v_exp_f32_e32 v189, v107
	v_pk_add_f32 v[106:107], v[184:185], v[122:123]
	v_pk_add_f32 v[104:105], v[182:183], v[120:121]
	v_cvt_pk_bf16_f32 v100, v182, v183
	v_cvt_pk_bf16_f32 v101, v184, v185
	v_cvt_pk_bf16_f32 v102, v124, v125
	v_cvt_pk_bf16_f32 v103, v126, v127
	v_pk_add_f32 v[118:119], v[126:127], v[106:107]
	v_pk_add_f32 v[116:117], v[124:125], v[104:105]
	v_mfma_f32_32x32x16_bf16 v[128:143], v[176:179], v[172:175], v[128:143]
	v_exp_f32_e32 v120, v108
	v_exp_f32_e32 v121, v109
	v_exp_f32_e32 v122, v110
	v_exp_f32_e32 v123, v111
	v_pk_add_f32 v[110:111], v[188:189], v[118:119]
	v_pk_add_f32 v[108:109], v[186:187], v[116:117]
	v_cvt_pk_bf16_f32 v104, v186, v187
	v_cvt_pk_bf16_f32 v105, v188, v189
	v_cvt_pk_bf16_f32 v106, v120, v121
	v_cvt_pk_bf16_f32 v107, v122, v123
	v_pk_add_f32 v[178:179], v[122:123], v[110:111]
	v_pk_add_f32 v[176:177], v[120:121], v[108:109]
	s_waitcnt vmcnt(4) lgkmcnt(0)
	s_barrier
	ds_read_b128 v[108:111], v236 offset:32768
	ds_read_b128 v[116:119], v236 offset:36864
	ds_read_b128 v[120:123], v236 offset:40960
	ds_read_b128 v[124:127], v236 offset:45056
	s_add_u32 s70, s98, 0x18000
	s_addc_u32 s71, s99, 0
	s_add_i32 s68, 0x8000, s57
	s_mov_b32 m0, s68
	s_nop 0
	global_load_lds_dwordx4 v198, s[70:71]
	s_add_i32 m0, s68, 0x400
	s_nop 0
	global_load_lds_dwordx4 v194, s[70:71]
	s_add_u32 s2, s100, 0x80
	s_addc_u32 s3, s101, 0
	s_add_i32 s49, s58, 0x8000
	s_add_i32 m0, s49, 0xc000
	s_nop 0
	global_load_lds_dwordx4 v196, s[2:3]
	s_add_i32 m0, s49, 0xc400
	s_nop 0
	global_load_lds_dwordx4 v192, s[2:3]
	s_waitcnt lgkmcnt(0)
	v_mfma_f32_32x32x16_bf16 v[80:95], v[108:111], v[112:115], v[80:95]
	ds_read_b128 v[108:111], v237 offset:32768
	v_mfma_f32_32x32x16_bf16 v[64:79], v[116:119], v[112:115], v[64:79]
	ds_read_b128 v[116:119], v237 offset:36864
	v_mfma_f32_32x32x16_bf16 v[16:31], v[120:123], v[112:115], v[16:31]
	ds_read_b128 v[120:123], v237 offset:40960
	v_mfma_f32_32x32x16_bf16 v[0:15], v[124:127], v[112:115], v[0:15]
	ds_read_b128 v[112:115], v237 offset:45056
	s_waitcnt lgkmcnt(0)
	v_mfma_f32_32x32x16_bf16 v[80:95], v[108:111], v[96:99], v[80:95]
	ds_read_b128 v[108:111], v238 offset:32768
	v_mfma_f32_32x32x16_bf16 v[64:79], v[116:119], v[96:99], v[64:79]
	ds_read_b128 v[116:119], v238 offset:36864
	v_mfma_f32_32x32x16_bf16 v[16:31], v[120:123], v[96:99], v[16:31]
	ds_read_b128 v[120:123], v238 offset:40960
	v_mfma_f32_32x32x16_bf16 v[0:15], v[112:115], v[96:99], v[0:15]
	ds_read_b128 v[96:99], v238 offset:45056
	s_waitcnt lgkmcnt(0)
	v_mfma_f32_32x32x16_bf16 v[80:95], v[108:111], v[100:103], v[80:95]
	ds_read_b128 v[108:111], v239 offset:32768
	v_mfma_f32_32x32x16_bf16 v[64:79], v[116:119], v[100:103], v[64:79]
	ds_read_b128 v[112:115], v239 offset:36864
	v_mfma_f32_32x32x16_bf16 v[16:31], v[120:123], v[100:103], v[16:31]
	ds_read_b128 v[116:119], v239 offset:40960
	v_mfma_f32_32x32x16_bf16 v[0:15], v[96:99], v[100:103], v[0:15]
	ds_read_b128 v[120:123], v239 offset:45056
	s_waitcnt lgkmcnt(0)
	v_mfma_f32_32x32x16_bf16 v[80:95], v[108:111], v[104:107], v[80:95]
	ds_read_b128 v[96:99], v205
	v_mfma_f32_32x32x16_bf16 v[64:79], v[112:115], v[104:107], v[64:79]
	ds_read_b128 v[100:103], v205 offset:8192
	v_mfma_f32_32x32x16_bf16 v[16:31], v[116:119], v[104:107], v[16:31]
	ds_read_b128 v[182:185], v211
	v_mfma_f32_32x32x16_bf16 v[0:15], v[120:123], v[104:107], v[0:15]
	ds_read_b128 v[186:189], v211 offset:8192
	s_waitcnt lgkmcnt(0)
	v_mfma_f32_32x32x16_bf16 v[112:127], v[96:99], v[160:163], 0
	ds_read_b128 v[216:219], v212
	v_exp_f32_e32 v224, v144
	v_exp_f32_e32 v225, v145
	v_exp_f32_e32 v226, v146
	v_exp_f32_e32 v227, v147
	ds_read_b128 v[220:223], v212 offset:8192
	v_mfma_f32_32x32x16_bf16 v[96:111], v[100:103], v[160:163], 0
	v_exp_f32_e32 v228, v148
	v_exp_f32_e32 v229, v149
	v_exp_f32_e32 v230, v150
	v_exp_f32_e32 v231, v151
	v_mfma_f32_32x32x16_bf16 v[112:127], v[182:185], v[164:167], v[112:127]
	ds_read_b128 v[148:151], v213
	v_exp_f32_e32 v232, v152
	v_exp_f32_e32 v233, v153
	v_exp_f32_e32 v234, v154
	v_exp_f32_e32 v235, v155
	v_cvt_pk_bf16_f32 v144, v224, v225
	v_cvt_pk_bf16_f32 v145, v226, v227
	v_cvt_pk_bf16_f32 v146, v228, v229
	v_cvt_pk_bf16_f32 v147, v230, v231
	v_pk_add_f32 v[154:155], v[230:231], v[226:227]
	v_pk_add_f32 v[152:153], v[228:229], v[224:225]
	v_mfma_f32_32x32x16_bf16 v[96:111], v[186:189], v[164:167], v[96:111]
	ds_read_b128 v[182:185], v213 offset:8192
	v_exp_f32_e32 v156, v156
	v_exp_f32_e32 v157, v157
	v_exp_f32_e32 v158, v158
	v_exp_f32_e32 v159, v159
	s_waitcnt lgkmcnt(0)
	v_mfma_f32_32x32x16_bf16 v[112:127], v[216:219], v[168:171], v[112:127]
	v_add_f32_e64 v154, v234, v154
	v_add_f32_e64 v155, v235, v155
	v_add_f32_e64 v152, v232, v152
	v_add_f32_e64 v153, v233, v153
	v_exp_f32_e32 v186, v128
	v_exp_f32_e32 v187, v129
	v_exp_f32_e32 v188, v130
	v_exp_f32_e32 v189, v131
	v_cvt_pk_bf16_f32 v128, v232, v233
	v_cvt_pk_bf16_f32 v129, v234, v235
	v_cvt_pk_bf16_f32 v130, v156, v157
	v_cvt_pk_bf16_f32 v131, v158, v159
	v_pk_add_f32 v[154:155], v[158:159], v[154:155]
	v_pk_add_f32 v[152:153], v[156:157], v[152:153]
	v_mfma_f32_32x32x16_bf16 v[96:111], v[220:223], v[168:171], v[96:111]
	v_exp_f32_e32 v156, v132
	v_exp_f32_e32 v157, v133
	v_exp_f32_e32 v158, v134
	v_exp_f32_e32 v159, v135
	v_mfma_f32_32x32x16_bf16 v[112:127], v[148:151], v[172:175], v[112:127]
	v_exp_f32_e32 v216, v136
	v_exp_f32_e32 v217, v137
	v_exp_f32_e32 v218, v138
	v_exp_f32_e32 v219, v139
	v_pk_add_f32 v[138:139], v[188:189], v[154:155]
	v_pk_add_f32 v[136:137], v[186:187], v[152:153]
	v_cvt_pk_bf16_f32 v132, v186, v187
	v_cvt_pk_bf16_f32 v133, v188, v189
	v_cvt_pk_bf16_f32 v134, v156, v157
	v_cvt_pk_bf16_f32 v135, v158, v159
	v_pk_add_f32 v[150:151], v[158:159], v[138:139]
	v_pk_add_f32 v[148:149], v[156:157], v[136:137]
	v_mfma_f32_32x32x16_bf16 v[96:111], v[182:185], v[172:175], v[96:111]
	v_exp_f32_e32 v152, v140
	v_exp_f32_e32 v153, v141
	v_exp_f32_e32 v154, v142
	v_exp_f32_e32 v155, v143
	v_pk_add_f32 v[142:143], v[218:219], v[150:151]
	v_pk_add_f32 v[140:141], v[216:217], v[148:149]
	v_cvt_pk_bf16_f32 v136, v216, v217
	v_cvt_pk_bf16_f32 v137, v218, v219
	v_cvt_pk_bf16_f32 v138, v152, v153
	v_cvt_pk_bf16_f32 v139, v154, v155
	v_pk_add_f32 v[142:143], v[154:155], v[142:143]
	v_pk_add_f32 v[140:141], v[152:153], v[140:141]
	s_waitcnt vmcnt(4) lgkmcnt(0)
	v_add_f32_e32 v148, v176, v177
	v_add_f32_e32 v149, v178, v179
	v_add_f32_e32 v148, v148, v149
	v_add_f32_e32 v140, v140, v141
	v_add_f32_e32 v141, v142, v143
	s_barrier
	v_add_f32_e32 v148, v180, v148
	v_add_f32_e32 v140, v140, v141
	v_add_f32_e32 v180, v148, v140
	ds_read_b128 v[140:143], v206 offset:49152
	ds_read_b128 v[148:151], v206 offset:53248
	ds_read_b128 v[152:155], v206 offset:57344
	ds_read_b128 v[156:159], v206 offset:61440
	s_add_u32 s98, s98, 0x30000
	s_addc_u32 s99, s99, 0
	s_add_u32 s100, s100, 0x100
	s_addc_u32 s101, s101, 0
	s_add_i32 s49, s58, 0
	s_mov_b32 m0, s49
	s_nop 0
	global_load_lds_dwordx4 v198, s[98:99]
	s_add_i32 m0, s49, 0x400
	s_nop 0
	global_load_lds_dwordx4 v194, s[98:99]
	s_add_i32 s49, s58, 0xc000
	s_add_i32 m0, s49, 0xc000
	s_nop 0
	global_load_lds_dwordx4 v196, s[100:101]
	s_add_i32 m0, s49, 0xc400
	s_nop 0
	global_load_lds_dwordx4 v192, s[100:101]
	s_waitcnt lgkmcnt(0)
	v_mfma_f32_32x32x16_bf16 v[80:95], v[140:143], v[144:147], v[80:95]
	ds_read_b128 v[140:143], v207 offset:49152
	v_mfma_f32_32x32x16_bf16 v[64:79], v[148:151], v[144:147], v[64:79]
	ds_read_b128 v[148:151], v207 offset:53248
	v_mfma_f32_32x32x16_bf16 v[16:31], v[152:155], v[144:147], v[16:31]
	ds_read_b128 v[152:155], v207 offset:57344
	v_mfma_f32_32x32x16_bf16 v[0:15], v[156:159], v[144:147], v[0:15]
	ds_read_b128 v[144:147], v207 offset:61440
	s_waitcnt lgkmcnt(0)
	v_mfma_f32_32x32x16_bf16 v[80:95], v[140:143], v[128:131], v[80:95]
	ds_read_b128 v[140:143], v208 offset:49152
	v_mfma_f32_32x32x16_bf16 v[64:79], v[148:151], v[128:131], v[64:79]
	ds_read_b128 v[148:151], v208 offset:53248
	v_mfma_f32_32x32x16_bf16 v[16:31], v[152:155], v[128:131], v[16:31]
	ds_read_b128 v[152:155], v208 offset:57344
	v_mfma_f32_32x32x16_bf16 v[0:15], v[144:147], v[128:131], v[0:15]
	ds_read_b128 v[128:131], v208 offset:61440
	s_waitcnt lgkmcnt(0)
	v_mfma_f32_32x32x16_bf16 v[80:95], v[140:143], v[132:135], v[80:95]
	ds_read_b128 v[140:143], v209 offset:49152
	v_mfma_f32_32x32x16_bf16 v[64:79], v[148:151], v[132:135], v[64:79]
	ds_read_b128 v[144:147], v209 offset:53248
	v_mfma_f32_32x32x16_bf16 v[16:31], v[152:155], v[132:135], v[16:31]
	ds_read_b128 v[148:151], v209 offset:57344
	v_mfma_f32_32x32x16_bf16 v[0:15], v[128:131], v[132:135], v[0:15]
	ds_read_b128 v[128:131], v209 offset:61440
	s_waitcnt lgkmcnt(0)
	v_mfma_f32_32x32x16_bf16 v[80:95], v[140:143], v[136:139], v[80:95]
	ds_read_b128 v[132:135], v205 offset:16384
	v_mfma_f32_32x32x16_bf16 v[64:79], v[144:147], v[136:139], v[64:79]
	ds_read_b128 v[140:143], v205 offset:24576
	v_mfma_f32_32x32x16_bf16 v[16:31], v[148:151], v[136:139], v[16:31]
	ds_read_b128 v[176:179], v211 offset:16384
	v_mfma_f32_32x32x16_bf16 v[0:15], v[128:131], v[136:139], v[0:15]
	ds_read_b128 v[182:185], v211 offset:24576
	s_waitcnt lgkmcnt(0)
	v_mfma_f32_32x32x16_bf16 v[144:159], v[132:135], v[160:163], 0
	ds_read_b128 v[186:189], v212 offset:16384
	v_exp_f32_e32 v220, v112
	v_exp_f32_e32 v221, v113
	v_exp_f32_e32 v222, v114
	v_exp_f32_e32 v223, v115
	v_mfma_f32_32x32x16_bf16 v[128:143], v[140:143], v[160:163], 0
	ds_read_b128 v[216:219], v212 offset:24576
	v_exp_f32_e32 v224, v116
	v_exp_f32_e32 v225, v117
	v_exp_f32_e32 v226, v118
	v_exp_f32_e32 v227, v119
	v_mfma_f32_32x32x16_bf16 v[144:159], v[176:179], v[164:167], v[144:159]
	ds_read_b128 v[116:119], v213 offset:16384
	v_exp_f32_e32 v228, v120
	v_exp_f32_e32 v229, v121
	v_exp_f32_e32 v230, v122
	v_exp_f32_e32 v231, v123
	v_cvt_pk_bf16_f32 v112, v220, v221
	v_cvt_pk_bf16_f32 v113, v222, v223
	v_cvt_pk_bf16_f32 v114, v224, v225
	v_cvt_pk_bf16_f32 v115, v226, v227
	v_pk_add_f32 v[122:123], v[226:227], v[222:223]
	v_pk_add_f32 v[120:121], v[224:225], v[220:221]
	v_mfma_f32_32x32x16_bf16 v[128:143], v[182:185], v[164:167], v[128:143]
	ds_read_b128 v[176:179], v213 offset:24576
	v_exp_f32_e32 v124, v124
	v_exp_f32_e32 v125, v125
	v_exp_f32_e32 v126, v126
	v_exp_f32_e32 v127, v127
	s_waitcnt lgkmcnt(0)
	v_mfma_f32_32x32x16_bf16 v[144:159], v[186:189], v[168:171], v[144:159]
	v_add_f32_e64 v122, v230, v122
	v_add_f32_e64 v123, v231, v123
	v_add_f32_e64 v120, v228, v120
	v_add_f32_e64 v121, v229, v121
	v_exp_f32_e32 v182, v96
	v_exp_f32_e32 v183, v97
	v_exp_f32_e32 v184, v98
	v_exp_f32_e32 v185, v99
	v_cvt_pk_bf16_f32 v96, v228, v229
	v_cvt_pk_bf16_f32 v97, v230, v231
	v_cvt_pk_bf16_f32 v98, v124, v125
	v_cvt_pk_bf16_f32 v99, v126, v127
	v_pk_add_f32 v[122:123], v[126:127], v[122:123]
	v_pk_add_f32 v[120:121], v[124:125], v[120:121]
	v_mfma_f32_32x32x16_bf16 v[128:143], v[216:219], v[168:171], v[128:143]
	v_exp_f32_e32 v124, v100
	v_exp_f32_e32 v125, v101
	v_exp_f32_e32 v126, v102
	v_exp_f32_e32 v127, v103
	v_mfma_f32_32x32x16_bf16 v[144:159], v[116:119], v[172:175], v[144:159]
	v_exp_f32_e32 v186, v104
	v_exp_f32_e32 v187, v105
	v_exp_f32_e32 v188, v106
	v_exp_f32_e32 v189, v107
	v_pk_add_f32 v[106:107], v[184:185], v[122:123]
	v_pk_add_f32 v[104:105], v[182:183], v[120:121]
	v_cvt_pk_bf16_f32 v100, v182, v183
	v_cvt_pk_bf16_f32 v101, v184, v185
	v_cvt_pk_bf16_f32 v102, v124, v125
	v_cvt_pk_bf16_f32 v103, v126, v127
	v_pk_add_f32 v[118:119], v[126:127], v[106:107]
	v_pk_add_f32 v[116:117], v[124:125], v[104:105]
	v_mfma_f32_32x32x16_bf16 v[128:143], v[176:179], v[172:175], v[128:143]
	v_exp_f32_e32 v120, v108
	v_exp_f32_e32 v121, v109
	v_exp_f32_e32 v122, v110
	v_exp_f32_e32 v123, v111
	v_pk_add_f32 v[110:111], v[188:189], v[118:119]
	v_pk_add_f32 v[108:109], v[186:187], v[116:117]
	v_cvt_pk_bf16_f32 v104, v186, v187
	v_cvt_pk_bf16_f32 v105, v188, v189
	v_cvt_pk_bf16_f32 v106, v120, v121
	v_cvt_pk_bf16_f32 v107, v122, v123
	v_pk_add_f32 v[178:179], v[122:123], v[110:111]
	v_pk_add_f32 v[176:177], v[120:121], v[108:109]
	s_waitcnt vmcnt(4) lgkmcnt(0)
	s_barrier
	ds_read_b128 v[108:111], v236
	ds_read_b128 v[116:119], v236 offset:4096
	ds_read_b128 v[120:123], v236 offset:8192
	ds_read_b128 v[124:127], v236 offset:12288
	s_add_u32 s70, s98, 0x18000
	s_addc_u32 s71, s99, 0
	s_add_i32 s68, 0x4000, s57
	s_mov_b32 m0, s68
	s_nop 0
	global_load_lds_dwordx4 v198, s[70:71]
	s_add_i32 m0, s68, 0x400
	s_nop 0
	global_load_lds_dwordx4 v194, s[70:71]
	s_add_u32 s2, s100, 0x80
	s_addc_u32 s3, s101, 0
	s_add_i32 s49, s58, 0
	s_add_i32 m0, s49, 0xc000
	s_nop 0
	global_load_lds_dwordx4 v196, s[2:3]
	s_add_i32 m0, s49, 0xc400
	s_nop 0
	global_load_lds_dwordx4 v192, s[2:3]
	s_waitcnt lgkmcnt(0)
	v_mfma_f32_32x32x16_bf16 v[80:95], v[108:111], v[112:115], v[80:95]
	ds_read_b128 v[108:111], v237
	v_mfma_f32_32x32x16_bf16 v[64:79], v[116:119], v[112:115], v[64:79]
	ds_read_b128 v[116:119], v237 offset:4096
	v_mfma_f32_32x32x16_bf16 v[16:31], v[120:123], v[112:115], v[16:31]
	ds_read_b128 v[120:123], v237 offset:8192
	v_mfma_f32_32x32x16_bf16 v[0:15], v[124:127], v[112:115], v[0:15]
	ds_read_b128 v[112:115], v237 offset:12288
	s_waitcnt lgkmcnt(0)
	v_mfma_f32_32x32x16_bf16 v[80:95], v[108:111], v[96:99], v[80:95]
	ds_read_b128 v[108:111], v238
	v_mfma_f32_32x32x16_bf16 v[64:79], v[116:119], v[96:99], v[64:79]
	ds_read_b128 v[116:119], v238 offset:4096
	v_mfma_f32_32x32x16_bf16 v[16:31], v[120:123], v[96:99], v[16:31]
	ds_read_b128 v[120:123], v238 offset:8192
	v_mfma_f32_32x32x16_bf16 v[0:15], v[112:115], v[96:99], v[0:15]
	ds_read_b128 v[96:99], v238 offset:12288
	s_waitcnt lgkmcnt(0)
	v_mfma_f32_32x32x16_bf16 v[80:95], v[108:111], v[100:103], v[80:95]
	ds_read_b128 v[108:111], v239
	v_mfma_f32_32x32x16_bf16 v[64:79], v[116:119], v[100:103], v[64:79]
	ds_read_b128 v[112:115], v239 offset:4096
	v_mfma_f32_32x32x16_bf16 v[16:31], v[120:123], v[100:103], v[16:31]
	ds_read_b128 v[116:119], v239 offset:8192
	v_mfma_f32_32x32x16_bf16 v[0:15], v[96:99], v[100:103], v[0:15]
	ds_read_b128 v[120:123], v239 offset:12288
	s_waitcnt lgkmcnt(0)
	v_mfma_f32_32x32x16_bf16 v[80:95], v[108:111], v[104:107], v[80:95]
	ds_read_b128 v[96:99], v205 offset:32768
	v_mfma_f32_32x32x16_bf16 v[64:79], v[112:115], v[104:107], v[64:79]
	ds_read_b128 v[100:103], v205 offset:40960
	v_mfma_f32_32x32x16_bf16 v[16:31], v[116:119], v[104:107], v[16:31]
	ds_read_b128 v[182:185], v211 offset:32768
	v_mfma_f32_32x32x16_bf16 v[0:15], v[120:123], v[104:107], v[0:15]
	ds_read_b128 v[186:189], v211 offset:40960
	s_waitcnt lgkmcnt(0)
	v_mfma_f32_32x32x16_bf16 v[112:127], v[96:99], v[160:163], 0
	ds_read_b128 v[216:219], v212 offset:32768
	v_exp_f32_e32 v224, v144
	v_exp_f32_e32 v225, v145
	v_exp_f32_e32 v226, v146
	v_exp_f32_e32 v227, v147
	ds_read_b128 v[220:223], v212 offset:40960
	v_mfma_f32_32x32x16_bf16 v[96:111], v[100:103], v[160:163], 0
	v_exp_f32_e32 v228, v148
	v_exp_f32_e32 v229, v149
	v_exp_f32_e32 v230, v150
	v_exp_f32_e32 v231, v151
	v_mfma_f32_32x32x16_bf16 v[112:127], v[182:185], v[164:167], v[112:127]
	ds_read_b128 v[148:151], v213 offset:32768
	v_exp_f32_e32 v232, v152
	v_exp_f32_e32 v233, v153
	v_exp_f32_e32 v234, v154
	v_exp_f32_e32 v235, v155
	v_cvt_pk_bf16_f32 v144, v224, v225
	v_cvt_pk_bf16_f32 v145, v226, v227
	v_cvt_pk_bf16_f32 v146, v228, v229
	v_cvt_pk_bf16_f32 v147, v230, v231
	v_pk_add_f32 v[154:155], v[230:231], v[226:227]
	v_pk_add_f32 v[152:153], v[228:229], v[224:225]
	v_mfma_f32_32x32x16_bf16 v[96:111], v[186:189], v[164:167], v[96:111]
	ds_read_b128 v[182:185], v213 offset:40960
	v_exp_f32_e32 v156, v156
	v_exp_f32_e32 v157, v157
	v_exp_f32_e32 v158, v158
	v_exp_f32_e32 v159, v159
	s_waitcnt lgkmcnt(0)
	v_mfma_f32_32x32x16_bf16 v[112:127], v[216:219], v[168:171], v[112:127]
	v_add_f32_e64 v154, v234, v154
	v_add_f32_e64 v155, v235, v155
	v_add_f32_e64 v152, v232, v152
	v_add_f32_e64 v153, v233, v153
	v_exp_f32_e32 v186, v128
	v_exp_f32_e32 v187, v129
	v_exp_f32_e32 v188, v130
	v_exp_f32_e32 v189, v131
	v_cvt_pk_bf16_f32 v128, v232, v233
	v_cvt_pk_bf16_f32 v129, v234, v235
	v_cvt_pk_bf16_f32 v130, v156, v157
	v_cvt_pk_bf16_f32 v131, v158, v159
	v_pk_add_f32 v[154:155], v[158:159], v[154:155]
	v_pk_add_f32 v[152:153], v[156:157], v[152:153]
	v_mfma_f32_32x32x16_bf16 v[96:111], v[220:223], v[168:171], v[96:111]
	v_exp_f32_e32 v156, v132
	v_exp_f32_e32 v157, v133
	v_exp_f32_e32 v158, v134
	v_exp_f32_e32 v159, v135
	v_mfma_f32_32x32x16_bf16 v[112:127], v[148:151], v[172:175], v[112:127]
	v_exp_f32_e32 v216, v136
	v_exp_f32_e32 v217, v137
	v_exp_f32_e32 v218, v138
	v_exp_f32_e32 v219, v139
	v_pk_add_f32 v[138:139], v[188:189], v[154:155]
	v_pk_add_f32 v[136:137], v[186:187], v[152:153]
	v_cvt_pk_bf16_f32 v132, v186, v187
	v_cvt_pk_bf16_f32 v133, v188, v189
	v_cvt_pk_bf16_f32 v134, v156, v157
	v_cvt_pk_bf16_f32 v135, v158, v159
	v_pk_add_f32 v[150:151], v[158:159], v[138:139]
	v_pk_add_f32 v[148:149], v[156:157], v[136:137]
	v_mfma_f32_32x32x16_bf16 v[96:111], v[182:185], v[172:175], v[96:111]
	v_exp_f32_e32 v152, v140
	v_exp_f32_e32 v153, v141
	v_exp_f32_e32 v154, v142
	v_exp_f32_e32 v155, v143
	v_pk_add_f32 v[142:143], v[218:219], v[150:151]
	v_pk_add_f32 v[140:141], v[216:217], v[148:149]
	v_cvt_pk_bf16_f32 v136, v216, v217
	v_cvt_pk_bf16_f32 v137, v218, v219
	v_cvt_pk_bf16_f32 v138, v152, v153
	v_cvt_pk_bf16_f32 v139, v154, v155
	v_pk_add_f32 v[142:143], v[154:155], v[142:143]
	v_pk_add_f32 v[140:141], v[152:153], v[140:141]
	s_waitcnt vmcnt(4) lgkmcnt(0)
	v_add_f32_e32 v148, v176, v177
	v_add_f32_e32 v149, v178, v179
	v_add_f32_e32 v148, v148, v149
	v_add_f32_e32 v140, v140, v141
	v_add_f32_e32 v141, v142, v143
	s_barrier
	v_add_f32_e32 v148, v180, v148
	v_add_f32_e32 v140, v140, v141
	v_add_f32_e32 v180, v148, v140
	ds_read_b128 v[140:143], v236 offset:16384
	ds_read_b128 v[148:151], v236 offset:20480
	ds_read_b128 v[152:155], v236 offset:24576
	ds_read_b128 v[156:159], v236 offset:28672
	s_add_u32 s98, s98, 0x30000
	s_addc_u32 s99, s99, 0
	s_add_u32 s100, s100, 0x100
	s_addc_u32 s101, s101, 0
	s_add_i32 s49, s58, 0x8000
	s_mov_b32 m0, s49
	s_nop 0
	global_load_lds_dwordx4 v198, s[98:99]
	s_add_i32 m0, s49, 0x400
	s_nop 0
	global_load_lds_dwordx4 v194, s[98:99]
	s_add_i32 s49, s58, 0x4000
	s_add_i32 m0, s49, 0xc000
	s_nop 0
	global_load_lds_dwordx4 v196, s[100:101]
	s_add_i32 m0, s49, 0xc400
	s_nop 0
	global_load_lds_dwordx4 v192, s[100:101]
	s_waitcnt lgkmcnt(0)
	v_mfma_f32_32x32x16_bf16 v[80:95], v[140:143], v[144:147], v[80:95]
	ds_read_b128 v[140:143], v237 offset:16384
	v_mfma_f32_32x32x16_bf16 v[64:79], v[148:151], v[144:147], v[64:79]
	ds_read_b128 v[148:151], v237 offset:20480
	v_mfma_f32_32x32x16_bf16 v[16:31], v[152:155], v[144:147], v[16:31]
	ds_read_b128 v[152:155], v237 offset:24576
	v_mfma_f32_32x32x16_bf16 v[0:15], v[156:159], v[144:147], v[0:15]
	ds_read_b128 v[144:147], v237 offset:28672
	s_waitcnt lgkmcnt(0)
	v_mfma_f32_32x32x16_bf16 v[80:95], v[140:143], v[128:131], v[80:95]
	ds_read_b128 v[140:143], v238 offset:16384
	v_mfma_f32_32x32x16_bf16 v[64:79], v[148:151], v[128:131], v[64:79]
	ds_read_b128 v[148:151], v238 offset:20480
	v_mfma_f32_32x32x16_bf16 v[16:31], v[152:155], v[128:131], v[16:31]
	ds_read_b128 v[152:155], v238 offset:24576
	v_mfma_f32_32x32x16_bf16 v[0:15], v[144:147], v[128:131], v[0:15]
	ds_read_b128 v[128:131], v238 offset:28672
	s_waitcnt lgkmcnt(0)
	v_mfma_f32_32x32x16_bf16 v[80:95], v[140:143], v[132:135], v[80:95]
	ds_read_b128 v[140:143], v239 offset:16384
	v_mfma_f32_32x32x16_bf16 v[64:79], v[148:151], v[132:135], v[64:79]
	ds_read_b128 v[144:147], v239 offset:20480
	v_mfma_f32_32x32x16_bf16 v[16:31], v[152:155], v[132:135], v[16:31]
	ds_read_b128 v[148:151], v239 offset:24576
	v_mfma_f32_32x32x16_bf16 v[0:15], v[128:131], v[132:135], v[0:15]
	ds_read_b128 v[128:131], v239 offset:28672
	s_waitcnt lgkmcnt(0)
	v_mfma_f32_32x32x16_bf16 v[80:95], v[140:143], v[136:139], v[80:95]
	ds_read_b128 v[132:135], v205
	v_mfma_f32_32x32x16_bf16 v[64:79], v[144:147], v[136:139], v[64:79]
	ds_read_b128 v[140:143], v205 offset:8192
	v_mfma_f32_32x32x16_bf16 v[16:31], v[148:151], v[136:139], v[16:31]
	ds_read_b128 v[176:179], v211
	v_mfma_f32_32x32x16_bf16 v[0:15], v[128:131], v[136:139], v[0:15]
	ds_read_b128 v[182:185], v211 offset:8192
	s_waitcnt lgkmcnt(0)
	v_mfma_f32_32x32x16_bf16 v[144:159], v[132:135], v[160:163], 0
	ds_read_b128 v[186:189], v212
	v_exp_f32_e32 v220, v112
	v_exp_f32_e32 v221, v113
	v_exp_f32_e32 v222, v114
	v_exp_f32_e32 v223, v115
	v_mfma_f32_32x32x16_bf16 v[128:143], v[140:143], v[160:163], 0
	ds_read_b128 v[216:219], v212 offset:8192
	v_exp_f32_e32 v224, v116
	v_exp_f32_e32 v225, v117
	v_exp_f32_e32 v226, v118
	v_exp_f32_e32 v227, v119
	v_mfma_f32_32x32x16_bf16 v[144:159], v[176:179], v[164:167], v[144:159]
	ds_read_b128 v[116:119], v213
	v_exp_f32_e32 v228, v120
	v_exp_f32_e32 v229, v121
	v_exp_f32_e32 v230, v122
	v_exp_f32_e32 v231, v123
	v_cvt_pk_bf16_f32 v112, v220, v221
	v_cvt_pk_bf16_f32 v113, v222, v223
	v_cvt_pk_bf16_f32 v114, v224, v225
	v_cvt_pk_bf16_f32 v115, v226, v227
	v_pk_add_f32 v[122:123], v[226:227], v[222:223]
	v_pk_add_f32 v[120:121], v[224:225], v[220:221]
	v_mfma_f32_32x32x16_bf16 v[128:143], v[182:185], v[164:167], v[128:143]
	ds_read_b128 v[176:179], v213 offset:8192
	v_exp_f32_e32 v124, v124
	v_exp_f32_e32 v125, v125
	v_exp_f32_e32 v126, v126
	v_exp_f32_e32 v127, v127
	s_waitcnt lgkmcnt(0)
	v_mfma_f32_32x32x16_bf16 v[144:159], v[186:189], v[168:171], v[144:159]
	v_add_f32_e64 v122, v230, v122
	v_add_f32_e64 v123, v231, v123
	v_add_f32_e64 v120, v228, v120
	v_add_f32_e64 v121, v229, v121
	v_exp_f32_e32 v182, v96
	v_exp_f32_e32 v183, v97
	v_exp_f32_e32 v184, v98
	v_exp_f32_e32 v185, v99
	v_cvt_pk_bf16_f32 v96, v228, v229
	v_cvt_pk_bf16_f32 v97, v230, v231
	v_cvt_pk_bf16_f32 v98, v124, v125
	v_cvt_pk_bf16_f32 v99, v126, v127
	v_pk_add_f32 v[122:123], v[126:127], v[122:123]
	v_pk_add_f32 v[120:121], v[124:125], v[120:121]
	v_mfma_f32_32x32x16_bf16 v[128:143], v[216:219], v[168:171], v[128:143]
	v_exp_f32_e32 v124, v100
	v_exp_f32_e32 v125, v101
	v_exp_f32_e32 v126, v102
	v_exp_f32_e32 v127, v103
	v_mfma_f32_32x32x16_bf16 v[144:159], v[116:119], v[172:175], v[144:159]
	v_exp_f32_e32 v186, v104
	v_exp_f32_e32 v187, v105
	v_exp_f32_e32 v188, v106
	v_exp_f32_e32 v189, v107
	v_pk_add_f32 v[106:107], v[184:185], v[122:123]
	v_pk_add_f32 v[104:105], v[182:183], v[120:121]
	v_cvt_pk_bf16_f32 v100, v182, v183
	v_cvt_pk_bf16_f32 v101, v184, v185
	v_cvt_pk_bf16_f32 v102, v124, v125
	v_cvt_pk_bf16_f32 v103, v126, v127
	v_pk_add_f32 v[118:119], v[126:127], v[106:107]
	v_pk_add_f32 v[116:117], v[124:125], v[104:105]
	v_mfma_f32_32x32x16_bf16 v[128:143], v[176:179], v[172:175], v[128:143]
	v_exp_f32_e32 v120, v108
	v_exp_f32_e32 v121, v109
	v_exp_f32_e32 v122, v110
	v_exp_f32_e32 v123, v111
	v_pk_add_f32 v[110:111], v[188:189], v[118:119]
	v_pk_add_f32 v[108:109], v[186:187], v[116:117]
	v_cvt_pk_bf16_f32 v104, v186, v187
	v_cvt_pk_bf16_f32 v105, v188, v189
	v_cvt_pk_bf16_f32 v106, v120, v121
	v_cvt_pk_bf16_f32 v107, v122, v123
	v_pk_add_f32 v[178:179], v[122:123], v[110:111]
	v_pk_add_f32 v[176:177], v[120:121], v[108:109]
	s_waitcnt vmcnt(4) lgkmcnt(0)
	s_barrier
	ds_read_b128 v[108:111], v236 offset:32768
	ds_read_b128 v[116:119], v236 offset:36864
	ds_read_b128 v[120:123], v236 offset:40960
	ds_read_b128 v[124:127], v236 offset:45056
	s_add_u32 s70, s98, 0x18000
	s_addc_u32 s71, s99, 0
	s_add_i32 s68, 0, s57
	s_mov_b32 m0, s68
	s_nop 0
	global_load_lds_dwordx4 v198, s[70:71]
	s_add_i32 m0, s68, 0x400
	s_nop 0
	global_load_lds_dwordx4 v194, s[70:71]
	s_add_u32 s2, s100, 0x80
	s_addc_u32 s3, s101, 0
	s_add_i32 s49, s58, 0x8000
	s_add_i32 m0, s49, 0xc000
	s_nop 0
	global_load_lds_dwordx4 v196, s[2:3]
	s_add_i32 m0, s49, 0xc400
	s_nop 0
	global_load_lds_dwordx4 v192, s[2:3]
	s_waitcnt lgkmcnt(0)
	v_mfma_f32_32x32x16_bf16 v[80:95], v[108:111], v[112:115], v[80:95]
	ds_read_b128 v[108:111], v237 offset:32768
	v_mfma_f32_32x32x16_bf16 v[64:79], v[116:119], v[112:115], v[64:79]
	ds_read_b128 v[116:119], v237 offset:36864
	v_mfma_f32_32x32x16_bf16 v[16:31], v[120:123], v[112:115], v[16:31]
	ds_read_b128 v[120:123], v237 offset:40960
	v_mfma_f32_32x32x16_bf16 v[0:15], v[124:127], v[112:115], v[0:15]
	ds_read_b128 v[112:115], v237 offset:45056
	s_waitcnt lgkmcnt(0)
	v_mfma_f32_32x32x16_bf16 v[80:95], v[108:111], v[96:99], v[80:95]
	ds_read_b128 v[108:111], v238 offset:32768
	v_mfma_f32_32x32x16_bf16 v[64:79], v[116:119], v[96:99], v[64:79]
	ds_read_b128 v[116:119], v238 offset:36864
	v_mfma_f32_32x32x16_bf16 v[16:31], v[120:123], v[96:99], v[16:31]
	ds_read_b128 v[120:123], v238 offset:40960
	v_mfma_f32_32x32x16_bf16 v[0:15], v[112:115], v[96:99], v[0:15]
	ds_read_b128 v[96:99], v238 offset:45056
	s_waitcnt lgkmcnt(0)
	v_mfma_f32_32x32x16_bf16 v[80:95], v[108:111], v[100:103], v[80:95]
	ds_read_b128 v[108:111], v239 offset:32768
	v_mfma_f32_32x32x16_bf16 v[64:79], v[116:119], v[100:103], v[64:79]
	ds_read_b128 v[112:115], v239 offset:36864
	v_mfma_f32_32x32x16_bf16 v[16:31], v[120:123], v[100:103], v[16:31]
	ds_read_b128 v[116:119], v239 offset:40960
	v_mfma_f32_32x32x16_bf16 v[0:15], v[96:99], v[100:103], v[0:15]
	ds_read_b128 v[120:123], v239 offset:45056
	s_waitcnt lgkmcnt(0)
	v_mfma_f32_32x32x16_bf16 v[80:95], v[108:111], v[104:107], v[80:95]
	ds_read_b128 v[96:99], v205 offset:16384
	v_mfma_f32_32x32x16_bf16 v[64:79], v[112:115], v[104:107], v[64:79]
	ds_read_b128 v[100:103], v205 offset:24576
	v_mfma_f32_32x32x16_bf16 v[16:31], v[116:119], v[104:107], v[16:31]
	ds_read_b128 v[182:185], v211 offset:16384
	v_mfma_f32_32x32x16_bf16 v[0:15], v[120:123], v[104:107], v[0:15]
	ds_read_b128 v[186:189], v211 offset:24576
	s_waitcnt lgkmcnt(0)
	v_mfma_f32_32x32x16_bf16 v[112:127], v[96:99], v[160:163], 0
	ds_read_b128 v[216:219], v212 offset:16384
	v_exp_f32_e32 v224, v144
	v_exp_f32_e32 v225, v145
	v_exp_f32_e32 v226, v146
	v_exp_f32_e32 v227, v147
	ds_read_b128 v[220:223], v212 offset:24576
	v_mfma_f32_32x32x16_bf16 v[96:111], v[100:103], v[160:163], 0
	v_exp_f32_e32 v228, v148
	v_exp_f32_e32 v229, v149
	v_exp_f32_e32 v230, v150
	v_exp_f32_e32 v231, v151
	v_mfma_f32_32x32x16_bf16 v[112:127], v[182:185], v[164:167], v[112:127]
	ds_read_b128 v[148:151], v213 offset:16384
	v_exp_f32_e32 v232, v152
	v_exp_f32_e32 v233, v153
	v_exp_f32_e32 v234, v154
	v_exp_f32_e32 v235, v155
	v_cvt_pk_bf16_f32 v144, v224, v225
	v_cvt_pk_bf16_f32 v145, v226, v227
	v_cvt_pk_bf16_f32 v146, v228, v229
	v_cvt_pk_bf16_f32 v147, v230, v231
	v_pk_add_f32 v[154:155], v[230:231], v[226:227]
	v_pk_add_f32 v[152:153], v[228:229], v[224:225]
	v_mfma_f32_32x32x16_bf16 v[96:111], v[186:189], v[164:167], v[96:111]
	ds_read_b128 v[182:185], v213 offset:24576
	v_exp_f32_e32 v156, v156
	v_exp_f32_e32 v157, v157
	v_exp_f32_e32 v158, v158
	v_exp_f32_e32 v159, v159
	s_waitcnt lgkmcnt(0)
	v_mfma_f32_32x32x16_bf16 v[112:127], v[216:219], v[168:171], v[112:127]
	v_add_f32_e64 v154, v234, v154
	v_add_f32_e64 v155, v235, v155
	v_add_f32_e64 v152, v232, v152
	v_add_f32_e64 v153, v233, v153
	v_exp_f32_e32 v186, v128
	v_exp_f32_e32 v187, v129
	v_exp_f32_e32 v188, v130
	v_exp_f32_e32 v189, v131
	v_cvt_pk_bf16_f32 v128, v232, v233
	v_cvt_pk_bf16_f32 v129, v234, v235
	v_cvt_pk_bf16_f32 v130, v156, v157
	v_cvt_pk_bf16_f32 v131, v158, v159
	v_pk_add_f32 v[154:155], v[158:159], v[154:155]
	v_pk_add_f32 v[152:153], v[156:157], v[152:153]
	v_mfma_f32_32x32x16_bf16 v[96:111], v[220:223], v[168:171], v[96:111]
	v_exp_f32_e32 v156, v132
	v_exp_f32_e32 v157, v133
	v_exp_f32_e32 v158, v134
	v_exp_f32_e32 v159, v135
	v_mfma_f32_32x32x16_bf16 v[112:127], v[148:151], v[172:175], v[112:127]
	v_exp_f32_e32 v216, v136
	v_exp_f32_e32 v217, v137
	v_exp_f32_e32 v218, v138
	v_exp_f32_e32 v219, v139
	v_pk_add_f32 v[138:139], v[188:189], v[154:155]
	v_pk_add_f32 v[136:137], v[186:187], v[152:153]
	v_cvt_pk_bf16_f32 v132, v186, v187
	v_cvt_pk_bf16_f32 v133, v188, v189
	v_cvt_pk_bf16_f32 v134, v156, v157
	v_cvt_pk_bf16_f32 v135, v158, v159
	v_pk_add_f32 v[150:151], v[158:159], v[138:139]
	v_pk_add_f32 v[148:149], v[156:157], v[136:137]
	v_mfma_f32_32x32x16_bf16 v[96:111], v[182:185], v[172:175], v[96:111]
	v_exp_f32_e32 v152, v140
	v_exp_f32_e32 v153, v141
	v_exp_f32_e32 v154, v142
	v_exp_f32_e32 v155, v143
	v_pk_add_f32 v[142:143], v[218:219], v[150:151]
	v_pk_add_f32 v[140:141], v[216:217], v[148:149]
	v_cvt_pk_bf16_f32 v136, v216, v217
	v_cvt_pk_bf16_f32 v137, v218, v219
	v_cvt_pk_bf16_f32 v138, v152, v153
	v_cvt_pk_bf16_f32 v139, v154, v155
	v_pk_add_f32 v[142:143], v[154:155], v[142:143]
	v_pk_add_f32 v[140:141], v[152:153], v[140:141]
	s_waitcnt vmcnt(4) lgkmcnt(0)
	v_add_f32_e32 v148, v176, v177
	v_add_f32_e32 v149, v178, v179
	v_add_f32_e32 v148, v148, v149
	v_add_f32_e32 v140, v140, v141
	v_add_f32_e32 v141, v142, v143
	s_barrier
	v_add_f32_e32 v148, v180, v148
	v_add_f32_e32 v140, v140, v141
	v_add_f32_e32 v180, v148, v140
	s_add_u32 s98, s98, 0x30000
	s_addc_u32 s99, s99, 0
	s_add_u32 s100, s100, 0x100
	s_addc_u32 s101, s101, 0
	s_add_i32 s47, s47, 12
	s_addk_i32 s41, 0x300
	s_add_i32 s46, s46, 0x30000
	s_cmp_lt_u32 s47, 50
	s_cbranch_scc1 .Lst1_u6_loop
	s_cmp_lt_u32 s47, 60
	s_cbranch_scc1 .Lst1_single
.Lst1_exit:
	s_cmp_lg_u32 s47, 61
	s_cbranch_scc1 .Lst1_orig
	s_cmp_lg_u32 s48, 1
	s_cbranch_scc1 .Lst1_orig
	s_and_b32 s2, s46, 0xffff
	s_cmp_lg_u32 s2, 0x0
	s_cbranch_scc1 .Lst1_orig
	s_mov_b32 s44, s21
	s_add_i32 s44, s44, s41
	s_sub_i32 s44, s44, 64
	s_mul_hi_i32 s45, s44, 0x600
	s_mulk_i32 s44, 0x600
	s_add_u32 s44, s14, s44
	s_addc_u32 s45, s15, s45
	s_add_i32 s49, s58, 0x4000
	s_mov_b32 m0, s49
	s_nop 0
	global_load_lds_dwordx4 v198, s[44:45]
	s_add_i32 m0, s49, 0x400
	s_nop 0
	global_load_lds_dwordx4 v194, s[44:45]
	s_mov_b32 s44, s40
	s_add_i32 s44, s44, s41
	s_addk_i32 s44, 0xff80
	s_ashr_i32 s45, s44, 31
	s_lshl_b64 s[44:45], s[44:45], 1
	s_add_u32 s44, s39, s44
	s_addc_u32 s45, s67, s45
	s_add_i32 s49, s46, 0xffffc000
	s_add_i32 s49, s58, 0xc000
	s_add_i32 m0, s49, 0xc000
	s_nop 0
	global_load_lds_dwordx4 v196, s[44:45]
	v_lshl_add_u64 v[140:141], s[44:45], 0, v[192:193]
	s_add_i32 m0, s49, 0xc400
	s_nop 0
	global_load_lds_dwordx4 v[140:141], off
	ds_read_b128 v[140:143], v206 offset:49152
	ds_read_b128 v[148:151], v206 offset:53248
	ds_read_b128 v[152:155], v206 offset:57344
	ds_read_b128 v[156:159], v206 offset:61440
	s_waitcnt lgkmcnt(0)
	v_mfma_f32_32x32x16_bf16 v[80:95], v[140:143], v[144:147], v[80:95]
	ds_read_b128 v[140:143], v207 offset:49152
	v_mfma_f32_32x32x16_bf16 v[64:79], v[148:151], v[144:147], v[64:79]
	ds_read_b128 v[148:151], v207 offset:53248
	v_mfma_f32_32x32x16_bf16 v[16:31], v[152:155], v[144:147], v[16:31]
	ds_read_b128 v[152:155], v207 offset:57344
	v_mfma_f32_32x32x16_bf16 v[0:15], v[156:159], v[144:147], v[0:15]
	ds_read_b128 v[144:147], v207 offset:61440
	s_waitcnt lgkmcnt(0)
	v_mfma_f32_32x32x16_bf16 v[80:95], v[140:143], v[128:131], v[80:95]
	ds_read_b128 v[140:143], v208 offset:49152
	v_mfma_f32_32x32x16_bf16 v[64:79], v[148:151], v[128:131], v[64:79]
	ds_read_b128 v[148:151], v208 offset:53248
	v_mfma_f32_32x32x16_bf16 v[16:31], v[152:155], v[128:131], v[16:31]
	ds_read_b128 v[152:155], v208 offset:57344
	v_mfma_f32_32x32x16_bf16 v[0:15], v[144:147], v[128:131], v[0:15]
	ds_read_b128 v[128:131], v208 offset:61440
	s_waitcnt lgkmcnt(0)
	v_mfma_f32_32x32x16_bf16 v[80:95], v[140:143], v[132:135], v[80:95]
	ds_read_b128 v[140:143], v209 offset:49152
	v_mfma_f32_32x32x16_bf16 v[64:79], v[148:151], v[132:135], v[64:79]
	ds_read_b128 v[144:147], v209 offset:53248
	v_mfma_f32_32x32x16_bf16 v[16:31], v[152:155], v[132:135], v[16:31]
	ds_read_b128 v[148:151], v209 offset:57344
	v_mfma_f32_32x32x16_bf16 v[0:15], v[128:131], v[132:135], v[0:15]
	ds_read_b128 v[128:131], v209 offset:61440
	s_waitcnt lgkmcnt(0)
	v_mfma_f32_32x32x16_bf16 v[80:95], v[140:143], v[136:139], v[80:95]
	ds_read_b128 v[132:135], v205 offset:32768
	v_mfma_f32_32x32x16_bf16 v[64:79], v[144:147], v[136:139], v[64:79]
	ds_read_b128 v[140:143], v205 offset:40960
	v_mfma_f32_32x32x16_bf16 v[16:31], v[148:151], v[136:139], v[16:31]
	ds_read_b128 v[176:179], v211 offset:32768
	v_mfma_f32_32x32x16_bf16 v[0:15], v[128:131], v[136:139], v[0:15]
	ds_read_b128 v[182:185], v211 offset:40960
	s_waitcnt lgkmcnt(0)
	v_mfma_f32_32x32x16_bf16 v[144:159], v[132:135], v[160:163], 0
	ds_read_b128 v[186:189], v212 offset:32768
	v_exp_f32_e32 v220, v112
	v_exp_f32_e32 v221, v113
	v_exp_f32_e32 v222, v114
	v_exp_f32_e32 v223, v115
	v_mfma_f32_32x32x16_bf16 v[128:143], v[140:143], v[160:163], 0
	ds_read_b128 v[216:219], v212 offset:40960
	v_exp_f32_e32 v224, v116
	v_exp_f32_e32 v225, v117
	v_exp_f32_e32 v226, v118
	v_exp_f32_e32 v227, v119
	v_mfma_f32_32x32x16_bf16 v[144:159], v[176:179], v[164:167], v[144:159]
	ds_read_b128 v[116:119], v213 offset:32768
	v_exp_f32_e32 v228, v120
	v_exp_f32_e32 v229, v121
	v_exp_f32_e32 v230, v122
	v_exp_f32_e32 v231, v123
	v_cvt_pk_bf16_f32 v112, v220, v221
	v_cvt_pk_bf16_f32 v113, v222, v223
	v_cvt_pk_bf16_f32 v114, v224, v225
	v_cvt_pk_bf16_f32 v115, v226, v227
	v_pk_add_f32 v[122:123], v[226:227], v[222:223]
	v_pk_add_f32 v[120:121], v[224:225], v[220:221]
	v_mfma_f32_32x32x16_bf16 v[128:143], v[182:185], v[164:167], v[128:143]
	ds_read_b128 v[176:179], v213 offset:40960
	v_exp_f32_e32 v124, v124
	v_exp_f32_e32 v125, v125
	v_exp_f32_e32 v126, v126
	v_exp_f32_e32 v127, v127
	s_waitcnt lgkmcnt(0)
	v_mfma_f32_32x32x16_bf16 v[144:159], v[186:189], v[168:171], v[144:159]
	v_add_f32_e64 v122, v230, v122
	v_add_f32_e64 v123, v231, v123
	v_add_f32_e64 v120, v228, v120
	v_add_f32_e64 v121, v229, v121
	v_exp_f32_e32 v182, v96
	v_exp_f32_e32 v183, v97
	v_exp_f32_e32 v184, v98
	v_exp_f32_e32 v185, v99
	v_cvt_pk_bf16_f32 v96, v228, v229
	v_cvt_pk_bf16_f32 v97, v230, v231
	v_cvt_pk_bf16_f32 v98, v124, v125
	v_cvt_pk_bf16_f32 v99, v126, v127
	v_pk_add_f32 v[122:123], v[126:127], v[122:123]
	v_pk_add_f32 v[120:121], v[124:125], v[120:121]
	v_mfma_f32_32x32x16_bf16 v[128:143], v[216:219], v[168:171], v[128:143]
	v_exp_f32_e32 v124, v100
	v_exp_f32_e32 v125, v101
	v_exp_f32_e32 v126, v102
	v_exp_f32_e32 v127, v103
	v_mfma_f32_32x32x16_bf16 v[144:159], v[116:119], v[172:175], v[144:159]
	v_exp_f32_e32 v186, v104
	v_exp_f32_e32 v187, v105
	v_exp_f32_e32 v188, v106
	v_exp_f32_e32 v189, v107
	v_pk_add_f32 v[106:107], v[184:185], v[122:123]
	v_pk_add_f32 v[104:105], v[182:183], v[120:121]
	v_cvt_pk_bf16_f32 v100, v182, v183
	v_cvt_pk_bf16_f32 v101, v184, v185
	v_cvt_pk_bf16_f32 v102, v124, v125
	v_cvt_pk_bf16_f32 v103, v126, v127
	v_pk_add_f32 v[118:119], v[126:127], v[106:107]
	v_pk_add_f32 v[116:117], v[124:125], v[104:105]
	v_mfma_f32_32x32x16_bf16 v[128:143], v[176:179], v[172:175], v[128:143]
	v_exp_f32_e32 v120, v108
	v_exp_f32_e32 v121, v109
	v_exp_f32_e32 v122, v110
	v_exp_f32_e32 v123, v111
	v_pk_add_f32 v[110:111], v[188:189], v[118:119]
	v_pk_add_f32 v[108:109], v[186:187], v[116:117]
	v_cvt_pk_bf16_f32 v104, v186, v187
	v_cvt_pk_bf16_f32 v105, v188, v189
	v_cvt_pk_bf16_f32 v106, v120, v121
	v_cvt_pk_bf16_f32 v107, v122, v123
	v_pk_add_f32 v[178:179], v[122:123], v[110:111]
	v_pk_add_f32 v[176:177], v[120:121], v[108:109]
	s_waitcnt vmcnt(4) lgkmcnt(0)
	s_barrier
	ds_read_b128 v[108:111], v236
	ds_read_b128 v[116:119], v236 offset:4096
	ds_read_b128 v[120:123], v236 offset:8192
	ds_read_b128 v[124:127], v236 offset:12288
	s_mov_b32 s69, s21
	s_add_i32 s69, s69, s41
	s_mul_hi_i32 s71, s69, 0x600
	s_mulk_i32 s69, 0x600
	s_add_u32 s70, s14, s69
	s_addc_u32 s71, s15, s71
	s_add_i32 s68, 0x8000, s57
	s_mov_b32 m0, s68
	s_nop 0
	global_load_lds_dwordx4 v198, s[70:71]
	s_add_i32 m0, s68, 0x400
	s_nop 0
	global_load_lds_dwordx4 v194, s[70:71]
	s_mov_b32 s2, s21
	s_add_i32 s2, s2, s41
	s_sub_i32 s2, s2, 64
	s_ashr_i32 s3, s2, 31
	s_lshl_b64 s[2:3], s[2:3], 1
	s_add_u32 s2, s39, s2
	s_addc_u32 s3, s67, s3
	s_add_i32 s49, s58, 0
	s_add_i32 m0, s49, 0xc000
	s_nop 0
	global_load_lds_dwordx4 v196, s[2:3]
	s_add_i32 m0, s49, 0xc400
	s_nop 0
	global_load_lds_dwordx4 v192, s[2:3]
	s_add_i32 s2, s46, 0xffff4000
	s_waitcnt lgkmcnt(0)
	v_mfma_f32_32x32x16_bf16 v[80:95], v[108:111], v[112:115], v[80:95]
	ds_read_b128 v[108:111], v237
	v_mfma_f32_32x32x16_bf16 v[64:79], v[116:119], v[112:115], v[64:79]
	ds_read_b128 v[116:119], v237 offset:4096
	v_mfma_f32_32x32x16_bf16 v[16:31], v[120:123], v[112:115], v[16:31]
	ds_read_b128 v[120:123], v237 offset:8192
	v_mfma_f32_32x32x16_bf16 v[0:15], v[124:127], v[112:115], v[0:15]
	ds_read_b128 v[112:115], v237 offset:12288
	s_waitcnt lgkmcnt(0)
	v_mfma_f32_32x32x16_bf16 v[80:95], v[108:111], v[96:99], v[80:95]
	ds_read_b128 v[108:111], v238
	v_mfma_f32_32x32x16_bf16 v[64:79], v[116:119], v[96:99], v[64:79]
	ds_read_b128 v[116:119], v238 offset:4096
	v_mfma_f32_32x32x16_bf16 v[16:31], v[120:123], v[96:99], v[16:31]
	ds_read_b128 v[120:123], v238 offset:8192
	v_mfma_f32_32x32x16_bf16 v[0:15], v[112:115], v[96:99], v[0:15]
	ds_read_b128 v[96:99], v238 offset:12288
	s_waitcnt lgkmcnt(0)
	v_mfma_f32_32x32x16_bf16 v[80:95], v[108:111], v[100:103], v[80:95]
	ds_read_b128 v[108:111], v239
	v_mfma_f32_32x32x16_bf16 v[64:79], v[116:119], v[100:103], v[64:79]
	ds_read_b128 v[112:115], v239 offset:4096
	v_mfma_f32_32x32x16_bf16 v[16:31], v[120:123], v[100:103], v[16:31]
	ds_read_b128 v[116:119], v239 offset:8192
	v_mfma_f32_32x32x16_bf16 v[0:15], v[96:99], v[100:103], v[0:15]
	ds_read_b128 v[120:123], v239 offset:12288
	s_waitcnt lgkmcnt(0)
	v_mfma_f32_32x32x16_bf16 v[80:95], v[108:111], v[104:107], v[80:95]
	ds_read_b128 v[96:99], v205
	v_mfma_f32_32x32x16_bf16 v[64:79], v[112:115], v[104:107], v[64:79]
	ds_read_b128 v[100:103], v205 offset:8192
	v_mfma_f32_32x32x16_bf16 v[16:31], v[116:119], v[104:107], v[16:31]
	ds_read_b128 v[182:185], v211
	v_mfma_f32_32x32x16_bf16 v[0:15], v[120:123], v[104:107], v[0:15]
	ds_read_b128 v[186:189], v211 offset:8192
	s_waitcnt lgkmcnt(0)
	v_mfma_f32_32x32x16_bf16 v[112:127], v[96:99], v[160:163], 0
	ds_read_b128 v[216:219], v212
	v_exp_f32_e32 v224, v144
	v_exp_f32_e32 v225, v145
	v_exp_f32_e32 v226, v146
	v_exp_f32_e32 v227, v147
	ds_read_b128 v[220:223], v212 offset:8192
	v_mfma_f32_32x32x16_bf16 v[96:111], v[100:103], v[160:163], 0
	v_exp_f32_e32 v228, v148
	v_exp_f32_e32 v229, v149
	v_exp_f32_e32 v230, v150
	v_exp_f32_e32 v231, v151
	v_mfma_f32_32x32x16_bf16 v[112:127], v[182:185], v[164:167], v[112:127]
	ds_read_b128 v[148:151], v213
	v_exp_f32_e32 v232, v152
	v_exp_f32_e32 v233, v153
	v_exp_f32_e32 v234, v154
	v_exp_f32_e32 v235, v155
	v_cvt_pk_bf16_f32 v144, v224, v225
	v_cvt_pk_bf16_f32 v145, v226, v227
	v_cvt_pk_bf16_f32 v146, v228, v229
	v_cvt_pk_bf16_f32 v147, v230, v231
	v_pk_add_f32 v[154:155], v[230:231], v[226:227]
	v_pk_add_f32 v[152:153], v[228:229], v[224:225]
	v_mfma_f32_32x32x16_bf16 v[96:111], v[186:189], v[164:167], v[96:111]
	ds_read_b128 v[182:185], v213 offset:8192
	v_exp_f32_e32 v156, v156
	v_exp_f32_e32 v157, v157
	v_exp_f32_e32 v158, v158
	v_exp_f32_e32 v159, v159
	s_waitcnt lgkmcnt(0)
	v_mfma_f32_32x32x16_bf16 v[112:127], v[216:219], v[168:171], v[112:127]
	v_add_f32_e64 v154, v234, v154
	v_add_f32_e64 v155, v235, v155
	v_add_f32_e64 v152, v232, v152
	v_add_f32_e64 v153, v233, v153
	v_exp_f32_e32 v186, v128
	v_exp_f32_e32 v187, v129
	v_exp_f32_e32 v188, v130
	v_exp_f32_e32 v189, v131
	v_cvt_pk_bf16_f32 v128, v232, v233
	v_cvt_pk_bf16_f32 v129, v234, v235
	v_cvt_pk_bf16_f32 v130, v156, v157
	v_cvt_pk_bf16_f32 v131, v158, v159
	v_pk_add_f32 v[154:155], v[158:159], v[154:155]
	v_pk_add_f32 v[152:153], v[156:157], v[152:153]
	v_mfma_f32_32x32x16_bf16 v[96:111], v[220:223], v[168:171], v[96:111]
	v_exp_f32_e32 v156, v132
	v_exp_f32_e32 v157, v133
	v_exp_f32_e32 v158, v134
	v_exp_f32_e32 v159, v135
	v_mfma_f32_32x32x16_bf16 v[112:127], v[148:151], v[172:175], v[112:127]
	v_exp_f32_e32 v216, v136
	v_exp_f32_e32 v217, v137
	v_exp_f32_e32 v218, v138
	v_exp_f32_e32 v219, v139
	v_pk_add_f32 v[138:139], v[188:189], v[154:155]
	v_pk_add_f32 v[136:137], v[186:187], v[152:153]
	v_cvt_pk_bf16_f32 v132, v186, v187
	v_cvt_pk_bf16_f32 v133, v188, v189
	v_cvt_pk_bf16_f32 v134, v156, v157
	v_cvt_pk_bf16_f32 v135, v158, v159
	v_pk_add_f32 v[150:151], v[158:159], v[138:139]
	v_pk_add_f32 v[148:149], v[156:157], v[136:137]
	v_mfma_f32_32x32x16_bf16 v[96:111], v[182:185], v[172:175], v[96:111]
	v_exp_f32_e32 v152, v140
	v_exp_f32_e32 v153, v141
	v_exp_f32_e32 v154, v142
	v_exp_f32_e32 v155, v143
	v_pk_add_f32 v[142:143], v[218:219], v[150:151]
	v_pk_add_f32 v[140:141], v[216:217], v[148:149]
	v_cvt_pk_bf16_f32 v136, v216, v217
	v_cvt_pk_bf16_f32 v137, v218, v219
	v_cvt_pk_bf16_f32 v138, v152, v153
	v_cvt_pk_bf16_f32 v139, v154, v155
	v_pk_add_f32 v[142:143], v[154:155], v[142:143]
	v_pk_add_f32 v[140:141], v[152:153], v[140:141]
	s_waitcnt vmcnt(4) lgkmcnt(0)
	v_add_f32_e32 v148, v176, v177
	v_add_f32_e32 v149, v178, v179
	v_add_f32_e32 v148, v148, v149
	v_add_f32_e32 v140, v140, v141
	v_add_f32_e32 v141, v142, v143
	s_barrier
	v_add_f32_e32 v148, v180, v148
	v_add_f32_e32 v140, v140, v141
	v_add_f32_e32 v180, v148, v140
	s_add_i32 s47, s47, 2
	s_addk_i32 s41, 0x80
	s_add_i32 s46, s46, 0x8000
	s_mov_b32 s44, s21
	s_add_i32 s44, s44, s41
	s_sub_i32 s44, s44, 64
	s_mul_hi_i32 s45, s44, 0x600
	s_mulk_i32 s44, 0x600
	s_add_u32 s44, s14, s44
	s_addc_u32 s45, s15, s45
	s_add_i32 s49, s58, 0
	s_mov_b32 m0, s49
	s_nop 0
	global_load_lds_dwordx4 v198, s[44:45]
	s_add_i32 m0, s49, 0x400
	s_nop 0
	global_load_lds_dwordx4 v194, s[44:45]
	s_mov_b32 s44, s21
	s_add_i32 s44, s44, s41
	s_addk_i32 s44, 0xff80
	s_ashr_i32 s45, s44, 31
	s_lshl_b64 s[44:45], s[44:45], 1
	s_add_u32 s44, s39, s44
	s_addc_u32 s45, s67, s45
	s_add_i32 s49, s46, 0xffffc000
	s_add_i32 s49, s58, 0x4000
	s_add_i32 m0, s49, 0xc000
	s_nop 0
	global_load_lds_dwordx4 v196, s[44:45]
	v_lshl_add_u64 v[140:141], s[44:45], 0, v[192:193]
	s_add_i32 m0, s49, 0xc400
	s_nop 0
	global_load_lds_dwordx4 v[140:141], off
	ds_read_b128 v[140:143], v236 offset:16384
	ds_read_b128 v[148:151], v236 offset:20480
	ds_read_b128 v[152:155], v236 offset:24576
	ds_read_b128 v[156:159], v236 offset:28672
	s_waitcnt lgkmcnt(0)
	v_mfma_f32_32x32x16_bf16 v[80:95], v[140:143], v[144:147], v[80:95]
	ds_read_b128 v[140:143], v237 offset:16384
	v_mfma_f32_32x32x16_bf16 v[64:79], v[148:151], v[144:147], v[64:79]
	ds_read_b128 v[148:151], v237 offset:20480
	v_mfma_f32_32x32x16_bf16 v[16:31], v[152:155], v[144:147], v[16:31]
	ds_read_b128 v[152:155], v237 offset:24576
	v_mfma_f32_32x32x16_bf16 v[0:15], v[156:159], v[144:147], v[0:15]
	ds_read_b128 v[144:147], v237 offset:28672
	s_waitcnt lgkmcnt(0)
	v_mfma_f32_32x32x16_bf16 v[80:95], v[140:143], v[128:131], v[80:95]
	ds_read_b128 v[140:143], v238 offset:16384
	v_mfma_f32_32x32x16_bf16 v[64:79], v[148:151], v[128:131], v[64:79]
	ds_read_b128 v[148:151], v238 offset:20480
	v_mfma_f32_32x32x16_bf16 v[16:31], v[152:155], v[128:131], v[16:31]
	ds_read_b128 v[152:155], v238 offset:24576
	v_mfma_f32_32x32x16_bf16 v[0:15], v[144:147], v[128:131], v[0:15]
	ds_read_b128 v[128:131], v238 offset:28672
	s_waitcnt lgkmcnt(0)
	v_mfma_f32_32x32x16_bf16 v[80:95], v[140:143], v[132:135], v[80:95]
	ds_read_b128 v[140:143], v239 offset:16384
	v_mfma_f32_32x32x16_bf16 v[64:79], v[148:151], v[132:135], v[64:79]
	ds_read_b128 v[144:147], v239 offset:20480
	v_mfma_f32_32x32x16_bf16 v[16:31], v[152:155], v[132:135], v[16:31]
	ds_read_b128 v[148:151], v239 offset:24576
	v_mfma_f32_32x32x16_bf16 v[0:15], v[128:131], v[132:135], v[0:15]
	ds_read_b128 v[128:131], v239 offset:28672
	s_waitcnt lgkmcnt(0)
	v_mfma_f32_32x32x16_bf16 v[80:95], v[140:143], v[136:139], v[80:95]
	ds_read_b128 v[132:135], v205 offset:16384
	v_mfma_f32_32x32x16_bf16 v[64:79], v[144:147], v[136:139], v[64:79]
	ds_read_b128 v[140:143], v205 offset:24576
	v_mfma_f32_32x32x16_bf16 v[16:31], v[148:151], v[136:139], v[16:31]
	ds_read_b128 v[176:179], v211 offset:16384
	v_mfma_f32_32x32x16_bf16 v[0:15], v[128:131], v[136:139], v[0:15]
	ds_read_b128 v[182:185], v211 offset:24576
	s_waitcnt lgkmcnt(0)
	v_mfma_f32_32x32x16_bf16 v[144:159], v[132:135], v[160:163], 0
	ds_read_b128 v[186:189], v212 offset:16384
	v_exp_f32_e32 v220, v112
	v_exp_f32_e32 v221, v113
	v_exp_f32_e32 v222, v114
	v_exp_f32_e32 v223, v115
	v_mfma_f32_32x32x16_bf16 v[128:143], v[140:143], v[160:163], 0
	ds_read_b128 v[216:219], v212 offset:24576
	v_exp_f32_e32 v224, v116
	v_exp_f32_e32 v225, v117
	v_exp_f32_e32 v226, v118
	v_exp_f32_e32 v227, v119
	v_mfma_f32_32x32x16_bf16 v[144:159], v[176:179], v[164:167], v[144:159]
	ds_read_b128 v[116:119], v213 offset:16384
	v_exp_f32_e32 v228, v120
	v_exp_f32_e32 v229, v121
	v_exp_f32_e32 v230, v122
	v_exp_f32_e32 v231, v123
	v_cvt_pk_bf16_f32 v112, v220, v221
	v_cvt_pk_bf16_f32 v113, v222, v223
	v_cvt_pk_bf16_f32 v114, v224, v225
	v_cvt_pk_bf16_f32 v115, v226, v227
	v_pk_add_f32 v[122:123], v[226:227], v[222:223]
	v_pk_add_f32 v[120:121], v[224:225], v[220:221]
	v_mfma_f32_32x32x16_bf16 v[128:143], v[182:185], v[164:167], v[128:143]
	ds_read_b128 v[176:179], v213 offset:24576
	v_exp_f32_e32 v124, v124
	v_exp_f32_e32 v125, v125
	v_exp_f32_e32 v126, v126
	v_exp_f32_e32 v127, v127
	s_waitcnt lgkmcnt(0)
	v_mfma_f32_32x32x16_bf16 v[144:159], v[186:189], v[168:171], v[144:159]
	v_add_f32_e64 v122, v230, v122
	v_add_f32_e64 v123, v231, v123
	v_add_f32_e64 v120, v228, v120
	v_add_f32_e64 v121, v229, v121
	v_exp_f32_e32 v182, v96
	v_exp_f32_e32 v183, v97
	v_exp_f32_e32 v184, v98
	v_exp_f32_e32 v185, v99
	v_cvt_pk_bf16_f32 v96, v228, v229
	v_cvt_pk_bf16_f32 v97, v230, v231
	v_cvt_pk_bf16_f32 v98, v124, v125
	v_cvt_pk_bf16_f32 v99, v126, v127
	v_pk_add_f32 v[122:123], v[126:127], v[122:123]
	v_pk_add_f32 v[120:121], v[124:125], v[120:121]
	v_mfma_f32_32x32x16_bf16 v[128:143], v[216:219], v[168:171], v[128:143]
	v_exp_f32_e32 v124, v100
	v_exp_f32_e32 v125, v101
	v_exp_f32_e32 v126, v102
	v_exp_f32_e32 v127, v103
	v_mfma_f32_32x32x16_bf16 v[144:159], v[116:119], v[172:175], v[144:159]
	v_exp_f32_e32 v186, v104
	v_exp_f32_e32 v187, v105
	v_exp_f32_e32 v188, v106
	v_exp_f32_e32 v189, v107
	v_pk_add_f32 v[106:107], v[184:185], v[122:123]
	v_pk_add_f32 v[104:105], v[182:183], v[120:121]
	v_cvt_pk_bf16_f32 v100, v182, v183
	v_cvt_pk_bf16_f32 v101, v184, v185
	v_cvt_pk_bf16_f32 v102, v124, v125
	v_cvt_pk_bf16_f32 v103, v126, v127
	v_pk_add_f32 v[118:119], v[126:127], v[106:107]
	v_pk_add_f32 v[116:117], v[124:125], v[104:105]
	v_mfma_f32_32x32x16_bf16 v[128:143], v[176:179], v[172:175], v[128:143]
	v_exp_f32_e32 v120, v108
	v_exp_f32_e32 v121, v109
	v_exp_f32_e32 v122, v110
	v_exp_f32_e32 v123, v111
	v_pk_add_f32 v[110:111], v[188:189], v[118:119]
	v_pk_add_f32 v[108:109], v[186:187], v[116:117]
	v_cvt_pk_bf16_f32 v104, v186, v187
	v_cvt_pk_bf16_f32 v105, v188, v189
	v_cvt_pk_bf16_f32 v106, v120, v121
	v_cvt_pk_bf16_f32 v107, v122, v123
	v_pk_add_f32 v[178:179], v[122:123], v[110:111]
	v_pk_add_f32 v[176:177], v[120:121], v[108:109]
	s_waitcnt vmcnt(4) lgkmcnt(0)
	s_barrier
	ds_read_b128 v[108:111], v236 offset:32768
	ds_read_b128 v[116:119], v236 offset:36864
	ds_read_b128 v[120:123], v236 offset:40960
	ds_read_b128 v[124:127], v236 offset:45056
	s_mov_b32 s69, s21
	s_add_i32 s69, s69, s41
	s_mul_hi_i32 s71, s69, 0x600
	s_mulk_i32 s69, 0x600
	s_add_u32 s70, s14, s69
	s_addc_u32 s71, s15, s71
	s_add_i32 s68, 0x4000, s57
	s_mov_b32 m0, s68
	s_nop 0
	global_load_lds_dwordx4 v198, s[70:71]
	s_add_i32 m0, s68, 0x400
	s_nop 0
	global_load_lds_dwordx4 v194, s[70:71]
	s_mov_b32 s2, s21
	s_add_i32 s2, s2, s41
	s_sub_i32 s2, s2, 64
	s_ashr_i32 s3, s2, 31
	s_lshl_b64 s[2:3], s[2:3], 1
	s_add_u32 s2, s39, s2
	s_addc_u32 s3, s67, s3
	s_add_i32 s49, s58, 0x8000
	s_add_i32 m0, s49, 0xc000
	s_nop 0
	global_load_lds_dwordx4 v196, s[2:3]
	s_add_i32 m0, s49, 0xc400
	s_nop 0
	global_load_lds_dwordx4 v192, s[2:3]
	s_add_i32 s2, s46, 0xffff4000
	s_waitcnt lgkmcnt(0)
	v_mfma_f32_32x32x16_bf16 v[80:95], v[108:111], v[112:115], v[80:95]
	ds_read_b128 v[108:111], v237 offset:32768
	v_mfma_f32_32x32x16_bf16 v[64:79], v[116:119], v[112:115], v[64:79]
	ds_read_b128 v[116:119], v237 offset:36864
	v_mfma_f32_32x32x16_bf16 v[16:31], v[120:123], v[112:115], v[16:31]
	ds_read_b128 v[120:123], v237 offset:40960
	v_mfma_f32_32x32x16_bf16 v[0:15], v[124:127], v[112:115], v[0:15]
	ds_read_b128 v[112:115], v237 offset:45056
	s_waitcnt lgkmcnt(0)
	v_mfma_f32_32x32x16_bf16 v[80:95], v[108:111], v[96:99], v[80:95]
	ds_read_b128 v[108:111], v238 offset:32768
	v_mfma_f32_32x32x16_bf16 v[64:79], v[116:119], v[96:99], v[64:79]
	ds_read_b128 v[116:119], v238 offset:36864
	v_mfma_f32_32x32x16_bf16 v[16:31], v[120:123], v[96:99], v[16:31]
	ds_read_b128 v[120:123], v238 offset:40960
	v_mfma_f32_32x32x16_bf16 v[0:15], v[112:115], v[96:99], v[0:15]
	ds_read_b128 v[96:99], v238 offset:45056
	s_waitcnt lgkmcnt(0)
	v_mfma_f32_32x32x16_bf16 v[80:95], v[108:111], v[100:103], v[80:95]
	ds_read_b128 v[108:111], v239 offset:32768
	v_mfma_f32_32x32x16_bf16 v[64:79], v[116:119], v[100:103], v[64:79]
	ds_read_b128 v[112:115], v239 offset:36864
	v_mfma_f32_32x32x16_bf16 v[16:31], v[120:123], v[100:103], v[16:31]
	ds_read_b128 v[116:119], v239 offset:40960
	v_mfma_f32_32x32x16_bf16 v[0:15], v[96:99], v[100:103], v[0:15]
	ds_read_b128 v[120:123], v239 offset:45056
	s_waitcnt lgkmcnt(0)
	v_mfma_f32_32x32x16_bf16 v[80:95], v[108:111], v[104:107], v[80:95]
	ds_read_b128 v[96:99], v205 offset:32768
	v_mfma_f32_32x32x16_bf16 v[64:79], v[112:115], v[104:107], v[64:79]
	ds_read_b128 v[100:103], v205 offset:40960
	v_mfma_f32_32x32x16_bf16 v[16:31], v[116:119], v[104:107], v[16:31]
	ds_read_b128 v[182:185], v211 offset:32768
	v_mfma_f32_32x32x16_bf16 v[0:15], v[120:123], v[104:107], v[0:15]
	ds_read_b128 v[186:189], v211 offset:40960
	s_waitcnt lgkmcnt(0)
	v_mfma_f32_32x32x16_bf16 v[112:127], v[96:99], v[160:163], 0
	ds_read_b128 v[216:219], v212 offset:32768
	v_exp_f32_e32 v224, v144
	v_exp_f32_e32 v225, v145
	v_exp_f32_e32 v226, v146
	v_exp_f32_e32 v227, v147
	ds_read_b128 v[220:223], v212 offset:40960
	v_mfma_f32_32x32x16_bf16 v[96:111], v[100:103], v[160:163], 0
	v_exp_f32_e32 v228, v148
	v_exp_f32_e32 v229, v149
	v_exp_f32_e32 v230, v150
	v_exp_f32_e32 v231, v151
	v_mfma_f32_32x32x16_bf16 v[112:127], v[182:185], v[164:167], v[112:127]
	ds_read_b128 v[148:151], v213 offset:32768
	v_exp_f32_e32 v232, v152
	v_exp_f32_e32 v233, v153
	v_exp_f32_e32 v234, v154
	v_exp_f32_e32 v235, v155
	v_cvt_pk_bf16_f32 v144, v224, v225
	v_cvt_pk_bf16_f32 v145, v226, v227
	v_cvt_pk_bf16_f32 v146, v228, v229
	v_cvt_pk_bf16_f32 v147, v230, v231
	v_pk_add_f32 v[154:155], v[230:231], v[226:227]
	v_pk_add_f32 v[152:153], v[228:229], v[224:225]
	v_mfma_f32_32x32x16_bf16 v[96:111], v[186:189], v[164:167], v[96:111]
	ds_read_b128 v[182:185], v213 offset:40960
	v_exp_f32_e32 v156, v156
	v_exp_f32_e32 v157, v157
	v_exp_f32_e32 v158, v158
	v_exp_f32_e32 v159, v159
	s_waitcnt lgkmcnt(0)
	v_mfma_f32_32x32x16_bf16 v[112:127], v[216:219], v[168:171], v[112:127]
	v_add_f32_e64 v154, v234, v154
	v_add_f32_e64 v155, v235, v155
	v_add_f32_e64 v152, v232, v152
	v_add_f32_e64 v153, v233, v153
	v_exp_f32_e32 v186, v128
	v_exp_f32_e32 v187, v129
	v_exp_f32_e32 v188, v130
	v_exp_f32_e32 v189, v131
	v_cvt_pk_bf16_f32 v128, v232, v233
	v_cvt_pk_bf16_f32 v129, v234, v235
	v_cvt_pk_bf16_f32 v130, v156, v157
	v_cvt_pk_bf16_f32 v131, v158, v159
	v_pk_add_f32 v[154:155], v[158:159], v[154:155]
	v_pk_add_f32 v[152:153], v[156:157], v[152:153]
	v_mfma_f32_32x32x16_bf16 v[96:111], v[220:223], v[168:171], v[96:111]
	v_exp_f32_e32 v156, v132
	v_exp_f32_e32 v157, v133
	v_exp_f32_e32 v158, v134
	v_exp_f32_e32 v159, v135
	v_mfma_f32_32x32x16_bf16 v[112:127], v[148:151], v[172:175], v[112:127]
	v_exp_f32_e32 v216, v136
	v_exp_f32_e32 v217, v137
	v_exp_f32_e32 v218, v138
	v_exp_f32_e32 v219, v139
	v_pk_add_f32 v[138:139], v[188:189], v[154:155]
	v_pk_add_f32 v[136:137], v[186:187], v[152:153]
	v_cvt_pk_bf16_f32 v132, v186, v187
	v_cvt_pk_bf16_f32 v133, v188, v189
	v_cvt_pk_bf16_f32 v134, v156, v157
	v_cvt_pk_bf16_f32 v135, v158, v159
	v_pk_add_f32 v[150:151], v[158:159], v[138:139]
	v_pk_add_f32 v[148:149], v[156:157], v[136:137]
	v_mfma_f32_32x32x16_bf16 v[96:111], v[182:185], v[172:175], v[96:111]
	v_exp_f32_e32 v152, v140
	v_exp_f32_e32 v153, v141
	v_exp_f32_e32 v154, v142
	v_exp_f32_e32 v155, v143
	v_pk_add_f32 v[142:143], v[218:219], v[150:151]
	v_pk_add_f32 v[140:141], v[216:217], v[148:149]
	v_cvt_pk_bf16_f32 v136, v216, v217
	v_cvt_pk_bf16_f32 v137, v218, v219
	v_cvt_pk_bf16_f32 v138, v152, v153
	v_cvt_pk_bf16_f32 v139, v154, v155
	v_pk_add_f32 v[142:143], v[154:155], v[142:143]
	v_pk_add_f32 v[140:141], v[152:153], v[140:141]
	s_waitcnt vmcnt(4) lgkmcnt(0)
	v_add_f32_e32 v148, v176, v177
	v_add_f32_e32 v149, v178, v179
	v_add_f32_e32 v148, v148, v149
	v_add_f32_e32 v140, v140, v141
	v_add_f32_e32 v141, v142, v143
	s_barrier
	v_add_f32_e32 v148, v180, v148
	v_add_f32_e32 v140, v140, v141
	v_add_f32_e32 v180, v148, v140
	s_add_i32 s47, s47, 2
	s_addk_i32 s41, 0x80
	s_add_i32 s46, s46, 0x8000
	s_mov_b32 s44, s21
	s_add_i32 s44, s44, s41
	s_addk_i32 s44, 0xff80
	s_ashr_i32 s45, s44, 31
	s_lshl_b64 s[44:45], s[44:45], 1
	s_add_u32 s44, s39, s44
	s_addc_u32 s45, s67, s45
	s_add_i32 s49, s46, 0xffffc000
	s_add_i32 s49, s58, 0xc000
	s_add_i32 m0, s49, 0xc000
	s_nop 0
	global_load_lds_dwordx4 v196, s[44:45]
	v_lshl_add_u64 v[140:141], s[44:45], 0, v[192:193]
	s_add_i32 m0, s49, 0xc400
	s_nop 0
	global_load_lds_dwordx4 v[140:141], off
	ds_read_b128 v[140:143], v206 offset:49152
	ds_read_b128 v[148:151], v206 offset:53248
	ds_read_b128 v[152:155], v206 offset:57344
	ds_read_b128 v[156:159], v206 offset:61440
	s_waitcnt lgkmcnt(0)
	v_mfma_f32_32x32x16_bf16 v[80:95], v[140:143], v[144:147], v[80:95]
	ds_read_b128 v[140:143], v207 offset:49152
	v_mfma_f32_32x32x16_bf16 v[64:79], v[148:151], v[144:147], v[64:79]
	ds_read_b128 v[148:151], v207 offset:53248
	v_mfma_f32_32x32x16_bf16 v[16:31], v[152:155], v[144:147], v[16:31]
	ds_read_b128 v[152:155], v207 offset:57344
	v_mfma_f32_32x32x16_bf16 v[0:15], v[156:159], v[144:147], v[0:15]
	ds_read_b128 v[144:147], v207 offset:61440
	s_waitcnt lgkmcnt(0)
	v_mfma_f32_32x32x16_bf16 v[80:95], v[140:143], v[128:131], v[80:95]
	ds_read_b128 v[140:143], v208 offset:49152
	v_mfma_f32_32x32x16_bf16 v[64:79], v[148:151], v[128:131], v[64:79]
	ds_read_b128 v[148:151], v208 offset:53248
	v_mfma_f32_32x32x16_bf16 v[16:31], v[152:155], v[128:131], v[16:31]
	ds_read_b128 v[152:155], v208 offset:57344
	v_mfma_f32_32x32x16_bf16 v[0:15], v[144:147], v[128:131], v[0:15]
	ds_read_b128 v[128:131], v208 offset:61440
	s_waitcnt lgkmcnt(0)
	v_mfma_f32_32x32x16_bf16 v[80:95], v[140:143], v[132:135], v[80:95]
	ds_read_b128 v[140:143], v209 offset:49152
	v_mfma_f32_32x32x16_bf16 v[64:79], v[148:151], v[132:135], v[64:79]
	ds_read_b128 v[144:147], v209 offset:53248
	v_mfma_f32_32x32x16_bf16 v[16:31], v[152:155], v[132:135], v[16:31]
	ds_read_b128 v[148:151], v209 offset:57344
	v_mfma_f32_32x32x16_bf16 v[0:15], v[128:131], v[132:135], v[0:15]
	ds_read_b128 v[128:131], v209 offset:61440
	s_waitcnt lgkmcnt(0)
	v_mfma_f32_32x32x16_bf16 v[80:95], v[140:143], v[136:139], v[80:95]
	ds_read_b128 v[132:135], v205
	v_mfma_f32_32x32x16_bf16 v[64:79], v[144:147], v[136:139], v[64:79]
	ds_read_b128 v[140:143], v205 offset:8192
	v_mfma_f32_32x32x16_bf16 v[16:31], v[148:151], v[136:139], v[16:31]
	ds_read_b128 v[176:179], v211
	v_mfma_f32_32x32x16_bf16 v[0:15], v[128:131], v[136:139], v[0:15]
	ds_read_b128 v[182:185], v211 offset:8192
	s_waitcnt lgkmcnt(0)
	v_mfma_f32_32x32x16_bf16 v[144:159], v[132:135], v[160:163], 0
	ds_read_b128 v[186:189], v212
	v_exp_f32_e32 v220, v112
	v_exp_f32_e32 v221, v113
	v_exp_f32_e32 v222, v114
	v_exp_f32_e32 v223, v115
	v_mfma_f32_32x32x16_bf16 v[128:143], v[140:143], v[160:163], 0
	ds_read_b128 v[216:219], v212 offset:8192
	v_exp_f32_e32 v224, v116
	v_exp_f32_e32 v225, v117
	v_exp_f32_e32 v226, v118
	v_exp_f32_e32 v227, v119
	v_mfma_f32_32x32x16_bf16 v[144:159], v[176:179], v[164:167], v[144:159]
	ds_read_b128 v[116:119], v213
	v_exp_f32_e32 v228, v120
	v_exp_f32_e32 v229, v121
	v_exp_f32_e32 v230, v122
	v_exp_f32_e32 v231, v123
	v_cvt_pk_bf16_f32 v112, v220, v221
	v_cvt_pk_bf16_f32 v113, v222, v223
	v_cvt_pk_bf16_f32 v114, v224, v225
	v_cvt_pk_bf16_f32 v115, v226, v227
	v_pk_add_f32 v[122:123], v[226:227], v[222:223]
	v_pk_add_f32 v[120:121], v[224:225], v[220:221]
	v_mfma_f32_32x32x16_bf16 v[128:143], v[182:185], v[164:167], v[128:143]
	ds_read_b128 v[176:179], v213 offset:8192
	v_exp_f32_e32 v124, v124
	v_exp_f32_e32 v125, v125
	v_exp_f32_e32 v126, v126
	v_exp_f32_e32 v127, v127
	s_waitcnt lgkmcnt(0)
	v_mfma_f32_32x32x16_bf16 v[144:159], v[186:189], v[168:171], v[144:159]
	v_add_f32_e64 v122, v230, v122
	v_add_f32_e64 v123, v231, v123
	v_add_f32_e64 v120, v228, v120
	v_add_f32_e64 v121, v229, v121
	v_exp_f32_e32 v182, v96
	v_exp_f32_e32 v183, v97
	v_exp_f32_e32 v184, v98
	v_exp_f32_e32 v185, v99
	v_cvt_pk_bf16_f32 v96, v228, v229
	v_cvt_pk_bf16_f32 v97, v230, v231
	v_cvt_pk_bf16_f32 v98, v124, v125
	v_cvt_pk_bf16_f32 v99, v126, v127
	v_pk_add_f32 v[122:123], v[126:127], v[122:123]
	v_pk_add_f32 v[120:121], v[124:125], v[120:121]
	v_mfma_f32_32x32x16_bf16 v[128:143], v[216:219], v[168:171], v[128:143]
	v_exp_f32_e32 v124, v100
	v_exp_f32_e32 v125, v101
	v_exp_f32_e32 v126, v102
	v_exp_f32_e32 v127, v103
	v_mfma_f32_32x32x16_bf16 v[144:159], v[116:119], v[172:175], v[144:159]
	v_exp_f32_e32 v186, v104
	v_exp_f32_e32 v187, v105
	v_exp_f32_e32 v188, v106
	v_exp_f32_e32 v189, v107
	v_pk_add_f32 v[106:107], v[184:185], v[122:123]
	v_pk_add_f32 v[104:105], v[182:183], v[120:121]
	v_cvt_pk_bf16_f32 v100, v182, v183
	v_cvt_pk_bf16_f32 v101, v184, v185
	v_cvt_pk_bf16_f32 v102, v124, v125
	v_cvt_pk_bf16_f32 v103, v126, v127
	v_pk_add_f32 v[118:119], v[126:127], v[106:107]
	v_pk_add_f32 v[116:117], v[124:125], v[104:105]
	v_mfma_f32_32x32x16_bf16 v[128:143], v[176:179], v[172:175], v[128:143]
	v_exp_f32_e32 v120, v108
	v_exp_f32_e32 v121, v109
	v_exp_f32_e32 v122, v110
	v_exp_f32_e32 v123, v111
	v_pk_add_f32 v[110:111], v[188:189], v[118:119]
	v_pk_add_f32 v[108:109], v[186:187], v[116:117]
	v_cvt_pk_bf16_f32 v104, v186, v187
	v_cvt_pk_bf16_f32 v105, v188, v189
	v_cvt_pk_bf16_f32 v106, v120, v121
	v_cvt_pk_bf16_f32 v107, v122, v123
	v_pk_add_f32 v[178:179], v[122:123], v[110:111]
	v_pk_add_f32 v[176:177], v[120:121], v[108:109]
	s_waitcnt vmcnt(2) lgkmcnt(0)
	s_barrier
	ds_read_b128 v[108:111], v236
	ds_read_b128 v[116:119], v236 offset:4096
	ds_read_b128 v[120:123], v236 offset:8192
	ds_read_b128 v[124:127], v236 offset:12288
	s_add_i32 s2, s46, 0xffff4000
	s_waitcnt lgkmcnt(0)
	v_mfma_f32_32x32x16_bf16 v[80:95], v[108:111], v[112:115], v[80:95]
	ds_read_b128 v[108:111], v237
	v_mfma_f32_32x32x16_bf16 v[64:79], v[116:119], v[112:115], v[64:79]
	ds_read_b128 v[116:119], v237 offset:4096
	v_mfma_f32_32x32x16_bf16 v[16:31], v[120:123], v[112:115], v[16:31]
	ds_read_b128 v[120:123], v237 offset:8192
	v_mfma_f32_32x32x16_bf16 v[0:15], v[124:127], v[112:115], v[0:15]
	ds_read_b128 v[112:115], v237 offset:12288
	s_waitcnt lgkmcnt(0)
	v_mfma_f32_32x32x16_bf16 v[80:95], v[108:111], v[96:99], v[80:95]
	ds_read_b128 v[108:111], v238
	v_mfma_f32_32x32x16_bf16 v[64:79], v[116:119], v[96:99], v[64:79]
	ds_read_b128 v[116:119], v238 offset:4096
	v_mfma_f32_32x32x16_bf16 v[16:31], v[120:123], v[96:99], v[16:31]
	ds_read_b128 v[120:123], v238 offset:8192
	v_mfma_f32_32x32x16_bf16 v[0:15], v[112:115], v[96:99], v[0:15]
	ds_read_b128 v[96:99], v238 offset:12288
	s_waitcnt lgkmcnt(0)
	v_mfma_f32_32x32x16_bf16 v[80:95], v[108:111], v[100:103], v[80:95]
	ds_read_b128 v[108:111], v239
	v_mfma_f32_32x32x16_bf16 v[64:79], v[116:119], v[100:103], v[64:79]
	ds_read_b128 v[112:115], v239 offset:4096
	v_mfma_f32_32x32x16_bf16 v[16:31], v[120:123], v[100:103], v[16:31]
	ds_read_b128 v[116:119], v239 offset:8192
	v_mfma_f32_32x32x16_bf16 v[0:15], v[96:99], v[100:103], v[0:15]
	ds_read_b128 v[120:123], v239 offset:12288
	s_waitcnt lgkmcnt(0)
	v_mfma_f32_32x32x16_bf16 v[80:95], v[108:111], v[104:107], v[80:95]
	ds_read_b128 v[96:99], v205 offset:16384
	v_mfma_f32_32x32x16_bf16 v[64:79], v[112:115], v[104:107], v[64:79]
	ds_read_b128 v[100:103], v205 offset:24576
	v_mfma_f32_32x32x16_bf16 v[16:31], v[116:119], v[104:107], v[16:31]
	ds_read_b128 v[182:185], v211 offset:16384
	v_mfma_f32_32x32x16_bf16 v[0:15], v[120:123], v[104:107], v[0:15]
	ds_read_b128 v[186:189], v211 offset:24576
	s_waitcnt lgkmcnt(0)
	v_mfma_f32_32x32x16_bf16 v[112:127], v[96:99], v[160:163], 0
	ds_read_b128 v[216:219], v212 offset:16384
	v_exp_f32_e32 v224, v144
	v_exp_f32_e32 v225, v145
	v_exp_f32_e32 v226, v146
	v_exp_f32_e32 v227, v147
	ds_read_b128 v[220:223], v212 offset:24576
	v_mfma_f32_32x32x16_bf16 v[96:111], v[100:103], v[160:163], 0
	v_exp_f32_e32 v228, v148
	v_exp_f32_e32 v229, v149
	v_exp_f32_e32 v230, v150
	v_exp_f32_e32 v231, v151
	v_mfma_f32_32x32x16_bf16 v[112:127], v[182:185], v[164:167], v[112:127]
	ds_read_b128 v[148:151], v213 offset:16384
	v_exp_f32_e32 v232, v152
	v_exp_f32_e32 v233, v153
	v_exp_f32_e32 v234, v154
	v_exp_f32_e32 v235, v155
	v_cvt_pk_bf16_f32 v144, v224, v225
	v_cvt_pk_bf16_f32 v145, v226, v227
	v_cvt_pk_bf16_f32 v146, v228, v229
	v_cvt_pk_bf16_f32 v147, v230, v231
	v_pk_add_f32 v[154:155], v[230:231], v[226:227]
	v_pk_add_f32 v[152:153], v[228:229], v[224:225]
	v_mfma_f32_32x32x16_bf16 v[96:111], v[186:189], v[164:167], v[96:111]
	ds_read_b128 v[182:185], v213 offset:24576
	v_exp_f32_e32 v156, v156
	v_exp_f32_e32 v157, v157
	v_exp_f32_e32 v158, v158
	v_exp_f32_e32 v159, v159
	s_waitcnt lgkmcnt(0)
	v_mfma_f32_32x32x16_bf16 v[112:127], v[216:219], v[168:171], v[112:127]
	v_add_f32_e64 v154, v234, v154
	v_add_f32_e64 v155, v235, v155
	v_add_f32_e64 v152, v232, v152
	v_add_f32_e64 v153, v233, v153
	v_exp_f32_e32 v186, v128
	v_exp_f32_e32 v187, v129
	v_exp_f32_e32 v188, v130
	v_exp_f32_e32 v189, v131
	v_cvt_pk_bf16_f32 v128, v232, v233
	v_cvt_pk_bf16_f32 v129, v234, v235
	v_cvt_pk_bf16_f32 v130, v156, v157
	v_cvt_pk_bf16_f32 v131, v158, v159
	v_pk_add_f32 v[154:155], v[158:159], v[154:155]
	v_pk_add_f32 v[152:153], v[156:157], v[152:153]
	v_mfma_f32_32x32x16_bf16 v[96:111], v[220:223], v[168:171], v[96:111]
	v_exp_f32_e32 v156, v132
	v_exp_f32_e32 v157, v133
	v_exp_f32_e32 v158, v134
	v_exp_f32_e32 v159, v135
	v_mfma_f32_32x32x16_bf16 v[112:127], v[148:151], v[172:175], v[112:127]
	v_exp_f32_e32 v216, v136
	v_exp_f32_e32 v217, v137
	v_exp_f32_e32 v218, v138
	v_exp_f32_e32 v219, v139
	v_pk_add_f32 v[138:139], v[188:189], v[154:155]
	v_pk_add_f32 v[136:137], v[186:187], v[152:153]
	v_cvt_pk_bf16_f32 v132, v186, v187
	v_cvt_pk_bf16_f32 v133, v188, v189
	v_cvt_pk_bf16_f32 v134, v156, v157
	v_cvt_pk_bf16_f32 v135, v158, v159
	v_pk_add_f32 v[150:151], v[158:159], v[138:139]
	v_pk_add_f32 v[148:149], v[156:157], v[136:137]
	v_mfma_f32_32x32x16_bf16 v[96:111], v[182:185], v[172:175], v[96:111]
	v_exp_f32_e32 v152, v140
	v_exp_f32_e32 v153, v141
	v_exp_f32_e32 v154, v142
	v_exp_f32_e32 v155, v143
	v_pk_add_f32 v[142:143], v[218:219], v[150:151]
	v_pk_add_f32 v[140:141], v[216:217], v[148:149]
	v_cvt_pk_bf16_f32 v136, v216, v217
	v_cvt_pk_bf16_f32 v137, v218, v219
	v_cvt_pk_bf16_f32 v138, v152, v153
	v_cvt_pk_bf16_f32 v139, v154, v155
	v_pk_add_f32 v[142:143], v[154:155], v[142:143]
	v_pk_add_f32 v[140:141], v[152:153], v[140:141]
	s_waitcnt vmcnt(0) lgkmcnt(0)
	v_add_f32_e32 v148, v176, v177
	v_add_f32_e32 v149, v178, v179
	v_add_f32_e32 v148, v148, v149
	v_add_f32_e32 v140, v140, v141
	v_add_f32_e32 v141, v142, v143
	s_barrier
	v_add_f32_e32 v148, v180, v148
	v_add_f32_e32 v140, v140, v141
	v_add_f32_e32 v180, v148, v140
	s_add_i32 s47, s47, 2
	s_addk_i32 s41, 0x80
	s_add_i32 s46, s46, 0x8000
	s_branch .LBB0_932
